# K-loop critical path trim in all 7 GEMM loops: setprio 1 moved before pre-MMA barrier, redundant lgkmcnt(0) after barrier removed, post-MMA setprio 0 moved after barrier, mid-segment setprio 0/1 pairs
# speedup vs baseline: 1.0015x; 1.0015x over previous
; #define PG8_STAGE(bufoff, gbase, voff) do { _Pragma("unroll") for (int _i = 0; _i < 2; ++_i) \
;         __builtin_amdgcn_global_load_lds((const unsigned*)((const char*)(gbase) + (voff)[_i]), (LAS unsigned*)(lds + (bufoff) + ldsw + _i * 8192), 16, 0, 0); } while (0)
; #define PG8_LDA(dst, b, h) do { _Pragma("unroll") for (int m = 0; m < 4; ++m) _Pragma("unroll") for (int k = 0; k < 2; ++k) dst[m][k] = *(const LAS bf16x8*)(lds + PG8_SA(b, h) + aoff + m * 2048 + k * 1024); } while (0)
; #define PG8_LDB(dst, b, h) do { _Pragma("unroll") for (int n = 0; n < 2; ++n) _Pragma("unroll") for (int k = 0; k < 2; ++k) dst[n][k] = *(const LAS bf16x8*)(lds + PG8_SB(b, h) + boff + n * 2048 + k * 1024); } while (0)
; #define PG8_MMA(ai, bj, At, Bt) do { __builtin_amdgcn_s_setprio(1); _Pragma("unroll") for (int m = 0; m < 4; ++m) _Pragma("unroll") for (int n = 0; n < 2; ++n) _Pragma("unroll") for (int k = 0; k < 2; ++k) \
;         acc[ai][bj][m][n] = __builtin_amdgcn_mfma_f32_16x16x32_bf16(Bt[n][k], At[m][k], acc[ai][bj][m][n], 0, 0, 0); __builtin_amdgcn_s_setprio(0); } while (0)
; #define PG8_WAIT_V(n) asm volatile("s_waitcnt vmcnt(" #n ")" ::: "memory")
; #define PG8_WAIT_L(n) asm volatile("s_waitcnt lgkmcnt(" #n ")" ::: "memory")
; #define PG8_BAR __builtin_amdgcn_s_barrier()
; #define PG8_SCHED __builtin_amdgcn_sched_barrier(0)
; template <class Epi, class Order = StaticOrder, bool HALFN = false>
; __device__ __forceinline__ void gemm_phase(LAS unsigned char* lds, const Gemm g, const Epi& E) {
;     ...
;             const char* a1 = cA + (size_t)(t + 1) * kstep;
;             const char* a2 = last ? nA : cA + (size_t)(t + 2) * kstep; const char* b2 = last ? nB : cB + (size_t)(t + 2) * kstep;
;             const char* a3 = a2 + kstep; const char* b3 = b2 + kstep;
;             PG8_LDB(B0, 0, 0); if constexpr (!HALFN) PG8_LDB(B1, 0, 1); PG8_SCHED; PG8_LDA(At, 0, 0); PG8_STAGE(PG8_SA(1, 1), a1 + hstepA, voffA);
;             PG8_WAIT_V(8); PG8_WAIT_L(0); PG8_BAR; PG8_MMA(0, 0, At, B0); if constexpr (!HALFN) PG8_MMA(0, 1, At, B1); PG8_BAR; PG8_SCHED;
;             PG8_LDA(At, 0, 1); PG8_STAGE(PG8_SB(0, 0), b2, voffB); PG8_STAGE(PG8_SB(0, 1), b2 + hstepB, voffB); PG8_STAGE(PG8_SA(0, 0), a2, voffA);
;             PG8_WAIT_V(8); PG8_WAIT_L(0); PG8_BAR; PG8_MMA(1, 0, At, B0); if constexpr (!HALFN) PG8_MMA(1, 1, At, B1); PG8_BAR; PG8_SCHED;
.LBB0_194:
	s_add_u32 s4, s62, 0xfff80080
	s_addc_u32 s5, s63, -1
	s_add_i32 s23, 0, 0x10000
	s_cmp_eq_u32 s22, 28
	s_cselect_b32 s7, s8, s5
	s_cselect_b32 s6, s9, s4
	v_add_u32_e32 v142, s23, v145
	s_cselect_b32 s5, s18, s21
	s_cselect_b32 s4, s19, s20
	s_add_i32 s26, 0, 0x14000
	ds_read_b128 v[148:151], v142
	ds_read_b128 v[152:155], v142 offset:1024
	ds_read_b128 v[156:159], v142 offset:2048
	ds_read_b128 v[168:171], v142 offset:3072
	v_add_u32_e32 v142, s26, v145
	ds_read_b128 v[172:175], v142
	ds_read_b128 v[176:179], v142 offset:1024
	ds_read_b128 v[180:183], v142 offset:2048
	ds_read_b128 v[184:187], v142 offset:3072
	v_lshl_add_u64 v[160:161], s[62:63], 0, v[138:139]
	s_add_i32 m0, s53, 0xc000
	ds_read_b128 v[208:211], v147
	ds_read_b128 v[212:215], v147 offset:1024
	ds_read_b128 v[216:219], v147 offset:2048
	ds_read_b128 v[220:223], v147 offset:3072
	ds_read_b128 v[224:227], v147 offset:4096
	ds_read_b128 v[228:231], v147 offset:5120
	ds_read_b128 v[232:235], v147 offset:6144
	ds_read_b128 v[236:239], v147 offset:7168
	global_load_lds_dwordx4 v[160:161], off
	v_lshl_add_u64 v[160:161], s[62:63], 0, v[140:141]
	s_add_i32 m0, s53, 0xe000
	s_nop 0
	global_load_lds_dwordx4 v[160:161], off
	s_waitcnt vmcnt(8)
	s_waitcnt lgkmcnt(0)
	s_setprio 1
	s_barrier
	v_mfma_f32_16x16x32_bf16 v[126:129], v[148:151], v[208:211], v[126:129]
	v_mfma_f32_16x16x32_bf16 v[122:125], v[156:159], v[208:211], v[122:125]
	v_mfma_f32_16x16x32_bf16 v[114:117], v[148:151], v[216:219], v[114:117]
	v_mfma_f32_16x16x32_bf16 v[106:109], v[156:159], v[216:219], v[106:109]
	v_mfma_f32_16x16x32_bf16 v[102:105], v[148:151], v[224:227], v[102:105]
	v_mfma_f32_16x16x32_bf16 v[94:97], v[156:159], v[224:227], v[94:97]
	v_mfma_f32_16x16x32_bf16 v[86:89], v[148:151], v[232:235], v[86:89]
	v_mfma_f32_16x16x32_bf16 v[78:81], v[156:159], v[232:235], v[78:81]
	v_mfma_f32_16x16x32_bf16 v[126:129], v[152:155], v[212:215], v[126:129]
	v_mfma_f32_16x16x32_bf16 v[122:125], v[168:171], v[212:215], v[122:125]
	v_mfma_f32_16x16x32_bf16 v[114:117], v[152:155], v[220:223], v[114:117]
	v_mfma_f32_16x16x32_bf16 v[106:109], v[168:171], v[220:223], v[106:109]
	v_mfma_f32_16x16x32_bf16 v[102:105], v[152:155], v[228:231], v[102:105]
	v_mfma_f32_16x16x32_bf16 v[94:97], v[168:171], v[228:231], v[94:97]
	v_mfma_f32_16x16x32_bf16 v[86:89], v[152:155], v[236:239], v[86:89]
	v_mfma_f32_16x16x32_bf16 v[78:81], v[168:171], v[236:239], v[78:81]
	v_mfma_f32_16x16x32_bf16 v[118:121], v[172:175], v[208:211], v[118:121]
	v_mfma_f32_16x16x32_bf16 v[110:113], v[180:183], v[208:211], v[110:113]
	v_mfma_f32_16x16x32_bf16 v[98:101], v[172:175], v[216:219], v[98:101]
	v_mfma_f32_16x16x32_bf16 v[90:93], v[180:183], v[216:219], v[90:93]
	v_mfma_f32_16x16x32_bf16 v[82:85], v[172:175], v[224:227], v[82:85]
	v_mfma_f32_16x16x32_bf16 v[74:77], v[180:183], v[224:227], v[74:77]
	v_mfma_f32_16x16x32_bf16 v[70:73], v[172:175], v[232:235], v[70:73]
	v_mfma_f32_16x16x32_bf16 v[66:69], v[180:183], v[232:235], v[66:69]
	v_mfma_f32_16x16x32_bf16 v[118:121], v[176:179], v[212:215], v[118:121]
	v_mfma_f32_16x16x32_bf16 v[110:113], v[184:187], v[212:215], v[110:113]
	v_mfma_f32_16x16x32_bf16 v[98:101], v[176:179], v[220:223], v[98:101]
	v_mfma_f32_16x16x32_bf16 v[90:93], v[184:187], v[220:223], v[90:93]
	v_mfma_f32_16x16x32_bf16 v[82:85], v[176:179], v[228:231], v[82:85]
	v_mfma_f32_16x16x32_bf16 v[74:77], v[184:187], v[228:231], v[74:77]
	v_mfma_f32_16x16x32_bf16 v[70:73], v[176:179], v[236:239], v[70:73]
	v_mfma_f32_16x16x32_bf16 v[66:69], v[184:187], v[236:239], v[66:69]
	s_barrier
	s_setprio 0
	s_add_i32 s23, s23, s56
	v_lshl_add_u64 v[160:161], s[4:5], 0, v[132:133]
	s_mov_b32 m0, s23
	ds_read_b128 v[208:211], v147 offset:16384
	ds_read_b128 v[212:215], v147 offset:17408
	ds_read_b128 v[216:219], v147 offset:18432
	ds_read_b128 v[220:223], v147 offset:19456
	ds_read_b128 v[224:227], v147 offset:20480
	ds_read_b128 v[228:231], v147 offset:21504
	ds_read_b128 v[232:235], v147 offset:22528
	ds_read_b128 v[236:239], v147 offset:23552
	global_load_lds_dwordx4 v[160:161], off
	s_add_i32 m0, s23, 0x2000
	s_add_u32 s24, s4, 0x80000
	v_lshl_add_u64 v[240:241], s[4:5], 0, v[136:137]
	s_addc_u32 s25, s5, 0
	s_add_i32 s23, s26, s56
	global_load_lds_dwordx4 v[240:241], off
	v_lshl_add_u64 v[242:243], s[24:25], 0, v[132:133]
	s_mov_b32 m0, s23
	v_lshl_add_u64 v[244:245], s[6:7], 0, v[134:135]
	global_load_lds_dwordx4 v[242:243], off
	v_lshl_add_u64 v[242:243], s[24:25], 0, v[136:137]
	s_add_i32 m0, s23, 0x2000
	s_nop 0
	global_load_lds_dwordx4 v[242:243], off
	v_lshl_add_u64 v[242:243], s[6:7], 0, v[130:131]
	s_mov_b32 m0, s53
	s_nop 0
	global_load_lds_dwordx4 v[242:243], off
	s_mov_b32 m0, s80
	s_nop 0
	global_load_lds_dwordx4 v[244:245], off
	s_waitcnt vmcnt(8)
	s_waitcnt lgkmcnt(0)
	s_setprio 1
	s_barrier
; #define PG8_STAGE(bufoff, gbase, voff) do { _Pragma("unroll") for (int _i = 0; _i < 2; ++_i) \
;         __builtin_amdgcn_global_load_lds((const unsigned*)((const char*)(gbase) + (voff)[_i]), (LAS unsigned*)(lds + (bufoff) + ldsw + _i * 8192), 16, 0, 0); } while (0)
; #define PG8_LDA(dst, b, h) do { _Pragma("unroll") for (int m = 0; m < 4; ++m) _Pragma("unroll") for (int k = 0; k < 2; ++k) dst[m][k] = *(const LAS bf16x8*)(lds + PG8_SA(b, h) + aoff + m * 2048 + k * 1024); } while (0)
; #define PG8_LDB(dst, b, h) do { _Pragma("unroll") for (int n = 0; n < 2; ++n) _Pragma("unroll") for (int k = 0; k < 2; ++k) dst[n][k] = *(const LAS bf16x8*)(lds + PG8_SB(b, h) + boff + n * 2048 + k * 1024); } while (0)
; #define PG8_MMA(ai, bj, At, Bt) do { __builtin_amdgcn_s_setprio(1); _Pragma("unroll") for (int m = 0; m < 4; ++m) _Pragma("unroll") for (int n = 0; n < 2; ++n) _Pragma("unroll") for (int k = 0; k < 2; ++k) \
;         acc[ai][bj][m][n] = __builtin_amdgcn_mfma_f32_16x16x32_bf16(Bt[n][k], At[m][k], acc[ai][bj][m][n], 0, 0, 0); __builtin_amdgcn_s_setprio(0); } while (0)
; #define PG8_WAIT_V(n) asm volatile("s_waitcnt vmcnt(" #n ")" ::: "memory")
; #define PG8_WAIT_L(n) asm volatile("s_waitcnt lgkmcnt(" #n ")" ::: "memory")
; #define PG8_BAR __builtin_amdgcn_s_barrier()
; #define PG8_SCHED __builtin_amdgcn_sched_barrier(0)
; template <class Epi, class Order = StaticOrder, bool HALFN = false>
; __device__ __forceinline__ void gemm_phase(LAS unsigned char* lds, const Gemm g, const Epi& E) {
;     ...
;             PG8_LDA(At, 0, 1); PG8_STAGE(PG8_SB(0, 0), b2, voffB); PG8_STAGE(PG8_SB(0, 1), b2 + hstepB, voffB); PG8_STAGE(PG8_SA(0, 0), a2, voffA);
;             PG8_WAIT_V(8); PG8_WAIT_L(0); PG8_BAR; PG8_MMA(1, 0, At, B0); if constexpr (!HALFN) PG8_MMA(1, 1, At, B1); PG8_BAR; PG8_SCHED;
;             PG8_LDB(B0, 1, 0); if constexpr (!HALFN) PG8_LDB(B1, 1, 1); PG8_SCHED; PG8_LDA(At, 1, 0); PG8_STAGE(PG8_SA(0, 1), a2 + hstepA, voffA);
;             PG8_WAIT_V(8); PG8_WAIT_L(0); PG8_BAR; PG8_MMA(0, 0, At, B0); if constexpr (!HALFN) PG8_MMA(0, 1, At, B1); PG8_BAR; PG8_SCHED;
;             PG8_LDA(At, 1, 1); PG8_STAGE(PG8_SB(1, 0), b3, voffB); PG8_STAGE(PG8_SB(1, 1), b3 + hstepB, voffB); PG8_STAGE(PG8_SA(1, 0), a3, voffA);
	v_mfma_f32_16x16x32_bf16 v[62:65], v[148:151], v[208:211], v[62:65]
	v_mfma_f32_16x16x32_bf16 v[58:61], v[156:159], v[208:211], v[58:61]
	v_mfma_f32_16x16x32_bf16 v[54:57], v[148:151], v[216:219], v[54:57]
	v_mfma_f32_16x16x32_bf16 v[46:49], v[156:159], v[216:219], v[46:49]
	v_mfma_f32_16x16x32_bf16 v[38:41], v[148:151], v[224:227], v[38:41]
	v_mfma_f32_16x16x32_bf16 v[30:33], v[156:159], v[224:227], v[30:33]
	v_mfma_f32_16x16x32_bf16 v[22:25], v[148:151], v[232:235], v[22:25]
	v_mfma_f32_16x16x32_bf16 v[14:17], v[156:159], v[232:235], v[14:17]
	v_mfma_f32_16x16x32_bf16 v[62:65], v[152:155], v[212:215], v[62:65]
	v_mfma_f32_16x16x32_bf16 v[58:61], v[168:171], v[212:215], v[58:61]
	v_mfma_f32_16x16x32_bf16 v[54:57], v[152:155], v[220:223], v[54:57]
	v_mfma_f32_16x16x32_bf16 v[46:49], v[168:171], v[220:223], v[46:49]
	v_mfma_f32_16x16x32_bf16 v[38:41], v[152:155], v[228:231], v[38:41]
	v_mfma_f32_16x16x32_bf16 v[30:33], v[168:171], v[228:231], v[30:33]
	v_mfma_f32_16x16x32_bf16 v[22:25], v[152:155], v[236:239], v[22:25]
	v_mfma_f32_16x16x32_bf16 v[14:17], v[168:171], v[236:239], v[14:17]
	v_mfma_f32_16x16x32_bf16 v[50:53], v[172:175], v[208:211], v[50:53]
	v_mfma_f32_16x16x32_bf16 v[42:45], v[180:183], v[208:211], v[42:45]
	v_mfma_f32_16x16x32_bf16 v[34:37], v[172:175], v[216:219], v[34:37]
	v_mfma_f32_16x16x32_bf16 v[26:29], v[180:183], v[216:219], v[26:29]
	v_mfma_f32_16x16x32_bf16 v[18:21], v[172:175], v[224:227], v[18:21]
	v_mfma_f32_16x16x32_bf16 v[10:13], v[180:183], v[224:227], v[10:13]
	v_mfma_f32_16x16x32_bf16 v[6:9], v[172:175], v[232:235], v[6:9]
	v_mfma_f32_16x16x32_bf16 v[2:5], v[180:183], v[232:235], v[2:5]
	v_mfma_f32_16x16x32_bf16 v[50:53], v[176:179], v[212:215], v[50:53]
	v_mfma_f32_16x16x32_bf16 v[42:45], v[184:187], v[212:215], v[42:45]
	v_mfma_f32_16x16x32_bf16 v[34:37], v[176:179], v[220:223], v[34:37]
	v_mfma_f32_16x16x32_bf16 v[26:29], v[184:187], v[220:223], v[26:29]
	v_mfma_f32_16x16x32_bf16 v[18:21], v[176:179], v[228:231], v[18:21]
	v_mfma_f32_16x16x32_bf16 v[10:13], v[184:187], v[228:231], v[10:13]
	v_mfma_f32_16x16x32_bf16 v[6:9], v[176:179], v[236:239], v[6:9]
	v_mfma_f32_16x16x32_bf16 v[2:5], v[184:187], v[236:239], v[2:5]
	s_barrier
	s_setprio 0
	s_add_i32 s23, 0, 0x18000
	v_add_u32_e32 v142, s23, v145
	s_add_i32 s24, 0, 0x1c000
	ds_read_b128 v[148:151], v142
	ds_read_b128 v[152:155], v142 offset:1024
	ds_read_b128 v[156:159], v142 offset:2048
	ds_read_b128 v[168:171], v142 offset:3072
	v_add_u32_e32 v142, s24, v145
	ds_read_b128 v[172:175], v142
	ds_read_b128 v[176:179], v142 offset:1024
	ds_read_b128 v[180:183], v142 offset:2048
	ds_read_b128 v[184:187], v142 offset:3072
	s_add_u32 s6, s6, 0x80000
	s_addc_u32 s7, s7, 0
	s_mov_b32 m0, s81
	v_lshl_add_u64 v[246:247], s[6:7], 0, v[130:131]
	ds_read_b128 v[208:211], v147 offset:32768
	ds_read_b128 v[212:215], v147 offset:33792
	ds_read_b128 v[216:219], v147 offset:34816
	ds_read_b128 v[220:223], v147 offset:35840
	ds_read_b128 v[224:227], v147 offset:36864
	ds_read_b128 v[228:231], v147 offset:37888
	ds_read_b128 v[232:235], v147 offset:38912
	ds_read_b128 v[236:239], v147 offset:39936
	global_load_lds_dwordx4 v[246:247], off
	v_lshl_add_u64 v[246:247], s[6:7], 0, v[134:135]
	s_mov_b32 m0, s82
	s_nop 0
	global_load_lds_dwordx4 v[246:247], off
	s_waitcnt vmcnt(8)
	s_waitcnt lgkmcnt(0)
	s_setprio 1
	s_barrier
	v_mfma_f32_16x16x32_bf16 v[126:129], v[148:151], v[208:211], v[126:129]
	v_mfma_f32_16x16x32_bf16 v[122:125], v[156:159], v[208:211], v[122:125]
	v_mfma_f32_16x16x32_bf16 v[114:117], v[148:151], v[216:219], v[114:117]
	v_mfma_f32_16x16x32_bf16 v[106:109], v[156:159], v[216:219], v[106:109]
	v_mfma_f32_16x16x32_bf16 v[102:105], v[148:151], v[224:227], v[102:105]
	v_mfma_f32_16x16x32_bf16 v[94:97], v[156:159], v[224:227], v[94:97]
	v_mfma_f32_16x16x32_bf16 v[86:89], v[148:151], v[232:235], v[86:89]
	v_mfma_f32_16x16x32_bf16 v[78:81], v[156:159], v[232:235], v[78:81]
	v_mfma_f32_16x16x32_bf16 v[126:129], v[152:155], v[212:215], v[126:129]
	v_mfma_f32_16x16x32_bf16 v[122:125], v[168:171], v[212:215], v[122:125]
	v_mfma_f32_16x16x32_bf16 v[114:117], v[152:155], v[220:223], v[114:117]
	v_mfma_f32_16x16x32_bf16 v[106:109], v[168:171], v[220:223], v[106:109]
	v_mfma_f32_16x16x32_bf16 v[102:105], v[152:155], v[228:231], v[102:105]
	v_mfma_f32_16x16x32_bf16 v[94:97], v[168:171], v[228:231], v[94:97]
	v_mfma_f32_16x16x32_bf16 v[86:89], v[152:155], v[236:239], v[86:89]
	v_mfma_f32_16x16x32_bf16 v[78:81], v[168:171], v[236:239], v[78:81]
	v_mfma_f32_16x16x32_bf16 v[118:121], v[172:175], v[208:211], v[118:121]
	v_mfma_f32_16x16x32_bf16 v[110:113], v[180:183], v[208:211], v[110:113]
	v_mfma_f32_16x16x32_bf16 v[98:101], v[172:175], v[216:219], v[98:101]
	v_mfma_f32_16x16x32_bf16 v[90:93], v[180:183], v[216:219], v[90:93]
	v_mfma_f32_16x16x32_bf16 v[82:85], v[172:175], v[224:227], v[82:85]
	v_mfma_f32_16x16x32_bf16 v[74:77], v[180:183], v[224:227], v[74:77]
	v_mfma_f32_16x16x32_bf16 v[70:73], v[172:175], v[232:235], v[70:73]
	v_mfma_f32_16x16x32_bf16 v[66:69], v[180:183], v[232:235], v[66:69]
	v_mfma_f32_16x16x32_bf16 v[118:121], v[176:179], v[212:215], v[118:121]
	v_mfma_f32_16x16x32_bf16 v[110:113], v[184:187], v[212:215], v[110:113]
	v_mfma_f32_16x16x32_bf16 v[98:101], v[176:179], v[220:223], v[98:101]
	v_mfma_f32_16x16x32_bf16 v[90:93], v[184:187], v[220:223], v[90:93]
	v_mfma_f32_16x16x32_bf16 v[82:85], v[176:179], v[228:231], v[82:85]
	v_mfma_f32_16x16x32_bf16 v[74:77], v[184:187], v[228:231], v[74:77]
	v_mfma_f32_16x16x32_bf16 v[70:73], v[176:179], v[236:239], v[70:73]
	v_mfma_f32_16x16x32_bf16 v[66:69], v[184:187], v[236:239], v[66:69]
	s_barrier
; #define PG8_STAGE(bufoff, gbase, voff) do { _Pragma("unroll") for (int _i = 0; _i < 2; ++_i) \
;         __builtin_amdgcn_global_load_lds((const unsigned*)((const char*)(gbase) + (voff)[_i]), (LAS unsigned*)(lds + (bufoff) + ldsw + _i * 8192), 16, 0, 0); } while (0)
; #define PG8_LDA(dst, b, h) do { _Pragma("unroll") for (int m = 0; m < 4; ++m) _Pragma("unroll") for (int k = 0; k < 2; ++k) dst[m][k] = *(const LAS bf16x8*)(lds + PG8_SA(b, h) + aoff + m * 2048 + k * 1024); } while (0)
; #define PG8_MMA(ai, bj, At, Bt) do { __builtin_amdgcn_s_setprio(1); _Pragma("unroll") for (int m = 0; m < 4; ++m) _Pragma("unroll") for (int n = 0; n < 2; ++n) _Pragma("unroll") for (int k = 0; k < 2; ++k) \
;         acc[ai][bj][m][n] = __builtin_amdgcn_mfma_f32_16x16x32_bf16(Bt[n][k], At[m][k], acc[ai][bj][m][n], 0, 0, 0); __builtin_amdgcn_s_setprio(0); } while (0)
; #define PG8_WAIT_V(n) asm volatile("s_waitcnt vmcnt(" #n ")" ::: "memory")
; #define PG8_WAIT_L(n) asm volatile("s_waitcnt lgkmcnt(" #n ")" ::: "memory")
; #define PG8_BAR __builtin_amdgcn_s_barrier()
; #define PG8_SCHED __builtin_amdgcn_sched_barrier(0)
; template <class Epi, class Order = StaticOrder, bool HALFN = false>
; __device__ __forceinline__ void gemm_phase(LAS unsigned char* lds, const Gemm g, const Epi& E) {
;     ...
;             PG8_LDA(At, 1, 1); PG8_STAGE(PG8_SB(1, 0), b3, voffB); PG8_STAGE(PG8_SB(1, 1), b3 + hstepB, voffB); PG8_STAGE(PG8_SA(1, 0), a3, voffA);
;             PG8_WAIT_V(8); PG8_WAIT_L(0); PG8_BAR; PG8_MMA(1, 0, At, B0); if constexpr (!HALFN) PG8_MMA(1, 1, At, B1); PG8_BAR; PG8_SCHED;
;         }
;         if (wr == 0) PG8_BAR;
	s_setprio 0
	s_add_i32 s6, s23, s56
	v_lshl_add_u64 v[160:161], v[160:161], 0, s[60:61]
	s_mov_b32 m0, s6
	ds_read_b128 v[208:211], v147 offset:49152
	ds_read_b128 v[212:215], v147 offset:50176
	ds_read_b128 v[216:219], v147 offset:51200
	ds_read_b128 v[220:223], v147 offset:52224
	ds_read_b128 v[224:227], v147 offset:53248
	ds_read_b128 v[228:231], v147 offset:54272
	ds_read_b128 v[232:235], v147 offset:55296
	ds_read_b128 v[236:239], v147 offset:56320
	global_load_lds_dwordx4 v[160:161], off
	s_add_i32 m0, s6, 0x2000
	s_add_u32 s4, s4, 0x80080
	v_lshl_add_u64 v[160:161], v[240:241], 0, s[60:61]
	s_addc_u32 s5, s5, 0
	s_add_i32 s6, s24, s56
	global_load_lds_dwordx4 v[160:161], off
	v_lshl_add_u64 v[160:161], s[4:5], 0, v[132:133]
	s_mov_b32 m0, s6
	s_nop 0
	global_load_lds_dwordx4 v[160:161], off
	v_lshl_add_u64 v[160:161], s[4:5], 0, v[136:137]
	s_add_i32 m0, s6, 0x2000
	s_nop 0
	global_load_lds_dwordx4 v[160:161], off
	v_lshl_add_u64 v[160:161], v[242:243], 0, s[60:61]
	s_mov_b32 m0, s95
	s_nop 0
	global_load_lds_dwordx4 v[160:161], off
	v_lshl_add_u64 v[160:161], v[244:245], 0, s[60:61]
	s_mov_b32 m0, s15
	s_nop 0
	global_load_lds_dwordx4 v[160:161], off
	s_waitcnt vmcnt(8)
	s_waitcnt lgkmcnt(0)
	s_setprio 1
	s_barrier
	v_mfma_f32_16x16x32_bf16 v[62:65], v[148:151], v[208:211], v[62:65]
	v_mfma_f32_16x16x32_bf16 v[58:61], v[156:159], v[208:211], v[58:61]
	v_mfma_f32_16x16x32_bf16 v[54:57], v[148:151], v[216:219], v[54:57]
	v_mfma_f32_16x16x32_bf16 v[46:49], v[156:159], v[216:219], v[46:49]
	v_mfma_f32_16x16x32_bf16 v[38:41], v[148:151], v[224:227], v[38:41]
	v_mfma_f32_16x16x32_bf16 v[30:33], v[156:159], v[224:227], v[30:33]
	v_mfma_f32_16x16x32_bf16 v[22:25], v[148:151], v[232:235], v[22:25]
	v_mfma_f32_16x16x32_bf16 v[14:17], v[156:159], v[232:235], v[14:17]
	v_mfma_f32_16x16x32_bf16 v[62:65], v[152:155], v[212:215], v[62:65]
	v_mfma_f32_16x16x32_bf16 v[58:61], v[168:171], v[212:215], v[58:61]
	v_mfma_f32_16x16x32_bf16 v[54:57], v[152:155], v[220:223], v[54:57]
	v_mfma_f32_16x16x32_bf16 v[46:49], v[168:171], v[220:223], v[46:49]
	v_mfma_f32_16x16x32_bf16 v[38:41], v[152:155], v[228:231], v[38:41]
	v_mfma_f32_16x16x32_bf16 v[30:33], v[168:171], v[228:231], v[30:33]
	v_mfma_f32_16x16x32_bf16 v[22:25], v[152:155], v[236:239], v[22:25]
	v_mfma_f32_16x16x32_bf16 v[14:17], v[168:171], v[236:239], v[14:17]
	v_mfma_f32_16x16x32_bf16 v[50:53], v[172:175], v[208:211], v[50:53]
	v_mfma_f32_16x16x32_bf16 v[42:45], v[180:183], v[208:211], v[42:45]
	v_mfma_f32_16x16x32_bf16 v[34:37], v[172:175], v[216:219], v[34:37]
	v_mfma_f32_16x16x32_bf16 v[26:29], v[180:183], v[216:219], v[26:29]
	v_mfma_f32_16x16x32_bf16 v[18:21], v[172:175], v[224:227], v[18:21]
	v_mfma_f32_16x16x32_bf16 v[10:13], v[180:183], v[224:227], v[10:13]
	v_mfma_f32_16x16x32_bf16 v[6:9], v[172:175], v[232:235], v[6:9]
	v_mfma_f32_16x16x32_bf16 v[2:5], v[180:183], v[232:235], v[2:5]
	v_mfma_f32_16x16x32_bf16 v[50:53], v[176:179], v[212:215], v[50:53]
	v_mfma_f32_16x16x32_bf16 v[42:45], v[184:187], v[212:215], v[42:45]
	v_mfma_f32_16x16x32_bf16 v[34:37], v[176:179], v[220:223], v[34:37]
	v_mfma_f32_16x16x32_bf16 v[26:29], v[184:187], v[220:223], v[26:29]
	v_mfma_f32_16x16x32_bf16 v[18:21], v[176:179], v[228:231], v[18:21]
	v_mfma_f32_16x16x32_bf16 v[10:13], v[184:187], v[228:231], v[10:13]
	v_mfma_f32_16x16x32_bf16 v[6:9], v[176:179], v[236:239], v[6:9]
	v_mfma_f32_16x16x32_bf16 v[2:5], v[184:187], v[236:239], v[2:5]
	s_barrier
	s_setprio 0
	s_add_i32 s22, s22, 2
	s_add_u32 s62, s62, 0x100
	s_addc_u32 s63, s63, 0
	s_add_u32 s20, s20, 0x100
	s_addc_u32 s21, s21, 0
	s_cmp_gt_u32 s22, 29
	s_cbranch_scc0 .LBB0_194
	s_and_b64 vcc, exec, s[46:47]
	s_cbranch_vccz .LBB0_197
	s_barrier

; #define PG8_STAGE(bufoff, gbase, voff) do { _Pragma("unroll") for (int _i = 0; _i < 2; ++_i) \
;         __builtin_amdgcn_global_load_lds((const unsigned*)((const char*)(gbase) + (voff)[_i]), (LAS unsigned*)(lds + (bufoff) + ldsw + _i * 8192), 16, 0, 0); } while (0)
; #define PG8_LDA(dst, b, h) do { _Pragma("unroll") for (int m = 0; m < 4; ++m) _Pragma("unroll") for (int k = 0; k < 2; ++k) dst[m][k] = *(const LAS bf16x8*)(lds + PG8_SA(b, h) + aoff + m * 2048 + k * 1024); } while (0)
; #define PG8_LDB(dst, b, h) do { _Pragma("unroll") for (int n = 0; n < 2; ++n) _Pragma("unroll") for (int k = 0; k < 2; ++k) dst[n][k] = *(const LAS bf16x8*)(lds + PG8_SB(b, h) + boff + n * 2048 + k * 1024); } while (0)
; #define PG8_MMA(ai, bj, At, Bt) do { __builtin_amdgcn_s_setprio(1); _Pragma("unroll") for (int m = 0; m < 4; ++m) _Pragma("unroll") for (int n = 0; n < 2; ++n) _Pragma("unroll") for (int k = 0; k < 2; ++k) \
;         acc[ai][bj][m][n] = __builtin_amdgcn_mfma_f32_16x16x32_bf16(Bt[n][k], At[m][k], acc[ai][bj][m][n], 0, 0, 0); __builtin_amdgcn_s_setprio(0); } while (0)
; #define PG8_WAIT_V(n) asm volatile("s_waitcnt vmcnt(" #n ")" ::: "memory")
; #define PG8_WAIT_L(n) asm volatile("s_waitcnt lgkmcnt(" #n ")" ::: "memory")
; #define PG8_BAR __builtin_amdgcn_s_barrier()
; #define PG8_SCHED __builtin_amdgcn_sched_barrier(0)
; template <class Epi, class Order = StaticOrder, bool HALFN = false>
; __device__ __forceinline__ void gemm_phase(LAS unsigned char* lds, const Gemm g, const Epi& E) {
;     ...
;             const char* a1 = cA + (size_t)(t + 1) * kstep;
;             const char* a2 = last ? nA : cA + (size_t)(t + 2) * kstep; const char* b2 = last ? nB : cB + (size_t)(t + 2) * kstep;
;             const char* a3 = a2 + kstep; const char* b3 = b2 + kstep;
;             PG8_LDB(B0, 0, 0); if constexpr (!HALFN) PG8_LDB(B1, 0, 1); PG8_SCHED; PG8_LDA(At, 0, 0); PG8_STAGE(PG8_SA(1, 1), a1 + hstepA, voffA);
;             PG8_WAIT_V(8); PG8_WAIT_L(0); PG8_BAR; PG8_MMA(0, 0, At, B0); if constexpr (!HALFN) PG8_MMA(0, 1, At, B1); PG8_BAR; PG8_SCHED;
;             PG8_LDA(At, 0, 1); PG8_STAGE(PG8_SB(0, 0), b2, voffB); PG8_STAGE(PG8_SB(0, 1), b2 + hstepB, voffB); PG8_STAGE(PG8_SA(0, 0), a2, voffA);
;             PG8_WAIT_V(8); PG8_WAIT_L(0); PG8_BAR; PG8_MMA(1, 0, At, B0); if constexpr (!HALFN) PG8_MMA(1, 1, At, B1); PG8_BAR; PG8_SCHED;
.LBB0_239:
	s_add_u32 s4, vcc_lo, 0xfff80080
	s_addc_u32 s5, vcc_hi, -1
	s_add_i32 s34, 0, 0x10000
	v_add_u32_e32 v78, s34, v81
	ds_read_b128 v[84:87], v78
	ds_read_b128 v[88:91], v78 offset:1024
	ds_read_b128 v[92:95], v78 offset:2048
	ds_read_b128 v[96:99], v78 offset:3072
	s_cmp_eq_u32 s31, 28
	s_cselect_b32 s9, s25, s5
	s_cselect_b32 s8, s26, s4
	s_cselect_b32 s5, s27, s30
	s_cselect_b32 s4, s28, s29
	v_lshl_add_u64 v[132:133], vcc, 0, v[74:75]
	s_add_i32 m0, s16, 0xc000
	ds_read_b128 v[100:103], v83
	ds_read_b128 v[104:107], v83 offset:1024
	ds_read_b128 v[108:111], v83 offset:2048
	ds_read_b128 v[112:115], v83 offset:3072
	ds_read_b128 v[116:119], v83 offset:4096
	ds_read_b128 v[120:123], v83 offset:5120
	ds_read_b128 v[124:127], v83 offset:6144
	ds_read_b128 v[128:131], v83 offset:7168
	global_load_lds_dwordx4 v[132:133], off
	v_lshl_add_u64 v[132:133], vcc, 0, v[76:77]
	s_add_i32 m0, s16, 0xe000
	s_nop 0
	global_load_lds_dwordx4 v[132:133], off
	s_waitcnt vmcnt(8)
	s_waitcnt lgkmcnt(0)
	s_setprio 1
	s_barrier
	v_mfma_f32_16x16x32_bf16 v[62:65], v[84:87], v[100:103], v[62:65]
	v_mfma_f32_16x16x32_bf16 v[58:61], v[92:95], v[100:103], v[58:61]
	v_mfma_f32_16x16x32_bf16 v[54:57], v[84:87], v[108:111], v[54:57]
	v_mfma_f32_16x16x32_bf16 v[50:53], v[92:95], v[108:111], v[50:53]
	v_mfma_f32_16x16x32_bf16 v[46:49], v[84:87], v[116:119], v[46:49]
	v_mfma_f32_16x16x32_bf16 v[42:45], v[92:95], v[116:119], v[42:45]
	v_mfma_f32_16x16x32_bf16 v[38:41], v[84:87], v[124:127], v[38:41]
	v_mfma_f32_16x16x32_bf16 v[34:37], v[92:95], v[124:127], v[34:37]
	v_mfma_f32_16x16x32_bf16 v[62:65], v[88:91], v[104:107], v[62:65]
	v_mfma_f32_16x16x32_bf16 v[58:61], v[96:99], v[104:107], v[58:61]
	v_mfma_f32_16x16x32_bf16 v[54:57], v[88:91], v[112:115], v[54:57]
	v_mfma_f32_16x16x32_bf16 v[50:53], v[96:99], v[112:115], v[50:53]
	v_mfma_f32_16x16x32_bf16 v[46:49], v[88:91], v[120:123], v[46:49]
	v_mfma_f32_16x16x32_bf16 v[42:45], v[96:99], v[120:123], v[42:45]
	v_mfma_f32_16x16x32_bf16 v[38:41], v[88:91], v[128:131], v[38:41]
	v_mfma_f32_16x16x32_bf16 v[34:37], v[96:99], v[128:131], v[34:37]
	s_barrier
	s_setprio 0
	s_add_i32 s34, s34, s15
	v_lshl_add_u64 v[132:133], s[4:5], 0, v[68:69]
	s_mov_b32 m0, s34
	ds_read_b128 v[100:103], v83 offset:16384
	ds_read_b128 v[104:107], v83 offset:17408
	ds_read_b128 v[108:111], v83 offset:18432
	ds_read_b128 v[112:115], v83 offset:19456
	ds_read_b128 v[116:119], v83 offset:20480
	ds_read_b128 v[120:123], v83 offset:21504
	ds_read_b128 v[124:127], v83 offset:22528
	ds_read_b128 v[128:131], v83 offset:23552
	global_load_lds_dwordx4 v[132:133], off
	s_add_i32 m0, s34, 0x2000
	s_add_u32 s34, s4, 0x80000
	v_lshl_add_u64 v[134:135], s[4:5], 0, v[72:73]
	s_addc_u32 s35, s5, 0
	global_load_lds_dwordx4 v[134:135], off
	v_lshl_add_u64 v[136:137], s[34:35], 0, v[68:69]
	s_mov_b32 m0, s17
	v_lshl_add_u64 v[138:139], s[8:9], 0, v[70:71]
	global_load_lds_dwordx4 v[136:137], off
	v_lshl_add_u64 v[136:137], s[34:35], 0, v[72:73]
	s_mov_b32 m0, s18
	s_nop 0
	global_load_lds_dwordx4 v[136:137], off
	v_lshl_add_u64 v[136:137], s[8:9], 0, v[66:67]
	s_mov_b32 m0, s16
	s_nop 0
	global_load_lds_dwordx4 v[136:137], off
	s_mov_b32 m0, s19
	s_nop 0
	global_load_lds_dwordx4 v[138:139], off
	s_waitcnt vmcnt(8)
	s_waitcnt lgkmcnt(0)
	s_setprio 1
	s_barrier
	v_mfma_f32_16x16x32_bf16 v[30:33], v[84:87], v[100:103], v[30:33]
	v_mfma_f32_16x16x32_bf16 v[26:29], v[92:95], v[100:103], v[26:29]
	v_mfma_f32_16x16x32_bf16 v[22:25], v[84:87], v[108:111], v[22:25]
	v_mfma_f32_16x16x32_bf16 v[18:21], v[92:95], v[108:111], v[18:21]
	v_mfma_f32_16x16x32_bf16 v[14:17], v[84:87], v[116:119], v[14:17]
	v_mfma_f32_16x16x32_bf16 v[10:13], v[92:95], v[116:119], v[10:13]
	v_mfma_f32_16x16x32_bf16 v[6:9], v[84:87], v[124:127], v[6:9]
	v_mfma_f32_16x16x32_bf16 v[2:5], v[92:95], v[124:127], v[2:5]
	v_mfma_f32_16x16x32_bf16 v[30:33], v[88:91], v[104:107], v[30:33]
	v_mfma_f32_16x16x32_bf16 v[26:29], v[96:99], v[104:107], v[26:29]
	v_mfma_f32_16x16x32_bf16 v[22:25], v[88:91], v[112:115], v[22:25]
	v_mfma_f32_16x16x32_bf16 v[18:21], v[96:99], v[112:115], v[18:21]
	v_mfma_f32_16x16x32_bf16 v[14:17], v[88:91], v[120:123], v[14:17]
	v_mfma_f32_16x16x32_bf16 v[10:13], v[96:99], v[120:123], v[10:13]
	v_mfma_f32_16x16x32_bf16 v[6:9], v[88:91], v[128:131], v[6:9]
	v_mfma_f32_16x16x32_bf16 v[2:5], v[96:99], v[128:131], v[2:5]
	s_barrier
; #define PG8_STAGE(bufoff, gbase, voff) do { _Pragma("unroll") for (int _i = 0; _i < 2; ++_i) \
;         __builtin_amdgcn_global_load_lds((const unsigned*)((const char*)(gbase) + (voff)[_i]), (LAS unsigned*)(lds + (bufoff) + ldsw + _i * 8192), 16, 0, 0); } while (0)
; #define PG8_LDA(dst, b, h) do { _Pragma("unroll") for (int m = 0; m < 4; ++m) _Pragma("unroll") for (int k = 0; k < 2; ++k) dst[m][k] = *(const LAS bf16x8*)(lds + PG8_SA(b, h) + aoff + m * 2048 + k * 1024); } while (0)
; #define PG8_LDB(dst, b, h) do { _Pragma("unroll") for (int n = 0; n < 2; ++n) _Pragma("unroll") for (int k = 0; k < 2; ++k) dst[n][k] = *(const LAS bf16x8*)(lds + PG8_SB(b, h) + boff + n * 2048 + k * 1024); } while (0)
; #define PG8_MMA(ai, bj, At, Bt) do { __builtin_amdgcn_s_setprio(1); _Pragma("unroll") for (int m = 0; m < 4; ++m) _Pragma("unroll") for (int n = 0; n < 2; ++n) _Pragma("unroll") for (int k = 0; k < 2; ++k) \
;         acc[ai][bj][m][n] = __builtin_amdgcn_mfma_f32_16x16x32_bf16(Bt[n][k], At[m][k], acc[ai][bj][m][n], 0, 0, 0); __builtin_amdgcn_s_setprio(0); } while (0)
; #define PG8_WAIT_V(n) asm volatile("s_waitcnt vmcnt(" #n ")" ::: "memory")
; #define PG8_WAIT_L(n) asm volatile("s_waitcnt lgkmcnt(" #n ")" ::: "memory")
; #define PG8_BAR __builtin_amdgcn_s_barrier()
; #define PG8_SCHED __builtin_amdgcn_sched_barrier(0)
; template <class Epi, class Order = StaticOrder, bool HALFN = false>
; __device__ __forceinline__ void gemm_phase(LAS unsigned char* lds, const Gemm g, const Epi& E) {
;     ...
;             PG8_LDB(B0, 1, 0); if constexpr (!HALFN) PG8_LDB(B1, 1, 1); PG8_SCHED; PG8_LDA(At, 1, 0); PG8_STAGE(PG8_SA(0, 1), a2 + hstepA, voffA);
;             PG8_WAIT_V(8); PG8_WAIT_L(0); PG8_BAR; PG8_MMA(0, 0, At, B0); if constexpr (!HALFN) PG8_MMA(0, 1, At, B1); PG8_BAR; PG8_SCHED;
;             PG8_LDA(At, 1, 1); PG8_STAGE(PG8_SB(1, 0), b3, voffB); PG8_STAGE(PG8_SB(1, 1), b3 + hstepB, voffB); PG8_STAGE(PG8_SA(1, 0), a3, voffA);
;             PG8_WAIT_V(8); PG8_WAIT_L(0); PG8_BAR; PG8_MMA(1, 0, At, B0); if constexpr (!HALFN) PG8_MMA(1, 1, At, B1); PG8_BAR; PG8_SCHED;
;         }
;         if (wr == 0) PG8_BAR;
	s_setprio 0
	s_add_i32 s34, 0, 0x18000
	v_add_u32_e32 v78, s34, v81
	ds_read_b128 v[84:87], v78
	ds_read_b128 v[88:91], v78 offset:1024
	ds_read_b128 v[92:95], v78 offset:2048
	ds_read_b128 v[96:99], v78 offset:3072
	s_add_u32 s8, s8, 0x80000
	s_addc_u32 s9, s9, 0
	s_mov_b32 m0, s20
	v_lshl_add_u64 v[140:141], s[8:9], 0, v[66:67]
	ds_read_b128 v[100:103], v83 offset:32768
	ds_read_b128 v[104:107], v83 offset:33792
	ds_read_b128 v[108:111], v83 offset:34816
	ds_read_b128 v[112:115], v83 offset:35840
	ds_read_b128 v[116:119], v83 offset:36864
	ds_read_b128 v[120:123], v83 offset:37888
	ds_read_b128 v[124:127], v83 offset:38912
	ds_read_b128 v[128:131], v83 offset:39936
	global_load_lds_dwordx4 v[140:141], off
	v_lshl_add_u64 v[140:141], s[8:9], 0, v[70:71]
	s_mov_b32 m0, s21
	s_nop 0
	global_load_lds_dwordx4 v[140:141], off
	s_waitcnt vmcnt(8)
	s_waitcnt lgkmcnt(0)
	s_setprio 1
	s_barrier
	v_mfma_f32_16x16x32_bf16 v[62:65], v[84:87], v[100:103], v[62:65]
	v_mfma_f32_16x16x32_bf16 v[58:61], v[92:95], v[100:103], v[58:61]
	v_mfma_f32_16x16x32_bf16 v[54:57], v[84:87], v[108:111], v[54:57]
	v_mfma_f32_16x16x32_bf16 v[50:53], v[92:95], v[108:111], v[50:53]
	v_mfma_f32_16x16x32_bf16 v[46:49], v[84:87], v[116:119], v[46:49]
	v_mfma_f32_16x16x32_bf16 v[42:45], v[92:95], v[116:119], v[42:45]
	v_mfma_f32_16x16x32_bf16 v[38:41], v[84:87], v[124:127], v[38:41]
	v_mfma_f32_16x16x32_bf16 v[34:37], v[92:95], v[124:127], v[34:37]
	v_mfma_f32_16x16x32_bf16 v[62:65], v[88:91], v[104:107], v[62:65]
	v_mfma_f32_16x16x32_bf16 v[58:61], v[96:99], v[104:107], v[58:61]
	v_mfma_f32_16x16x32_bf16 v[54:57], v[88:91], v[112:115], v[54:57]
	v_mfma_f32_16x16x32_bf16 v[50:53], v[96:99], v[112:115], v[50:53]
	v_mfma_f32_16x16x32_bf16 v[46:49], v[88:91], v[120:123], v[46:49]
	v_mfma_f32_16x16x32_bf16 v[42:45], v[96:99], v[120:123], v[42:45]
	v_mfma_f32_16x16x32_bf16 v[38:41], v[88:91], v[128:131], v[38:41]
	v_mfma_f32_16x16x32_bf16 v[34:37], v[96:99], v[128:131], v[34:37]
	s_barrier
	s_setprio 0
	s_add_i32 s8, s34, s15
	v_lshl_add_u64 v[132:133], v[132:133], 0, s[60:61]
	s_mov_b32 m0, s8
	ds_read_b128 v[100:103], v83 offset:49152
	ds_read_b128 v[104:107], v83 offset:50176
	ds_read_b128 v[108:111], v83 offset:51200
	ds_read_b128 v[112:115], v83 offset:52224
	ds_read_b128 v[116:119], v83 offset:53248
	ds_read_b128 v[120:123], v83 offset:54272
	ds_read_b128 v[124:127], v83 offset:55296
	ds_read_b128 v[128:131], v83 offset:56320
	global_load_lds_dwordx4 v[132:133], off
	s_add_i32 m0, s8, 0x2000
	s_add_u32 s4, s4, 0x80080
	v_lshl_add_u64 v[132:133], v[134:135], 0, s[60:61]
	s_addc_u32 s5, s5, 0
	global_load_lds_dwordx4 v[132:133], off
	v_lshl_add_u64 v[132:133], s[4:5], 0, v[68:69]
	s_mov_b32 m0, s56
	s_nop 0
	global_load_lds_dwordx4 v[132:133], off
	v_lshl_add_u64 v[132:133], s[4:5], 0, v[72:73]
	s_mov_b32 m0, s81
	s_nop 0
	global_load_lds_dwordx4 v[132:133], off
	v_lshl_add_u64 v[132:133], v[136:137], 0, s[60:61]
	s_mov_b32 m0, s51
	s_nop 0
	global_load_lds_dwordx4 v[132:133], off
	v_lshl_add_u64 v[132:133], v[138:139], 0, s[60:61]
	s_mov_b32 m0, s53
	s_nop 0
	global_load_lds_dwordx4 v[132:133], off
	s_waitcnt vmcnt(8)
	s_waitcnt lgkmcnt(0)
	s_setprio 1
	s_barrier
	v_mfma_f32_16x16x32_bf16 v[30:33], v[84:87], v[100:103], v[30:33]
	v_mfma_f32_16x16x32_bf16 v[26:29], v[92:95], v[100:103], v[26:29]
	v_mfma_f32_16x16x32_bf16 v[22:25], v[84:87], v[108:111], v[22:25]
	v_mfma_f32_16x16x32_bf16 v[18:21], v[92:95], v[108:111], v[18:21]
	v_mfma_f32_16x16x32_bf16 v[14:17], v[84:87], v[116:119], v[14:17]
	v_mfma_f32_16x16x32_bf16 v[10:13], v[92:95], v[116:119], v[10:13]
	v_mfma_f32_16x16x32_bf16 v[6:9], v[84:87], v[124:127], v[6:9]
	v_mfma_f32_16x16x32_bf16 v[2:5], v[92:95], v[124:127], v[2:5]
	v_mfma_f32_16x16x32_bf16 v[30:33], v[88:91], v[104:107], v[30:33]
	v_mfma_f32_16x16x32_bf16 v[26:29], v[96:99], v[104:107], v[26:29]
	v_mfma_f32_16x16x32_bf16 v[22:25], v[88:91], v[112:115], v[22:25]
	v_mfma_f32_16x16x32_bf16 v[18:21], v[96:99], v[112:115], v[18:21]
	v_mfma_f32_16x16x32_bf16 v[14:17], v[88:91], v[120:123], v[14:17]
	v_mfma_f32_16x16x32_bf16 v[10:13], v[96:99], v[120:123], v[10:13]
	v_mfma_f32_16x16x32_bf16 v[6:9], v[88:91], v[128:131], v[6:9]
	v_mfma_f32_16x16x32_bf16 v[2:5], v[96:99], v[128:131], v[2:5]
	s_barrier
	s_setprio 0
	s_add_i32 s31, s31, 2
	s_add_u32 vcc_lo, vcc_lo, 0x100
	s_addc_u32 vcc_hi, vcc_hi, 0
	s_add_u32 s29, s29, 0x100
	s_addc_u32 s30, s30, 0
	s_cmp_gt_u32 s31, 29
	s_cbranch_scc0 .LBB0_239
	s_and_b64 vcc, exec, s[48:49]
	s_cbranch_vccz .LBB0_242
	s_barrier

; #define PG8_STAGE(bufoff, gbase, voff) do { _Pragma("unroll") for (int _i = 0; _i < 2; ++_i) \
;         __builtin_amdgcn_global_load_lds((const unsigned*)((const char*)(gbase) + (voff)[_i]), (LAS unsigned*)(lds + (bufoff) + ldsw + _i * 8192), 16, 0, 0); } while (0)
; #define PG8_LDA(dst, b, h) do { _Pragma("unroll") for (int m = 0; m < 4; ++m) _Pragma("unroll") for (int k = 0; k < 2; ++k) dst[m][k] = *(const LAS bf16x8*)(lds + PG8_SA(b, h) + aoff + m * 2048 + k * 1024); } while (0)
; #define PG8_LDB(dst, b, h) do { _Pragma("unroll") for (int n = 0; n < 2; ++n) _Pragma("unroll") for (int k = 0; k < 2; ++k) dst[n][k] = *(const LAS bf16x8*)(lds + PG8_SB(b, h) + boff + n * 2048 + k * 1024); } while (0)
; #define PG8_MMA(ai, bj, At, Bt) do { __builtin_amdgcn_s_setprio(1); _Pragma("unroll") for (int m = 0; m < 4; ++m) _Pragma("unroll") for (int n = 0; n < 2; ++n) _Pragma("unroll") for (int k = 0; k < 2; ++k) \
;         acc[ai][bj][m][n] = __builtin_amdgcn_mfma_f32_16x16x32_bf16(Bt[n][k], At[m][k], acc[ai][bj][m][n], 0, 0, 0); __builtin_amdgcn_s_setprio(0); } while (0)
; #define PG8_WAIT_V(n) asm volatile("s_waitcnt vmcnt(" #n ")" ::: "memory")
; template <class Epi, class Order = StaticOrder, bool HALFN = false>
; __device__ __forceinline__ void gemm_phase(LAS unsigned char* lds, const Gemm g, const Epi& E) {
;     ...
;             const bool last = (t == nt - 2);
;             if constexpr (Epi::SEAMS) { if (t == Epi::SEAM0 || t == Epi::SEAM1) E.seam(acc, cur, t == Epi::SEAM0 ? 0 : 1, wr, wc, fr, fq); }
;             const char* a1 = cA + (size_t)(t + 1) * kstep;
;             const char* a2 = last ? nA : cA + (size_t)(t + 2) * kstep; const char* b2 = last ? nB : cB + (size_t)(t + 2) * kstep;
;             const char* a3 = a2 + kstep; const char* b3 = b2 + kstep;
;             PG8_LDB(B0, 0, 0); if constexpr (!HALFN) PG8_LDB(B1, 0, 1); PG8_SCHED; PG8_LDA(At, 0, 0); PG8_STAGE(PG8_SA(1, 1), a1 + hstepA, voffA);
;             PG8_WAIT_V(8); PG8_WAIT_L(0); PG8_BAR; PG8_MMA(0, 0, At, B0); if constexpr (!HALFN) PG8_MMA(0, 1, At, B1); PG8_BAR; PG8_SCHED;
;             PG8_LDA(At, 0, 1); PG8_STAGE(PG8_SB(0, 0), b2, voffB); PG8_STAGE(PG8_SB(0, 1), b2 + hstepB, voffB); PG8_STAGE(PG8_SA(0, 0), a2, voffA);
;             PG8_WAIT_V(8); PG8_WAIT_L(0); PG8_BAR; PG8_MMA(1, 0, At, B0); if constexpr (!HALFN) PG8_MMA(1, 1, At, B1); PG8_BAR; PG8_SCHED;
.LBB0_489:
	s_add_u32 s8, s54, s4
	s_addc_u32 s9, s55, s5
	s_add_u32 s10, s8, 0x100
	s_addc_u32 s11, s9, 0
	s_and_b64 s[6:7], s[42:43], exec
	s_cselect_b32 s7, s26, s11
	s_cselect_b32 s6, s27, s10
	s_add_u32 s4, s94, s4
	s_addc_u32 s5, s95, s5
	s_add_u32 s10, s4, 0x100
	s_addc_u32 s11, s5, 0
	s_add_i32 s83, 0, 0x10000
	s_and_b64 s[4:5], s[42:43], exec
	s_cselect_b32 vcc_hi, s49, s11
	s_cselect_b32 vcc_lo, s51, s10
	s_add_i32 s5, 0, 0x14000
	s_add_u32 s10, s8, 0x40080
	s_addc_u32 s11, s9, 0
	s_add_i32 s37, s83, s96
	s_add_i32 m0, s59, 0xc000
	s_add_i32 s88, s59, 0xe000
	s_add_i32 s34, s37, 0x2000
	s_add_u32 s8, vcc_lo, 0x10000
	v_add_u32_e32 v142, s83, v181
	v_add_u32_e32 v172, s5, v181
	s_addc_u32 s9, vcc_hi, 0
	s_add_i32 s36, s5, s96
	ds_read_b128 v[118:121], v142
	ds_read_b128 v[126:129], v142 offset:1024
	ds_read_b128 v[138:141], v142 offset:2048
	ds_read_b128 v[142:145], v142 offset:3072
	ds_read_b128 v[146:149], v172
	ds_read_b128 v[150:153], v172 offset:1024
	ds_read_b128 v[154:157], v172 offset:2048
	ds_read_b128 v[172:175], v172 offset:3072
	s_add_i32 s35, s36, 0x2000
	s_add_i32 s31, 0, 0x18000
	s_add_i32 s30, 0, 0x1c000
	s_add_u32 s42, s6, 0x40000
	s_addc_u32 s43, s7, 0
	s_add_i32 s29, s31, s96
	s_add_i32 s28, s29, 0x2000
	s_add_u32 s4, vcc_lo, 0x10080
	s_addc_u32 s5, vcc_hi, 0
	s_add_i32 s93, s30, s96
	s_add_i32 s83, s93, 0x2000
	v_lshl_add_u64 v[232:233], s[10:11], 0, v[158:159]
	ds_read_b128 v[176:179], v182
	ds_read_b128 v[184:187], v182 offset:1024
	ds_read_b128 v[208:211], v182 offset:2048
	ds_read_b128 v[212:215], v182 offset:3072
	ds_read_b128 v[216:219], v182 offset:4096
	ds_read_b128 v[220:223], v182 offset:5120
	ds_read_b128 v[224:227], v182 offset:6144
	ds_read_b128 v[228:231], v182 offset:7168
	global_load_lds_dwordx4 v[232:233], off
	v_lshl_add_u64 v[232:233], s[10:11], 0, v[168:169]
	s_mov_b32 m0, s88
	s_nop 0
	global_load_lds_dwordx4 v[232:233], off
	s_waitcnt vmcnt(8)
	s_waitcnt lgkmcnt(0)
	s_setprio 1
	s_barrier
	v_mfma_f32_16x16x32_bf16 v[134:137], v[118:121], v[176:179], v[134:137]
	v_mfma_f32_16x16x32_bf16 v[130:133], v[138:141], v[176:179], v[130:133]
	v_mfma_f32_16x16x32_bf16 v[110:113], v[118:121], v[208:211], v[110:113]
	v_mfma_f32_16x16x32_bf16 v[106:109], v[138:141], v[208:211], v[106:109]
	v_mfma_f32_16x16x32_bf16 v[94:97], v[118:121], v[216:219], v[94:97]
	v_mfma_f32_16x16x32_bf16 v[90:93], v[138:141], v[216:219], v[90:93]
	v_mfma_f32_16x16x32_bf16 v[78:81], v[118:121], v[224:227], v[78:81]
	v_mfma_f32_16x16x32_bf16 v[74:77], v[138:141], v[224:227], v[74:77]
	v_mfma_f32_16x16x32_bf16 v[134:137], v[126:129], v[184:187], v[134:137]
	v_mfma_f32_16x16x32_bf16 v[130:133], v[142:145], v[184:187], v[130:133]
	v_mfma_f32_16x16x32_bf16 v[110:113], v[126:129], v[212:215], v[110:113]
	v_mfma_f32_16x16x32_bf16 v[106:109], v[142:145], v[212:215], v[106:109]
	v_mfma_f32_16x16x32_bf16 v[94:97], v[126:129], v[220:223], v[94:97]
	v_mfma_f32_16x16x32_bf16 v[90:93], v[142:145], v[220:223], v[90:93]
	v_mfma_f32_16x16x32_bf16 v[78:81], v[126:129], v[228:231], v[78:81]
	v_mfma_f32_16x16x32_bf16 v[74:77], v[142:145], v[228:231], v[74:77]
	v_mfma_f32_16x16x32_bf16 v[122:125], v[146:149], v[176:179], v[122:125]
	v_mfma_f32_16x16x32_bf16 v[114:117], v[154:157], v[176:179], v[114:117]
	v_mfma_f32_16x16x32_bf16 v[102:105], v[146:149], v[208:211], v[102:105]
	v_mfma_f32_16x16x32_bf16 v[98:101], v[154:157], v[208:211], v[98:101]
	v_mfma_f32_16x16x32_bf16 v[86:89], v[146:149], v[216:219], v[86:89]
	v_mfma_f32_16x16x32_bf16 v[82:85], v[154:157], v[216:219], v[82:85]
	v_mfma_f32_16x16x32_bf16 v[70:73], v[146:149], v[224:227], v[70:73]
	v_mfma_f32_16x16x32_bf16 v[66:69], v[154:157], v[224:227], v[66:69]
	v_mfma_f32_16x16x32_bf16 v[122:125], v[150:153], v[184:187], v[122:125]
	v_mfma_f32_16x16x32_bf16 v[114:117], v[172:175], v[184:187], v[114:117]
	v_mfma_f32_16x16x32_bf16 v[102:105], v[150:153], v[212:215], v[102:105]
	v_mfma_f32_16x16x32_bf16 v[98:101], v[172:175], v[212:215], v[98:101]
	v_mfma_f32_16x16x32_bf16 v[86:89], v[150:153], v[220:223], v[86:89]
	v_mfma_f32_16x16x32_bf16 v[82:85], v[172:175], v[220:223], v[82:85]
	v_mfma_f32_16x16x32_bf16 v[70:73], v[150:153], v[228:231], v[70:73]
	v_mfma_f32_16x16x32_bf16 v[66:69], v[172:175], v[228:231], v[66:69]
	s_barrier
	s_setprio 0
	s_mov_b32 m0, s37
	v_lshl_add_u64 v[232:233], vcc, 0, v[160:161]
	ds_read_b128 v[176:179], v182 offset:16384
	ds_read_b128 v[184:187], v182 offset:17408
	ds_read_b128 v[208:211], v182 offset:18432
	ds_read_b128 v[212:215], v182 offset:19456
	ds_read_b128 v[216:219], v182 offset:20480
	ds_read_b128 v[220:223], v182 offset:21504
	ds_read_b128 v[224:227], v182 offset:22528
	ds_read_b128 v[228:231], v182 offset:23552
	global_load_lds_dwordx4 v[232:233], off
	v_lshl_add_u64 v[234:235], vcc, 0, v[170:171]
	s_mov_b32 m0, s34
	v_lshl_add_u64 v[236:237], s[8:9], 0, v[160:161]
	global_load_lds_dwordx4 v[234:235], off
	s_mov_b32 m0, s36
	v_lshl_add_u64 v[238:239], s[6:7], 0, v[168:169]
	global_load_lds_dwordx4 v[236:237], off
	v_lshl_add_u64 v[236:237], s[8:9], 0, v[170:171]
	s_mov_b32 m0, s35
	s_nop 0
	global_load_lds_dwordx4 v[236:237], off
	v_lshl_add_u64 v[236:237], s[6:7], 0, v[158:159]
	s_mov_b32 m0, s59
	s_nop 0
	global_load_lds_dwordx4 v[236:237], off
	s_mov_b32 m0, s97
	s_nop 0
	global_load_lds_dwordx4 v[238:239], off
	s_waitcnt vmcnt(8)
	s_waitcnt lgkmcnt(0)
	s_setprio 1
	s_barrier
; #define PG8_STAGE(bufoff, gbase, voff) do { _Pragma("unroll") for (int _i = 0; _i < 2; ++_i) \
;         __builtin_amdgcn_global_load_lds((const unsigned*)((const char*)(gbase) + (voff)[_i]), (LAS unsigned*)(lds + (bufoff) + ldsw + _i * 8192), 16, 0, 0); } while (0)
; #define PG8_LDA(dst, b, h) do { _Pragma("unroll") for (int m = 0; m < 4; ++m) _Pragma("unroll") for (int k = 0; k < 2; ++k) dst[m][k] = *(const LAS bf16x8*)(lds + PG8_SA(b, h) + aoff + m * 2048 + k * 1024); } while (0)
; #define PG8_LDB(dst, b, h) do { _Pragma("unroll") for (int n = 0; n < 2; ++n) _Pragma("unroll") for (int k = 0; k < 2; ++k) dst[n][k] = *(const LAS bf16x8*)(lds + PG8_SB(b, h) + boff + n * 2048 + k * 1024); } while (0)
; #define PG8_MMA(ai, bj, At, Bt) do { __builtin_amdgcn_s_setprio(1); _Pragma("unroll") for (int m = 0; m < 4; ++m) _Pragma("unroll") for (int n = 0; n < 2; ++n) _Pragma("unroll") for (int k = 0; k < 2; ++k) \
;         acc[ai][bj][m][n] = __builtin_amdgcn_mfma_f32_16x16x32_bf16(Bt[n][k], At[m][k], acc[ai][bj][m][n], 0, 0, 0); __builtin_amdgcn_s_setprio(0); } while (0)
; #define PG8_WAIT_V(n) asm volatile("s_waitcnt vmcnt(" #n ")" ::: "memory")
; #define PG8_WAIT_L(n) asm volatile("s_waitcnt lgkmcnt(" #n ")" ::: "memory")
; #define PG8_BAR __builtin_amdgcn_s_barrier()
; #define PG8_SCHED __builtin_amdgcn_sched_barrier(0)
; template <class Epi, class Order = StaticOrder, bool HALFN = false>
; __device__ __forceinline__ void gemm_phase(LAS unsigned char* lds, const Gemm g, const Epi& E) {
;     ...
;             PG8_WAIT_V(8); PG8_WAIT_L(0); PG8_BAR; PG8_MMA(1, 0, At, B0); if constexpr (!HALFN) PG8_MMA(1, 1, At, B1); PG8_BAR; PG8_SCHED;
;             PG8_LDB(B0, 1, 0); if constexpr (!HALFN) PG8_LDB(B1, 1, 1); PG8_SCHED; PG8_LDA(At, 1, 0); PG8_STAGE(PG8_SA(0, 1), a2 + hstepA, voffA);
;             PG8_WAIT_V(8); PG8_WAIT_L(0); PG8_BAR; PG8_MMA(0, 0, At, B0); if constexpr (!HALFN) PG8_MMA(0, 1, At, B1); PG8_BAR; PG8_SCHED;
;             PG8_LDA(At, 1, 1); PG8_STAGE(PG8_SB(1, 0), b3, voffB); PG8_STAGE(PG8_SB(1, 1), b3 + hstepB, voffB); PG8_STAGE(PG8_SA(1, 0), a3, voffA);
;             PG8_WAIT_V(8); PG8_WAIT_L(0); PG8_BAR; PG8_MMA(1, 0, At, B0); if constexpr (!HALFN) PG8_MMA(1, 1, At, B1); PG8_BAR; PG8_SCHED;
	v_mfma_f32_16x16x32_bf16 v[62:65], v[118:121], v[176:179], v[62:65]
	v_mfma_f32_16x16x32_bf16 v[58:61], v[138:141], v[176:179], v[58:61]
	v_mfma_f32_16x16x32_bf16 v[46:49], v[118:121], v[208:211], v[46:49]
	v_mfma_f32_16x16x32_bf16 v[42:45], v[138:141], v[208:211], v[42:45]
	v_mfma_f32_16x16x32_bf16 v[30:33], v[118:121], v[216:219], v[30:33]
	v_mfma_f32_16x16x32_bf16 v[26:29], v[138:141], v[216:219], v[26:29]
	v_mfma_f32_16x16x32_bf16 v[14:17], v[118:121], v[224:227], v[14:17]
	v_mfma_f32_16x16x32_bf16 v[10:13], v[138:141], v[224:227], v[10:13]
	v_mfma_f32_16x16x32_bf16 v[62:65], v[126:129], v[184:187], v[62:65]
	v_mfma_f32_16x16x32_bf16 v[58:61], v[142:145], v[184:187], v[58:61]
	v_mfma_f32_16x16x32_bf16 v[46:49], v[126:129], v[212:215], v[46:49]
	v_mfma_f32_16x16x32_bf16 v[42:45], v[142:145], v[212:215], v[42:45]
	v_mfma_f32_16x16x32_bf16 v[30:33], v[126:129], v[220:223], v[30:33]
	v_mfma_f32_16x16x32_bf16 v[26:29], v[142:145], v[220:223], v[26:29]
	v_mfma_f32_16x16x32_bf16 v[14:17], v[126:129], v[228:231], v[14:17]
	v_mfma_f32_16x16x32_bf16 v[10:13], v[142:145], v[228:231], v[10:13]
	v_mfma_f32_16x16x32_bf16 v[54:57], v[146:149], v[176:179], v[54:57]
	v_mfma_f32_16x16x32_bf16 v[50:53], v[154:157], v[176:179], v[50:53]
	v_mfma_f32_16x16x32_bf16 v[38:41], v[146:149], v[208:211], v[38:41]
	v_mfma_f32_16x16x32_bf16 v[34:37], v[154:157], v[208:211], v[34:37]
	v_mfma_f32_16x16x32_bf16 v[22:25], v[146:149], v[216:219], v[22:25]
	v_mfma_f32_16x16x32_bf16 v[18:21], v[154:157], v[216:219], v[18:21]
	v_mfma_f32_16x16x32_bf16 v[6:9], v[146:149], v[224:227], v[6:9]
	v_mfma_f32_16x16x32_bf16 v[2:5], v[154:157], v[224:227], v[2:5]
	v_mfma_f32_16x16x32_bf16 v[54:57], v[150:153], v[184:187], v[54:57]
	v_mfma_f32_16x16x32_bf16 v[50:53], v[172:175], v[184:187], v[50:53]
	v_mfma_f32_16x16x32_bf16 v[38:41], v[150:153], v[212:215], v[38:41]
	v_mfma_f32_16x16x32_bf16 v[34:37], v[172:175], v[212:215], v[34:37]
	v_mfma_f32_16x16x32_bf16 v[22:25], v[150:153], v[220:223], v[22:25]
	v_mfma_f32_16x16x32_bf16 v[18:21], v[172:175], v[220:223], v[18:21]
	v_mfma_f32_16x16x32_bf16 v[6:9], v[150:153], v[228:231], v[6:9]
	v_mfma_f32_16x16x32_bf16 v[2:5], v[172:175], v[228:231], v[2:5]
	s_barrier
	s_setprio 0
	v_add_u32_e32 v142, s31, v181
	v_add_u32_e32 v172, s30, v181
	ds_read_b128 v[118:121], v142
	ds_read_b128 v[126:129], v142 offset:1024
	ds_read_b128 v[138:141], v142 offset:2048
	ds_read_b128 v[142:145], v142 offset:3072
	ds_read_b128 v[146:149], v172
	ds_read_b128 v[150:153], v172 offset:1024
	ds_read_b128 v[154:157], v172 offset:2048
	ds_read_b128 v[172:175], v172 offset:3072
	s_mov_b32 m0, s78
	v_lshl_add_u64 v[240:241], s[42:43], 0, v[158:159]
	ds_read_b128 v[176:179], v182 offset:32768
	ds_read_b128 v[184:187], v182 offset:33792
	ds_read_b128 v[208:211], v182 offset:34816
	ds_read_b128 v[212:215], v182 offset:35840
	ds_read_b128 v[216:219], v182 offset:36864
	ds_read_b128 v[220:223], v182 offset:37888
	ds_read_b128 v[224:227], v182 offset:38912
	ds_read_b128 v[228:231], v182 offset:39936
	global_load_lds_dwordx4 v[240:241], off
	v_lshl_add_u64 v[240:241], s[42:43], 0, v[168:169]
	s_mov_b32 m0, s79
	s_nop 0
	global_load_lds_dwordx4 v[240:241], off
	s_waitcnt vmcnt(8)
	s_waitcnt lgkmcnt(0)
	s_setprio 1
	s_barrier
	v_mfma_f32_16x16x32_bf16 v[134:137], v[118:121], v[176:179], v[134:137]
	v_mfma_f32_16x16x32_bf16 v[130:133], v[138:141], v[176:179], v[130:133]
	v_mfma_f32_16x16x32_bf16 v[110:113], v[118:121], v[208:211], v[110:113]
	v_mfma_f32_16x16x32_bf16 v[106:109], v[138:141], v[208:211], v[106:109]
	v_mfma_f32_16x16x32_bf16 v[94:97], v[118:121], v[216:219], v[94:97]
	v_mfma_f32_16x16x32_bf16 v[90:93], v[138:141], v[216:219], v[90:93]
	v_mfma_f32_16x16x32_bf16 v[78:81], v[118:121], v[224:227], v[78:81]
	v_mfma_f32_16x16x32_bf16 v[74:77], v[138:141], v[224:227], v[74:77]
	v_mfma_f32_16x16x32_bf16 v[134:137], v[126:129], v[184:187], v[134:137]
	v_mfma_f32_16x16x32_bf16 v[130:133], v[142:145], v[184:187], v[130:133]
	v_mfma_f32_16x16x32_bf16 v[110:113], v[126:129], v[212:215], v[110:113]
	v_mfma_f32_16x16x32_bf16 v[106:109], v[142:145], v[212:215], v[106:109]
	v_mfma_f32_16x16x32_bf16 v[94:97], v[126:129], v[220:223], v[94:97]
	v_mfma_f32_16x16x32_bf16 v[90:93], v[142:145], v[220:223], v[90:93]
	v_mfma_f32_16x16x32_bf16 v[78:81], v[126:129], v[228:231], v[78:81]
	v_mfma_f32_16x16x32_bf16 v[74:77], v[142:145], v[228:231], v[74:77]
	v_mfma_f32_16x16x32_bf16 v[122:125], v[146:149], v[176:179], v[122:125]
	v_mfma_f32_16x16x32_bf16 v[114:117], v[154:157], v[176:179], v[114:117]
	v_mfma_f32_16x16x32_bf16 v[102:105], v[146:149], v[208:211], v[102:105]
	v_mfma_f32_16x16x32_bf16 v[98:101], v[154:157], v[208:211], v[98:101]
	v_mfma_f32_16x16x32_bf16 v[86:89], v[146:149], v[216:219], v[86:89]
	v_mfma_f32_16x16x32_bf16 v[82:85], v[154:157], v[216:219], v[82:85]
	v_mfma_f32_16x16x32_bf16 v[70:73], v[146:149], v[224:227], v[70:73]
	v_mfma_f32_16x16x32_bf16 v[66:69], v[154:157], v[224:227], v[66:69]
	v_mfma_f32_16x16x32_bf16 v[122:125], v[150:153], v[184:187], v[122:125]
	v_mfma_f32_16x16x32_bf16 v[114:117], v[172:175], v[184:187], v[114:117]
	v_mfma_f32_16x16x32_bf16 v[102:105], v[150:153], v[212:215], v[102:105]
	v_mfma_f32_16x16x32_bf16 v[98:101], v[172:175], v[212:215], v[98:101]
	v_mfma_f32_16x16x32_bf16 v[86:89], v[150:153], v[220:223], v[86:89]
	v_mfma_f32_16x16x32_bf16 v[82:85], v[172:175], v[220:223], v[82:85]
	v_mfma_f32_16x16x32_bf16 v[70:73], v[150:153], v[228:231], v[70:73]
	v_mfma_f32_16x16x32_bf16 v[66:69], v[172:175], v[228:231], v[66:69]
	s_barrier
; #define PG8_STAGE(bufoff, gbase, voff) do { _Pragma("unroll") for (int _i = 0; _i < 2; ++_i) \
;         __builtin_amdgcn_global_load_lds((const unsigned*)((const char*)(gbase) + (voff)[_i]), (LAS unsigned*)(lds + (bufoff) + ldsw + _i * 8192), 16, 0, 0); } while (0)
; #define PG8_LDA(dst, b, h) do { _Pragma("unroll") for (int m = 0; m < 4; ++m) _Pragma("unroll") for (int k = 0; k < 2; ++k) dst[m][k] = *(const LAS bf16x8*)(lds + PG8_SA(b, h) + aoff + m * 2048 + k * 1024); } while (0)
; #define PG8_MMA(ai, bj, At, Bt) do { __builtin_amdgcn_s_setprio(1); _Pragma("unroll") for (int m = 0; m < 4; ++m) _Pragma("unroll") for (int n = 0; n < 2; ++n) _Pragma("unroll") for (int k = 0; k < 2; ++k) \
;         acc[ai][bj][m][n] = __builtin_amdgcn_mfma_f32_16x16x32_bf16(Bt[n][k], At[m][k], acc[ai][bj][m][n], 0, 0, 0); __builtin_amdgcn_s_setprio(0); } while (0)
; #define PG8_WAIT_V(n) asm volatile("s_waitcnt vmcnt(" #n ")" ::: "memory")
; #define PG8_WAIT_L(n) asm volatile("s_waitcnt lgkmcnt(" #n ")" ::: "memory")
; #define PG8_BAR __builtin_amdgcn_s_barrier()
; #define PG8_SCHED __builtin_amdgcn_sched_barrier(0)
; template <class Epi, class Order = StaticOrder, bool HALFN = false>
; __device__ __forceinline__ void gemm_phase(LAS unsigned char* lds, const Gemm g, const Epi& E) {
;     ...
;             PG8_LDA(At, 1, 1); PG8_STAGE(PG8_SB(1, 0), b3, voffB); PG8_STAGE(PG8_SB(1, 1), b3 + hstepB, voffB); PG8_STAGE(PG8_SA(1, 0), a3, voffA);
;             PG8_WAIT_V(8); PG8_WAIT_L(0); PG8_BAR; PG8_MMA(1, 0, At, B0); if constexpr (!HALFN) PG8_MMA(1, 1, At, B1); PG8_BAR; PG8_SCHED;
;         }
;         if (wr == 0) PG8_BAR;
	s_setprio 0
	s_mov_b32 m0, s29
	v_lshl_add_u64 v[232:233], v[232:233], 0, s[60:61]
	ds_read_b128 v[176:179], v182 offset:49152
	ds_read_b128 v[184:187], v182 offset:50176
	ds_read_b128 v[208:211], v182 offset:51200
	ds_read_b128 v[212:215], v182 offset:52224
	ds_read_b128 v[216:219], v182 offset:53248
	ds_read_b128 v[220:223], v182 offset:54272
	ds_read_b128 v[224:227], v182 offset:55296
	ds_read_b128 v[228:231], v182 offset:56320
	global_load_lds_dwordx4 v[232:233], off
	v_lshl_add_u64 v[232:233], v[234:235], 0, s[60:61]
	s_mov_b32 m0, s28
	s_nop 0
	global_load_lds_dwordx4 v[232:233], off
	v_lshl_add_u64 v[232:233], s[4:5], 0, v[160:161]
	s_mov_b32 m0, s93
	s_nop 0
	global_load_lds_dwordx4 v[232:233], off
	v_lshl_add_u64 v[232:233], s[4:5], 0, v[170:171]
	s_mov_b32 m0, s83
	s_nop 0
	global_load_lds_dwordx4 v[232:233], off
	v_lshl_add_u64 v[232:233], v[236:237], 0, s[60:61]
	s_mov_b32 m0, s24
	s_nop 0
	global_load_lds_dwordx4 v[232:233], off
	v_lshl_add_u64 v[232:233], v[238:239], 0, s[60:61]
	s_mov_b32 m0, s25
	s_nop 0
	global_load_lds_dwordx4 v[232:233], off
	s_waitcnt vmcnt(8)
	s_waitcnt lgkmcnt(0)
	s_setprio 1
	s_barrier
	v_mfma_f32_16x16x32_bf16 v[62:65], v[118:121], v[176:179], v[62:65]
	v_mfma_f32_16x16x32_bf16 v[58:61], v[138:141], v[176:179], v[58:61]
	v_mfma_f32_16x16x32_bf16 v[46:49], v[118:121], v[208:211], v[46:49]
	v_mfma_f32_16x16x32_bf16 v[42:45], v[138:141], v[208:211], v[42:45]
	v_mfma_f32_16x16x32_bf16 v[30:33], v[118:121], v[216:219], v[30:33]
	v_mfma_f32_16x16x32_bf16 v[26:29], v[138:141], v[216:219], v[26:29]
	v_mfma_f32_16x16x32_bf16 v[14:17], v[118:121], v[224:227], v[14:17]
	v_mfma_f32_16x16x32_bf16 v[10:13], v[138:141], v[224:227], v[10:13]
	v_mfma_f32_16x16x32_bf16 v[62:65], v[126:129], v[184:187], v[62:65]
	v_mfma_f32_16x16x32_bf16 v[58:61], v[142:145], v[184:187], v[58:61]
	v_mfma_f32_16x16x32_bf16 v[46:49], v[126:129], v[212:215], v[46:49]
	v_mfma_f32_16x16x32_bf16 v[42:45], v[142:145], v[212:215], v[42:45]
	v_mfma_f32_16x16x32_bf16 v[30:33], v[126:129], v[220:223], v[30:33]
	v_mfma_f32_16x16x32_bf16 v[26:29], v[142:145], v[220:223], v[26:29]
	v_mfma_f32_16x16x32_bf16 v[14:17], v[126:129], v[228:231], v[14:17]
	v_mfma_f32_16x16x32_bf16 v[10:13], v[142:145], v[228:231], v[10:13]
	v_mfma_f32_16x16x32_bf16 v[54:57], v[146:149], v[176:179], v[54:57]
	v_mfma_f32_16x16x32_bf16 v[50:53], v[154:157], v[176:179], v[50:53]
	v_mfma_f32_16x16x32_bf16 v[38:41], v[146:149], v[208:211], v[38:41]
	v_mfma_f32_16x16x32_bf16 v[34:37], v[154:157], v[208:211], v[34:37]
	v_mfma_f32_16x16x32_bf16 v[22:25], v[146:149], v[216:219], v[22:25]
	v_mfma_f32_16x16x32_bf16 v[18:21], v[154:157], v[216:219], v[18:21]
	v_mfma_f32_16x16x32_bf16 v[6:9], v[146:149], v[224:227], v[6:9]
	v_mfma_f32_16x16x32_bf16 v[2:5], v[154:157], v[224:227], v[2:5]
	v_mfma_f32_16x16x32_bf16 v[54:57], v[150:153], v[184:187], v[54:57]
	v_mfma_f32_16x16x32_bf16 v[50:53], v[172:175], v[184:187], v[50:53]
	v_mfma_f32_16x16x32_bf16 v[38:41], v[150:153], v[212:215], v[38:41]
	v_mfma_f32_16x16x32_bf16 v[34:37], v[172:175], v[212:215], v[34:37]
	v_mfma_f32_16x16x32_bf16 v[22:25], v[150:153], v[220:223], v[22:25]
	v_mfma_f32_16x16x32_bf16 v[18:21], v[172:175], v[220:223], v[18:21]
	v_mfma_f32_16x16x32_bf16 v[6:9], v[150:153], v[228:231], v[6:9]
	v_mfma_f32_16x16x32_bf16 v[2:5], v[172:175], v[228:231], v[2:5]
	s_barrier
	s_setprio 0
	s_andn2_b64 vcc, exec, s[62:63]
	s_mov_b64 s[42:43], -1
	s_mov_b64 s[62:63], 0
	s_mov_b64 s[4:5], 0x100
	s_cbranch_vccz .LBB0_489
	s_and_b64 vcc, exec, s[46:47]
	s_cbranch_vccz .LBB0_492
	s_barrier

; #define PG8_STAGE(bufoff, gbase, voff) do { _Pragma("unroll") for (int _i = 0; _i < 2; ++_i) \
;         __builtin_amdgcn_global_load_lds((const unsigned*)((const char*)(gbase) + (voff)[_i]), (LAS unsigned*)(lds + (bufoff) + ldsw + _i * 8192), 16, 0, 0); } while (0)
; #define PG8_LDA(dst, b, h) do { _Pragma("unroll") for (int m = 0; m < 4; ++m) _Pragma("unroll") for (int k = 0; k < 2; ++k) dst[m][k] = *(const LAS bf16x8*)(lds + PG8_SA(b, h) + aoff + m * 2048 + k * 1024); } while (0)
; #define PG8_LDB(dst, b, h) do { _Pragma("unroll") for (int n = 0; n < 2; ++n) _Pragma("unroll") for (int k = 0; k < 2; ++k) dst[n][k] = *(const LAS bf16x8*)(lds + PG8_SB(b, h) + boff + n * 2048 + k * 1024); } while (0)
; #define PG8_MMA(ai, bj, At, Bt) do { __builtin_amdgcn_s_setprio(1); _Pragma("unroll") for (int m = 0; m < 4; ++m) _Pragma("unroll") for (int n = 0; n < 2; ++n) _Pragma("unroll") for (int k = 0; k < 2; ++k) \
;         acc[ai][bj][m][n] = __builtin_amdgcn_mfma_f32_16x16x32_bf16(Bt[n][k], At[m][k], acc[ai][bj][m][n], 0, 0, 0); __builtin_amdgcn_s_setprio(0); } while (0)
; #define PG8_WAIT_V(n) asm volatile("s_waitcnt vmcnt(" #n ")" ::: "memory")
; template <class Epi, class Order = StaticOrder, bool HALFN = false>
; __device__ __forceinline__ void gemm_phase(LAS unsigned char* lds, const Gemm g, const Epi& E) {
;     ...
;             const bool last = (t == nt - 2);
;             if constexpr (Epi::SEAMS) { if (t == Epi::SEAM0 || t == Epi::SEAM1) E.seam(acc, cur, t == Epi::SEAM0 ? 0 : 1, wr, wc, fr, fq); }
;             const char* a1 = cA + (size_t)(t + 1) * kstep;
;             const char* a2 = last ? nA : cA + (size_t)(t + 2) * kstep; const char* b2 = last ? nB : cB + (size_t)(t + 2) * kstep;
;             const char* a3 = a2 + kstep; const char* b3 = b2 + kstep;
;             PG8_LDB(B0, 0, 0); if constexpr (!HALFN) PG8_LDB(B1, 0, 1); PG8_SCHED; PG8_LDA(At, 0, 0); PG8_STAGE(PG8_SA(1, 1), a1 + hstepA, voffA);
;             PG8_WAIT_V(8); PG8_WAIT_L(0); PG8_BAR; PG8_MMA(0, 0, At, B0); if constexpr (!HALFN) PG8_MMA(0, 1, At, B1); PG8_BAR; PG8_SCHED;
;             PG8_LDA(At, 0, 1); PG8_STAGE(PG8_SB(0, 0), b2, voffB); PG8_STAGE(PG8_SB(0, 1), b2 + hstepB, voffB); PG8_STAGE(PG8_SA(0, 0), a2, voffA);
;             PG8_WAIT_V(8); PG8_WAIT_L(0); PG8_BAR; PG8_MMA(1, 0, At, B0); if constexpr (!HALFN) PG8_MMA(1, 1, At, B1); PG8_BAR; PG8_SCHED;
.LBB0_521:
	s_add_u32 s8, s74, s4
	s_addc_u32 s9, s75, s5
	s_add_u32 s10, s8, 0x100
	s_addc_u32 s11, s9, 0
	s_and_b64 s[6:7], s[42:43], exec
	s_cselect_b32 s7, s27, s11
	s_cselect_b32 s6, s53, s10
	s_add_u32 s4, s54, s4
	s_addc_u32 s5, s55, s5
	s_add_u32 s10, s4, 0x100
	s_addc_u32 s11, s5, 0
	s_add_i32 s88, 0, 0x10000
	s_and_b64 s[4:5], s[42:43], exec
	s_cselect_b32 s95, s51, s11
	s_cselect_b32 s94, s28, s10
	s_add_i32 s5, 0, 0x14000
	s_add_u32 s10, s8, 0x10080
	s_addc_u32 s11, s9, 0
	s_add_i32 vcc_lo, s88, s19
	s_add_i32 m0, s59, 0xc000
	s_add_i32 s20, s59, 0xe000
	s_add_i32 s35, vcc_lo, 0x2000
	v_add_u32_e32 v141, s88, v139
	s_add_u32 s8, s94, 0x10000
	ds_read_b128 v[142:145], v141
	ds_read_b128 v[146:149], v141 offset:1024
	ds_read_b128 v[150:153], v141 offset:2048
	ds_read_b128 v[154:157], v141 offset:3072
	v_add_u32_e32 v141, s5, v139
	s_addc_u32 s9, s95, 0
	s_add_i32 s37, s5, s19
	ds_read_b128 v[158:161], v141
	ds_read_b128 v[168:171], v141 offset:1024
	ds_read_b128 v[172:175], v141 offset:2048
	ds_read_b128 v[176:179], v141 offset:3072
	s_add_i32 s36, s37, 0x2000
	s_add_i32 s34, 0, 0x18000
	s_add_i32 s31, 0, 0x1c000
	s_add_u32 s42, s6, 0x10000
	s_addc_u32 s43, s7, 0
	s_add_i32 s30, s34, s19
	s_add_i32 s29, s30, 0x2000
	s_add_u32 s4, s94, 0x10080
	s_addc_u32 s5, s95, 0
	s_add_i32 vcc_hi, s31, s19
	s_add_i32 s88, vcc_hi, 0x2000
	v_lshl_add_u64 v[232:233], s[10:11], 0, v[130:131]
	ds_read_b128 v[180:183], v140
	ds_read_b128 v[184:187], v140 offset:1024
	ds_read_b128 v[208:211], v140 offset:2048
	ds_read_b128 v[212:215], v140 offset:3072
	ds_read_b128 v[216:219], v140 offset:4096
	ds_read_b128 v[220:223], v140 offset:5120
	ds_read_b128 v[224:227], v140 offset:6144
	ds_read_b128 v[228:231], v140 offset:7168
	global_load_lds_dwordx4 v[232:233], off
	v_lshl_add_u64 v[232:233], s[10:11], 0, v[134:135]
	s_mov_b32 m0, s20
	s_nop 0
	global_load_lds_dwordx4 v[232:233], off
	s_waitcnt vmcnt(8)
	s_waitcnt lgkmcnt(0)
	s_setprio 1
	s_barrier
	v_mfma_f32_16x16x32_bf16 v[126:129], v[142:145], v[180:183], v[126:129]
	v_mfma_f32_16x16x32_bf16 v[122:125], v[150:153], v[180:183], v[122:125]
	v_mfma_f32_16x16x32_bf16 v[118:121], v[142:145], v[208:211], v[118:121]
	v_mfma_f32_16x16x32_bf16 v[114:117], v[150:153], v[208:211], v[114:117]
	v_mfma_f32_16x16x32_bf16 v[102:105], v[142:145], v[216:219], v[102:105]
	v_mfma_f32_16x16x32_bf16 v[98:101], v[150:153], v[216:219], v[98:101]
	v_mfma_f32_16x16x32_bf16 v[86:89], v[142:145], v[224:227], v[86:89]
	v_mfma_f32_16x16x32_bf16 v[82:85], v[150:153], v[224:227], v[82:85]
	v_mfma_f32_16x16x32_bf16 v[126:129], v[146:149], v[184:187], v[126:129]
	v_mfma_f32_16x16x32_bf16 v[122:125], v[154:157], v[184:187], v[122:125]
	v_mfma_f32_16x16x32_bf16 v[118:121], v[146:149], v[212:215], v[118:121]
	v_mfma_f32_16x16x32_bf16 v[114:117], v[154:157], v[212:215], v[114:117]
	v_mfma_f32_16x16x32_bf16 v[102:105], v[146:149], v[220:223], v[102:105]
	v_mfma_f32_16x16x32_bf16 v[98:101], v[154:157], v[220:223], v[98:101]
	v_mfma_f32_16x16x32_bf16 v[86:89], v[146:149], v[228:231], v[86:89]
	v_mfma_f32_16x16x32_bf16 v[82:85], v[154:157], v[228:231], v[82:85]
	v_mfma_f32_16x16x32_bf16 v[110:113], v[158:161], v[180:183], v[110:113]
	v_mfma_f32_16x16x32_bf16 v[106:109], v[172:175], v[180:183], v[106:109]
	v_mfma_f32_16x16x32_bf16 v[94:97], v[158:161], v[208:211], v[94:97]
	v_mfma_f32_16x16x32_bf16 v[90:93], v[172:175], v[208:211], v[90:93]
	v_mfma_f32_16x16x32_bf16 v[78:81], v[158:161], v[216:219], v[78:81]
	v_mfma_f32_16x16x32_bf16 v[74:77], v[172:175], v[216:219], v[74:77]
	v_mfma_f32_16x16x32_bf16 v[70:73], v[158:161], v[224:227], v[70:73]
	v_mfma_f32_16x16x32_bf16 v[66:69], v[172:175], v[224:227], v[66:69]
	v_mfma_f32_16x16x32_bf16 v[110:113], v[168:171], v[184:187], v[110:113]
	v_mfma_f32_16x16x32_bf16 v[106:109], v[176:179], v[184:187], v[106:109]
	v_mfma_f32_16x16x32_bf16 v[94:97], v[168:171], v[212:215], v[94:97]
	v_mfma_f32_16x16x32_bf16 v[90:93], v[176:179], v[212:215], v[90:93]
	v_mfma_f32_16x16x32_bf16 v[78:81], v[168:171], v[220:223], v[78:81]
	v_mfma_f32_16x16x32_bf16 v[74:77], v[176:179], v[220:223], v[74:77]
	v_mfma_f32_16x16x32_bf16 v[70:73], v[168:171], v[228:231], v[70:73]
	v_mfma_f32_16x16x32_bf16 v[66:69], v[176:179], v[228:231], v[66:69]
	s_barrier
	s_setprio 0
	s_mov_b32 m0, vcc_lo
	v_lshl_add_u64 v[232:233], s[94:95], 0, v[132:133]
	ds_read_b128 v[180:183], v140 offset:16384
	ds_read_b128 v[184:187], v140 offset:17408
	ds_read_b128 v[208:211], v140 offset:18432
	ds_read_b128 v[212:215], v140 offset:19456
	ds_read_b128 v[216:219], v140 offset:20480
	ds_read_b128 v[220:223], v140 offset:21504
	ds_read_b128 v[224:227], v140 offset:22528
	ds_read_b128 v[228:231], v140 offset:23552
	global_load_lds_dwordx4 v[232:233], off
	v_lshl_add_u64 v[234:235], s[94:95], 0, v[136:137]
	s_mov_b32 m0, s35
	v_lshl_add_u64 v[236:237], s[8:9], 0, v[132:133]
	global_load_lds_dwordx4 v[234:235], off
	s_mov_b32 m0, s37
	v_lshl_add_u64 v[238:239], s[6:7], 0, v[134:135]
	global_load_lds_dwordx4 v[236:237], off
	v_lshl_add_u64 v[236:237], s[8:9], 0, v[136:137]
	s_mov_b32 m0, s36
	s_nop 0
	global_load_lds_dwordx4 v[236:237], off
	v_lshl_add_u64 v[236:237], s[6:7], 0, v[130:131]
	s_mov_b32 m0, s59
	s_nop 0
	global_load_lds_dwordx4 v[236:237], off
	s_mov_b32 m0, s21
	s_nop 0
	global_load_lds_dwordx4 v[238:239], off
	s_waitcnt vmcnt(8)
	s_waitcnt lgkmcnt(0)
	s_setprio 1
	s_barrier
; #define PG8_STAGE(bufoff, gbase, voff) do { _Pragma("unroll") for (int _i = 0; _i < 2; ++_i) \
;         __builtin_amdgcn_global_load_lds((const unsigned*)((const char*)(gbase) + (voff)[_i]), (LAS unsigned*)(lds + (bufoff) + ldsw + _i * 8192), 16, 0, 0); } while (0)
; #define PG8_LDA(dst, b, h) do { _Pragma("unroll") for (int m = 0; m < 4; ++m) _Pragma("unroll") for (int k = 0; k < 2; ++k) dst[m][k] = *(const LAS bf16x8*)(lds + PG8_SA(b, h) + aoff + m * 2048 + k * 1024); } while (0)
; #define PG8_LDB(dst, b, h) do { _Pragma("unroll") for (int n = 0; n < 2; ++n) _Pragma("unroll") for (int k = 0; k < 2; ++k) dst[n][k] = *(const LAS bf16x8*)(lds + PG8_SB(b, h) + boff + n * 2048 + k * 1024); } while (0)
; #define PG8_MMA(ai, bj, At, Bt) do { __builtin_amdgcn_s_setprio(1); _Pragma("unroll") for (int m = 0; m < 4; ++m) _Pragma("unroll") for (int n = 0; n < 2; ++n) _Pragma("unroll") for (int k = 0; k < 2; ++k) \
;         acc[ai][bj][m][n] = __builtin_amdgcn_mfma_f32_16x16x32_bf16(Bt[n][k], At[m][k], acc[ai][bj][m][n], 0, 0, 0); __builtin_amdgcn_s_setprio(0); } while (0)
; #define PG8_WAIT_V(n) asm volatile("s_waitcnt vmcnt(" #n ")" ::: "memory")
; #define PG8_WAIT_L(n) asm volatile("s_waitcnt lgkmcnt(" #n ")" ::: "memory")
; #define PG8_BAR __builtin_amdgcn_s_barrier()
; #define PG8_SCHED __builtin_amdgcn_sched_barrier(0)
; template <class Epi, class Order = StaticOrder, bool HALFN = false>
; __device__ __forceinline__ void gemm_phase(LAS unsigned char* lds, const Gemm g, const Epi& E) {
;     ...
;             PG8_WAIT_V(8); PG8_WAIT_L(0); PG8_BAR; PG8_MMA(1, 0, At, B0); if constexpr (!HALFN) PG8_MMA(1, 1, At, B1); PG8_BAR; PG8_SCHED;
;             PG8_LDB(B0, 1, 0); if constexpr (!HALFN) PG8_LDB(B1, 1, 1); PG8_SCHED; PG8_LDA(At, 1, 0); PG8_STAGE(PG8_SA(0, 1), a2 + hstepA, voffA);
;             PG8_WAIT_V(8); PG8_WAIT_L(0); PG8_BAR; PG8_MMA(0, 0, At, B0); if constexpr (!HALFN) PG8_MMA(0, 1, At, B1); PG8_BAR; PG8_SCHED;
;             PG8_LDA(At, 1, 1); PG8_STAGE(PG8_SB(1, 0), b3, voffB); PG8_STAGE(PG8_SB(1, 1), b3 + hstepB, voffB); PG8_STAGE(PG8_SA(1, 0), a3, voffA);
;             PG8_WAIT_V(8); PG8_WAIT_L(0); PG8_BAR; PG8_MMA(1, 0, At, B0); if constexpr (!HALFN) PG8_MMA(1, 1, At, B1); PG8_BAR; PG8_SCHED;
	v_mfma_f32_16x16x32_bf16 v[62:65], v[142:145], v[180:183], v[62:65]
	v_mfma_f32_16x16x32_bf16 v[58:61], v[150:153], v[180:183], v[58:61]
	v_mfma_f32_16x16x32_bf16 v[54:57], v[142:145], v[208:211], v[54:57]
	v_mfma_f32_16x16x32_bf16 v[50:53], v[150:153], v[208:211], v[50:53]
	v_mfma_f32_16x16x32_bf16 v[38:41], v[142:145], v[216:219], v[38:41]
	v_mfma_f32_16x16x32_bf16 v[34:37], v[150:153], v[216:219], v[34:37]
	v_mfma_f32_16x16x32_bf16 v[22:25], v[142:145], v[224:227], v[22:25]
	v_mfma_f32_16x16x32_bf16 v[18:21], v[150:153], v[224:227], v[18:21]
	v_mfma_f32_16x16x32_bf16 v[62:65], v[146:149], v[184:187], v[62:65]
	v_mfma_f32_16x16x32_bf16 v[58:61], v[154:157], v[184:187], v[58:61]
	v_mfma_f32_16x16x32_bf16 v[54:57], v[146:149], v[212:215], v[54:57]
	v_mfma_f32_16x16x32_bf16 v[50:53], v[154:157], v[212:215], v[50:53]
	v_mfma_f32_16x16x32_bf16 v[38:41], v[146:149], v[220:223], v[38:41]
	v_mfma_f32_16x16x32_bf16 v[34:37], v[154:157], v[220:223], v[34:37]
	v_mfma_f32_16x16x32_bf16 v[22:25], v[146:149], v[228:231], v[22:25]
	v_mfma_f32_16x16x32_bf16 v[18:21], v[154:157], v[228:231], v[18:21]
	v_mfma_f32_16x16x32_bf16 v[46:49], v[158:161], v[180:183], v[46:49]
	v_mfma_f32_16x16x32_bf16 v[42:45], v[172:175], v[180:183], v[42:45]
	v_mfma_f32_16x16x32_bf16 v[30:33], v[158:161], v[208:211], v[30:33]
	v_mfma_f32_16x16x32_bf16 v[26:29], v[172:175], v[208:211], v[26:29]
	v_mfma_f32_16x16x32_bf16 v[14:17], v[158:161], v[216:219], v[14:17]
	v_mfma_f32_16x16x32_bf16 v[10:13], v[172:175], v[216:219], v[10:13]
	v_mfma_f32_16x16x32_bf16 v[6:9], v[158:161], v[224:227], v[6:9]
	v_mfma_f32_16x16x32_bf16 v[2:5], v[172:175], v[224:227], v[2:5]
	v_mfma_f32_16x16x32_bf16 v[46:49], v[168:171], v[184:187], v[46:49]
	v_mfma_f32_16x16x32_bf16 v[42:45], v[176:179], v[184:187], v[42:45]
	v_mfma_f32_16x16x32_bf16 v[30:33], v[168:171], v[212:215], v[30:33]
	v_mfma_f32_16x16x32_bf16 v[26:29], v[176:179], v[212:215], v[26:29]
	v_mfma_f32_16x16x32_bf16 v[14:17], v[168:171], v[220:223], v[14:17]
	v_mfma_f32_16x16x32_bf16 v[10:13], v[176:179], v[220:223], v[10:13]
	v_mfma_f32_16x16x32_bf16 v[6:9], v[168:171], v[228:231], v[6:9]
	v_mfma_f32_16x16x32_bf16 v[2:5], v[176:179], v[228:231], v[2:5]
	s_barrier
	s_setprio 0
	v_add_u32_e32 v141, s34, v139
	ds_read_b128 v[142:145], v141
	ds_read_b128 v[146:149], v141 offset:1024
	ds_read_b128 v[150:153], v141 offset:2048
	ds_read_b128 v[154:157], v141 offset:3072
	v_add_u32_e32 v141, s31, v139
	ds_read_b128 v[158:161], v141
	ds_read_b128 v[168:171], v141 offset:1024
	ds_read_b128 v[172:175], v141 offset:2048
	ds_read_b128 v[176:179], v141 offset:3072
	s_mov_b32 m0, s22
	v_lshl_add_u64 v[240:241], s[42:43], 0, v[130:131]
	ds_read_b128 v[180:183], v140 offset:32768
	ds_read_b128 v[184:187], v140 offset:33792
	ds_read_b128 v[208:211], v140 offset:34816
	ds_read_b128 v[212:215], v140 offset:35840
	ds_read_b128 v[216:219], v140 offset:36864
	ds_read_b128 v[220:223], v140 offset:37888
	ds_read_b128 v[224:227], v140 offset:38912
	ds_read_b128 v[228:231], v140 offset:39936
	global_load_lds_dwordx4 v[240:241], off
	v_lshl_add_u64 v[240:241], s[42:43], 0, v[134:135]
	s_mov_b32 m0, s23
	s_nop 0
	global_load_lds_dwordx4 v[240:241], off
	s_waitcnt vmcnt(8)
	s_waitcnt lgkmcnt(0)
	s_setprio 1
	s_barrier
	v_mfma_f32_16x16x32_bf16 v[126:129], v[142:145], v[180:183], v[126:129]
	v_mfma_f32_16x16x32_bf16 v[122:125], v[150:153], v[180:183], v[122:125]
	v_mfma_f32_16x16x32_bf16 v[118:121], v[142:145], v[208:211], v[118:121]
	v_mfma_f32_16x16x32_bf16 v[114:117], v[150:153], v[208:211], v[114:117]
	v_mfma_f32_16x16x32_bf16 v[102:105], v[142:145], v[216:219], v[102:105]
	v_mfma_f32_16x16x32_bf16 v[98:101], v[150:153], v[216:219], v[98:101]
	v_mfma_f32_16x16x32_bf16 v[86:89], v[142:145], v[224:227], v[86:89]
	v_mfma_f32_16x16x32_bf16 v[82:85], v[150:153], v[224:227], v[82:85]
	v_mfma_f32_16x16x32_bf16 v[126:129], v[146:149], v[184:187], v[126:129]
	v_mfma_f32_16x16x32_bf16 v[122:125], v[154:157], v[184:187], v[122:125]
	v_mfma_f32_16x16x32_bf16 v[118:121], v[146:149], v[212:215], v[118:121]
	v_mfma_f32_16x16x32_bf16 v[114:117], v[154:157], v[212:215], v[114:117]
	v_mfma_f32_16x16x32_bf16 v[102:105], v[146:149], v[220:223], v[102:105]
	v_mfma_f32_16x16x32_bf16 v[98:101], v[154:157], v[220:223], v[98:101]
	v_mfma_f32_16x16x32_bf16 v[86:89], v[146:149], v[228:231], v[86:89]
	v_mfma_f32_16x16x32_bf16 v[82:85], v[154:157], v[228:231], v[82:85]
	v_mfma_f32_16x16x32_bf16 v[110:113], v[158:161], v[180:183], v[110:113]
	v_mfma_f32_16x16x32_bf16 v[106:109], v[172:175], v[180:183], v[106:109]
	v_mfma_f32_16x16x32_bf16 v[94:97], v[158:161], v[208:211], v[94:97]
	v_mfma_f32_16x16x32_bf16 v[90:93], v[172:175], v[208:211], v[90:93]
	v_mfma_f32_16x16x32_bf16 v[78:81], v[158:161], v[216:219], v[78:81]
	v_mfma_f32_16x16x32_bf16 v[74:77], v[172:175], v[216:219], v[74:77]
	v_mfma_f32_16x16x32_bf16 v[70:73], v[158:161], v[224:227], v[70:73]
	v_mfma_f32_16x16x32_bf16 v[66:69], v[172:175], v[224:227], v[66:69]
	v_mfma_f32_16x16x32_bf16 v[110:113], v[168:171], v[184:187], v[110:113]
	v_mfma_f32_16x16x32_bf16 v[106:109], v[176:179], v[184:187], v[106:109]
	v_mfma_f32_16x16x32_bf16 v[94:97], v[168:171], v[212:215], v[94:97]
	v_mfma_f32_16x16x32_bf16 v[90:93], v[176:179], v[212:215], v[90:93]
	v_mfma_f32_16x16x32_bf16 v[78:81], v[168:171], v[220:223], v[78:81]
	v_mfma_f32_16x16x32_bf16 v[74:77], v[176:179], v[220:223], v[74:77]
	v_mfma_f32_16x16x32_bf16 v[70:73], v[168:171], v[228:231], v[70:73]
	v_mfma_f32_16x16x32_bf16 v[66:69], v[176:179], v[228:231], v[66:69]
	s_barrier
; #define PG8_STAGE(bufoff, gbase, voff) do { _Pragma("unroll") for (int _i = 0; _i < 2; ++_i) \
;         __builtin_amdgcn_global_load_lds((const unsigned*)((const char*)(gbase) + (voff)[_i]), (LAS unsigned*)(lds + (bufoff) + ldsw + _i * 8192), 16, 0, 0); } while (0)
; #define PG8_LDA(dst, b, h) do { _Pragma("unroll") for (int m = 0; m < 4; ++m) _Pragma("unroll") for (int k = 0; k < 2; ++k) dst[m][k] = *(const LAS bf16x8*)(lds + PG8_SA(b, h) + aoff + m * 2048 + k * 1024); } while (0)
; #define PG8_MMA(ai, bj, At, Bt) do { __builtin_amdgcn_s_setprio(1); _Pragma("unroll") for (int m = 0; m < 4; ++m) _Pragma("unroll") for (int n = 0; n < 2; ++n) _Pragma("unroll") for (int k = 0; k < 2; ++k) \
;         acc[ai][bj][m][n] = __builtin_amdgcn_mfma_f32_16x16x32_bf16(Bt[n][k], At[m][k], acc[ai][bj][m][n], 0, 0, 0); __builtin_amdgcn_s_setprio(0); } while (0)
; #define PG8_WAIT_V(n) asm volatile("s_waitcnt vmcnt(" #n ")" ::: "memory")
; #define PG8_WAIT_L(n) asm volatile("s_waitcnt lgkmcnt(" #n ")" ::: "memory")
; #define PG8_BAR __builtin_amdgcn_s_barrier()
; #define PG8_SCHED __builtin_amdgcn_sched_barrier(0)
; template <class Epi, class Order = StaticOrder, bool HALFN = false>
; __device__ __forceinline__ void gemm_phase(LAS unsigned char* lds, const Gemm g, const Epi& E) {
;     ...
;             PG8_LDA(At, 1, 1); PG8_STAGE(PG8_SB(1, 0), b3, voffB); PG8_STAGE(PG8_SB(1, 1), b3 + hstepB, voffB); PG8_STAGE(PG8_SA(1, 0), a3, voffA);
;             PG8_WAIT_V(8); PG8_WAIT_L(0); PG8_BAR; PG8_MMA(1, 0, At, B0); if constexpr (!HALFN) PG8_MMA(1, 1, At, B1); PG8_BAR; PG8_SCHED;
;         }
;         if (wr == 0) PG8_BAR;
	s_setprio 0
	s_mov_b32 m0, s30
	v_lshl_add_u64 v[232:233], v[232:233], 0, s[60:61]
	ds_read_b128 v[180:183], v140 offset:49152
	ds_read_b128 v[184:187], v140 offset:50176
	ds_read_b128 v[208:211], v140 offset:51200
	ds_read_b128 v[212:215], v140 offset:52224
	ds_read_b128 v[216:219], v140 offset:53248
	ds_read_b128 v[220:223], v140 offset:54272
	ds_read_b128 v[224:227], v140 offset:55296
	ds_read_b128 v[228:231], v140 offset:56320
	global_load_lds_dwordx4 v[232:233], off
	v_lshl_add_u64 v[232:233], v[234:235], 0, s[60:61]
	s_mov_b32 m0, s29
	s_nop 0
	global_load_lds_dwordx4 v[232:233], off
	v_lshl_add_u64 v[232:233], s[4:5], 0, v[132:133]
	s_mov_b32 m0, vcc_hi
	s_nop 0
	global_load_lds_dwordx4 v[232:233], off
	v_lshl_add_u64 v[232:233], s[4:5], 0, v[136:137]
	s_mov_b32 m0, s88
	s_nop 0
	global_load_lds_dwordx4 v[232:233], off
	v_lshl_add_u64 v[232:233], v[236:237], 0, s[60:61]
	s_mov_b32 m0, s47
	s_nop 0
	global_load_lds_dwordx4 v[232:233], off
	v_lshl_add_u64 v[232:233], v[238:239], 0, s[60:61]
	s_mov_b32 m0, s89
	s_nop 0
	global_load_lds_dwordx4 v[232:233], off
	s_waitcnt vmcnt(8)
	s_waitcnt lgkmcnt(0)
	s_setprio 1
	s_barrier
	v_mfma_f32_16x16x32_bf16 v[62:65], v[142:145], v[180:183], v[62:65]
	v_mfma_f32_16x16x32_bf16 v[58:61], v[150:153], v[180:183], v[58:61]
	v_mfma_f32_16x16x32_bf16 v[54:57], v[142:145], v[208:211], v[54:57]
	v_mfma_f32_16x16x32_bf16 v[50:53], v[150:153], v[208:211], v[50:53]
	v_mfma_f32_16x16x32_bf16 v[38:41], v[142:145], v[216:219], v[38:41]
	v_mfma_f32_16x16x32_bf16 v[34:37], v[150:153], v[216:219], v[34:37]
	v_mfma_f32_16x16x32_bf16 v[22:25], v[142:145], v[224:227], v[22:25]
	v_mfma_f32_16x16x32_bf16 v[18:21], v[150:153], v[224:227], v[18:21]
	v_mfma_f32_16x16x32_bf16 v[62:65], v[146:149], v[184:187], v[62:65]
	v_mfma_f32_16x16x32_bf16 v[58:61], v[154:157], v[184:187], v[58:61]
	v_mfma_f32_16x16x32_bf16 v[54:57], v[146:149], v[212:215], v[54:57]
	v_mfma_f32_16x16x32_bf16 v[50:53], v[154:157], v[212:215], v[50:53]
	v_mfma_f32_16x16x32_bf16 v[38:41], v[146:149], v[220:223], v[38:41]
	v_mfma_f32_16x16x32_bf16 v[34:37], v[154:157], v[220:223], v[34:37]
	v_mfma_f32_16x16x32_bf16 v[22:25], v[146:149], v[228:231], v[22:25]
	v_mfma_f32_16x16x32_bf16 v[18:21], v[154:157], v[228:231], v[18:21]
	v_mfma_f32_16x16x32_bf16 v[46:49], v[158:161], v[180:183], v[46:49]
	v_mfma_f32_16x16x32_bf16 v[42:45], v[172:175], v[180:183], v[42:45]
	v_mfma_f32_16x16x32_bf16 v[30:33], v[158:161], v[208:211], v[30:33]
	v_mfma_f32_16x16x32_bf16 v[26:29], v[172:175], v[208:211], v[26:29]
	v_mfma_f32_16x16x32_bf16 v[14:17], v[158:161], v[216:219], v[14:17]
	v_mfma_f32_16x16x32_bf16 v[10:13], v[172:175], v[216:219], v[10:13]
	v_mfma_f32_16x16x32_bf16 v[6:9], v[158:161], v[224:227], v[6:9]
	v_mfma_f32_16x16x32_bf16 v[2:5], v[172:175], v[224:227], v[2:5]
	v_mfma_f32_16x16x32_bf16 v[46:49], v[168:171], v[184:187], v[46:49]
	v_mfma_f32_16x16x32_bf16 v[42:45], v[176:179], v[184:187], v[42:45]
	v_mfma_f32_16x16x32_bf16 v[30:33], v[168:171], v[212:215], v[30:33]
	v_mfma_f32_16x16x32_bf16 v[26:29], v[176:179], v[212:215], v[26:29]
	v_mfma_f32_16x16x32_bf16 v[14:17], v[168:171], v[220:223], v[14:17]
	v_mfma_f32_16x16x32_bf16 v[10:13], v[176:179], v[220:223], v[10:13]
	v_mfma_f32_16x16x32_bf16 v[6:9], v[168:171], v[228:231], v[6:9]
	v_mfma_f32_16x16x32_bf16 v[2:5], v[176:179], v[228:231], v[2:5]
	s_barrier
	s_setprio 0
	s_andn2_b64 vcc, exec, s[62:63]
	s_mov_b64 s[42:43], -1
	s_mov_b64 s[62:63], 0
	s_mov_b64 s[4:5], 0x100
	s_cbranch_vccz .LBB0_521
	s_and_b64 vcc, exec, s[48:49]
	s_cbranch_vccz .LBB0_524
	s_barrier

; #define PG8_STAGE(bufoff, gbase, voff) do { _Pragma("unroll") for (int _i = 0; _i < 2; ++_i) \
;         __builtin_amdgcn_global_load_lds((const unsigned*)((const char*)(gbase) + (voff)[_i]), (LAS unsigned*)(lds + (bufoff) + ldsw + _i * 8192), 16, 0, 0); } while (0)
; #define PG8_LDA(dst, b, h) do { _Pragma("unroll") for (int m = 0; m < 4; ++m) _Pragma("unroll") for (int k = 0; k < 2; ++k) dst[m][k] = *(const LAS bf16x8*)(lds + PG8_SA(b, h) + aoff + m * 2048 + k * 1024); } while (0)
; #define PG8_LDB(dst, b, h) do { _Pragma("unroll") for (int n = 0; n < 2; ++n) _Pragma("unroll") for (int k = 0; k < 2; ++k) dst[n][k] = *(const LAS bf16x8*)(lds + PG8_SB(b, h) + boff + n * 2048 + k * 1024); } while (0)
; #define PG8_MMA(ai, bj, At, Bt) do { __builtin_amdgcn_s_setprio(1); _Pragma("unroll") for (int m = 0; m < 4; ++m) _Pragma("unroll") for (int n = 0; n < 2; ++n) _Pragma("unroll") for (int k = 0; k < 2; ++k) \
;         acc[ai][bj][m][n] = __builtin_amdgcn_mfma_f32_16x16x32_bf16(Bt[n][k], At[m][k], acc[ai][bj][m][n], 0, 0, 0); __builtin_amdgcn_s_setprio(0); } while (0)
; #define PG8_WAIT_V(n) asm volatile("s_waitcnt vmcnt(" #n ")" ::: "memory")
; template <class Epi, class Order = StaticOrder, bool HALFN = false>
; __device__ __forceinline__ void gemm_phase(LAS unsigned char* lds, const Gemm g, const Epi& E) {
;     ...
;             const bool last = (t == nt - 2);
;             if constexpr (Epi::SEAMS) { if (t == Epi::SEAM0 || t == Epi::SEAM1) E.seam(acc, cur, t == Epi::SEAM0 ? 0 : 1, wr, wc, fr, fq); }
;             const char* a1 = cA + (size_t)(t + 1) * kstep;
;             const char* a2 = last ? nA : cA + (size_t)(t + 2) * kstep; const char* b2 = last ? nB : cB + (size_t)(t + 2) * kstep;
;             const char* a3 = a2 + kstep; const char* b3 = b2 + kstep;
;             PG8_LDB(B0, 0, 0); if constexpr (!HALFN) PG8_LDB(B1, 0, 1); PG8_SCHED; PG8_LDA(At, 0, 0); PG8_STAGE(PG8_SA(1, 1), a1 + hstepA, voffA);
;             PG8_WAIT_V(8); PG8_WAIT_L(0); PG8_BAR; PG8_MMA(0, 0, At, B0); if constexpr (!HALFN) PG8_MMA(0, 1, At, B1); PG8_BAR; PG8_SCHED;
;             PG8_LDA(At, 0, 1); PG8_STAGE(PG8_SB(0, 0), b2, voffB); PG8_STAGE(PG8_SB(0, 1), b2 + hstepB, voffB); PG8_STAGE(PG8_SA(0, 0), a2, voffA);
;             PG8_WAIT_V(8); PG8_WAIT_L(0); PG8_BAR; PG8_MMA(1, 0, At, B0); if constexpr (!HALFN) PG8_MMA(1, 1, At, B1); PG8_BAR; PG8_SCHED;
.LBB0_619:
	s_add_u32 s4, s52, s54
	s_addc_u32 s5, s53, s55
	s_add_u32 s4, s4, 0x100
	s_addc_u32 s5, s5, 0
	s_add_u32 s26, s62, s54
	s_addc_u32 s27, s63, s55
	s_add_i32 s28, 0, 0x10000
	s_cmpk_eq_i32 s54, 0x1700
	s_cselect_b32 s7, s49, s5
	s_cselect_b32 s6, s48, s4
	v_add_u32_e32 v1, s28, v182
	s_cselect_b32 s5, s51, s27
	s_cselect_b32 s4, s50, s26
	s_add_i32 s29, 0, 0x14000
	ds_read_b128 v[148:151], v1
	ds_read_b128 v[152:155], v1 offset:1024
	ds_read_b128 v[156:159], v1 offset:2048
	ds_read_b128 v[168:171], v1 offset:3072
	v_add_u32_e32 v1, s29, v182
	ds_read_b128 v[172:175], v1
	ds_read_b128 v[176:179], v1 offset:1024
	ds_read_b128 v[184:187], v1 offset:2048
	ds_read_b128 v[208:211], v1 offset:3072
	v_lshl_add_u64 v[2:3], v[144:145], 0, s[54:55]
	s_add_i32 m0, s16, 0xc000
	ds_read_b128 v[212:215], v183
	ds_read_b128 v[216:219], v183 offset:1024
	ds_read_b128 v[220:223], v183 offset:2048
	ds_read_b128 v[224:227], v183 offset:3072
	ds_read_b128 v[228:231], v183 offset:4096
	ds_read_b128 v[232:235], v183 offset:5120
	ds_read_b128 v[236:239], v183 offset:6144
	ds_read_b128 v[240:243], v183 offset:7168
	global_load_lds_dwordx4 v[2:3], off
	v_lshl_add_u64 v[2:3], v[146:147], 0, s[54:55]
	s_add_i32 m0, s16, 0xe000
	s_nop 0
	global_load_lds_dwordx4 v[2:3], off
	s_waitcnt vmcnt(8)
	s_waitcnt lgkmcnt(0)
	s_setprio 1
	s_barrier
	v_mfma_f32_16x16x32_bf16 v[128:131], v[148:151], v[212:215], v[128:131]
	v_mfma_f32_16x16x32_bf16 v[124:127], v[156:159], v[212:215], v[124:127]
	v_mfma_f32_16x16x32_bf16 v[112:115], v[148:151], v[220:223], v[112:115]
	v_mfma_f32_16x16x32_bf16 v[108:111], v[156:159], v[220:223], v[108:111]
	v_mfma_f32_16x16x32_bf16 v[96:99], v[148:151], v[228:231], v[96:99]
	v_mfma_f32_16x16x32_bf16 v[92:95], v[156:159], v[228:231], v[92:95]
	v_mfma_f32_16x16x32_bf16 v[80:83], v[148:151], v[236:239], v[80:83]
	v_mfma_f32_16x16x32_bf16 v[76:79], v[156:159], v[236:239], v[76:79]
	v_mfma_f32_16x16x32_bf16 v[128:131], v[152:155], v[216:219], v[128:131]
	v_mfma_f32_16x16x32_bf16 v[124:127], v[168:171], v[216:219], v[124:127]
	v_mfma_f32_16x16x32_bf16 v[112:115], v[152:155], v[224:227], v[112:115]
	v_mfma_f32_16x16x32_bf16 v[108:111], v[168:171], v[224:227], v[108:111]
	v_mfma_f32_16x16x32_bf16 v[96:99], v[152:155], v[232:235], v[96:99]
	v_mfma_f32_16x16x32_bf16 v[92:95], v[168:171], v[232:235], v[92:95]
	v_mfma_f32_16x16x32_bf16 v[80:83], v[152:155], v[240:243], v[80:83]
	v_mfma_f32_16x16x32_bf16 v[76:79], v[168:171], v[240:243], v[76:79]
	v_mfma_f32_16x16x32_bf16 v[120:123], v[172:175], v[212:215], v[120:123]
	v_mfma_f32_16x16x32_bf16 v[116:119], v[184:187], v[212:215], v[116:119]
	v_mfma_f32_16x16x32_bf16 v[104:107], v[172:175], v[220:223], v[104:107]
	v_mfma_f32_16x16x32_bf16 v[100:103], v[184:187], v[220:223], v[100:103]
	v_mfma_f32_16x16x32_bf16 v[88:91], v[172:175], v[228:231], v[88:91]
	v_mfma_f32_16x16x32_bf16 v[84:87], v[184:187], v[228:231], v[84:87]
	v_mfma_f32_16x16x32_bf16 v[72:75], v[172:175], v[236:239], v[72:75]
	v_mfma_f32_16x16x32_bf16 v[68:71], v[184:187], v[236:239], v[68:71]
	v_mfma_f32_16x16x32_bf16 v[120:123], v[176:179], v[216:219], v[120:123]
	v_mfma_f32_16x16x32_bf16 v[116:119], v[208:211], v[216:219], v[116:119]
	v_mfma_f32_16x16x32_bf16 v[104:107], v[176:179], v[224:227], v[104:107]
	v_mfma_f32_16x16x32_bf16 v[100:103], v[208:211], v[224:227], v[100:103]
	v_mfma_f32_16x16x32_bf16 v[88:91], v[176:179], v[232:235], v[88:91]
	v_mfma_f32_16x16x32_bf16 v[84:87], v[208:211], v[232:235], v[84:87]
	v_mfma_f32_16x16x32_bf16 v[72:75], v[176:179], v[240:243], v[72:75]
	v_mfma_f32_16x16x32_bf16 v[68:71], v[208:211], v[240:243], v[68:71]
	s_barrier
	s_setprio 0
	s_add_i32 s26, s28, s15
	v_lshl_add_u64 v[160:161], s[4:5], 0, v[134:135]
	s_mov_b32 m0, s26
	ds_read_b128 v[212:215], v183 offset:16384
	ds_read_b128 v[216:219], v183 offset:17408
	ds_read_b128 v[220:223], v183 offset:18432
	ds_read_b128 v[224:227], v183 offset:19456
	ds_read_b128 v[228:231], v183 offset:20480
	ds_read_b128 v[232:235], v183 offset:21504
	ds_read_b128 v[236:239], v183 offset:22528
	ds_read_b128 v[240:243], v183 offset:23552
	global_load_lds_dwordx4 v[160:161], off
	s_add_i32 m0, s26, 0x2000
	s_add_u32 s26, s4, 0xc0000
	v_lshl_add_u64 v[244:245], s[4:5], 0, v[138:139]
	s_addc_u32 s27, s5, 0
	s_add_i32 s28, s29, s15
	global_load_lds_dwordx4 v[244:245], off
	v_lshl_add_u64 v[2:3], s[26:27], 0, v[134:135]
	s_mov_b32 m0, s28
	v_lshl_add_u64 v[246:247], s[6:7], 0, v[132:133]
	global_load_lds_dwordx4 v[2:3], off
	v_lshl_add_u64 v[2:3], s[26:27], 0, v[138:139]
	s_add_i32 m0, s28, 0x2000
	v_lshl_add_u64 v[248:249], s[6:7], 0, v[136:137]
	global_load_lds_dwordx4 v[2:3], off
	s_mov_b32 m0, s16
	s_nop 0
	global_load_lds_dwordx4 v[246:247], off
	s_mov_b32 m0, s17
	s_nop 0
	global_load_lds_dwordx4 v[248:249], off
	s_waitcnt vmcnt(8)
	s_waitcnt lgkmcnt(0)
	s_setprio 1
	s_barrier
; #define PG8_STAGE(bufoff, gbase, voff) do { _Pragma("unroll") for (int _i = 0; _i < 2; ++_i) \
;         __builtin_amdgcn_global_load_lds((const unsigned*)((const char*)(gbase) + (voff)[_i]), (LAS unsigned*)(lds + (bufoff) + ldsw + _i * 8192), 16, 0, 0); } while (0)
; #define PG8_LDA(dst, b, h) do { _Pragma("unroll") for (int m = 0; m < 4; ++m) _Pragma("unroll") for (int k = 0; k < 2; ++k) dst[m][k] = *(const LAS bf16x8*)(lds + PG8_SA(b, h) + aoff + m * 2048 + k * 1024); } while (0)
; #define PG8_LDB(dst, b, h) do { _Pragma("unroll") for (int n = 0; n < 2; ++n) _Pragma("unroll") for (int k = 0; k < 2; ++k) dst[n][k] = *(const LAS bf16x8*)(lds + PG8_SB(b, h) + boff + n * 2048 + k * 1024); } while (0)
; #define PG8_MMA(ai, bj, At, Bt) do { __builtin_amdgcn_s_setprio(1); _Pragma("unroll") for (int m = 0; m < 4; ++m) _Pragma("unroll") for (int n = 0; n < 2; ++n) _Pragma("unroll") for (int k = 0; k < 2; ++k) \
;         acc[ai][bj][m][n] = __builtin_amdgcn_mfma_f32_16x16x32_bf16(Bt[n][k], At[m][k], acc[ai][bj][m][n], 0, 0, 0); __builtin_amdgcn_s_setprio(0); } while (0)
; #define PG8_WAIT_V(n) asm volatile("s_waitcnt vmcnt(" #n ")" ::: "memory")
; #define PG8_WAIT_L(n) asm volatile("s_waitcnt lgkmcnt(" #n ")" ::: "memory")
; #define PG8_BAR __builtin_amdgcn_s_barrier()
; #define PG8_SCHED __builtin_amdgcn_sched_barrier(0)
; template <class Epi, class Order = StaticOrder, bool HALFN = false>
; __device__ __forceinline__ void gemm_phase(LAS unsigned char* lds, const Gemm g, const Epi& E) {
;     ...
;             PG8_WAIT_V(8); PG8_WAIT_L(0); PG8_BAR; PG8_MMA(1, 0, At, B0); if constexpr (!HALFN) PG8_MMA(1, 1, At, B1); PG8_BAR; PG8_SCHED;
;             PG8_LDB(B0, 1, 0); if constexpr (!HALFN) PG8_LDB(B1, 1, 1); PG8_SCHED; PG8_LDA(At, 1, 0); PG8_STAGE(PG8_SA(0, 1), a2 + hstepA, voffA);
;             PG8_WAIT_V(8); PG8_WAIT_L(0); PG8_BAR; PG8_MMA(0, 0, At, B0); if constexpr (!HALFN) PG8_MMA(0, 1, At, B1); PG8_BAR; PG8_SCHED;
;             PG8_LDA(At, 1, 1); PG8_STAGE(PG8_SB(1, 0), b3, voffB); PG8_STAGE(PG8_SB(1, 1), b3 + hstepB, voffB); PG8_STAGE(PG8_SA(1, 0), a3, voffA);
;             PG8_WAIT_V(8); PG8_WAIT_L(0); PG8_BAR; PG8_MMA(1, 0, At, B0); if constexpr (!HALFN) PG8_MMA(1, 1, At, B1); PG8_BAR; PG8_SCHED;
	v_mfma_f32_16x16x32_bf16 v[64:67], v[148:151], v[212:215], v[64:67]
	v_mfma_f32_16x16x32_bf16 v[60:63], v[156:159], v[212:215], v[60:63]
	v_mfma_f32_16x16x32_bf16 v[48:51], v[148:151], v[220:223], v[48:51]
	v_mfma_f32_16x16x32_bf16 v[44:47], v[156:159], v[220:223], v[44:47]
	v_mfma_f32_16x16x32_bf16 v[32:35], v[148:151], v[228:231], v[32:35]
	v_mfma_f32_16x16x32_bf16 v[28:31], v[156:159], v[228:231], v[28:31]
	v_mfma_f32_16x16x32_bf16 v[16:19], v[148:151], v[236:239], v[16:19]
	v_mfma_f32_16x16x32_bf16 v[12:15], v[156:159], v[236:239], v[12:15]
	v_mfma_f32_16x16x32_bf16 v[64:67], v[152:155], v[216:219], v[64:67]
	v_mfma_f32_16x16x32_bf16 v[60:63], v[168:171], v[216:219], v[60:63]
	v_mfma_f32_16x16x32_bf16 v[48:51], v[152:155], v[224:227], v[48:51]
	v_mfma_f32_16x16x32_bf16 v[44:47], v[168:171], v[224:227], v[44:47]
	v_mfma_f32_16x16x32_bf16 v[32:35], v[152:155], v[232:235], v[32:35]
	v_mfma_f32_16x16x32_bf16 v[28:31], v[168:171], v[232:235], v[28:31]
	v_mfma_f32_16x16x32_bf16 v[16:19], v[152:155], v[240:243], v[16:19]
	v_mfma_f32_16x16x32_bf16 v[12:15], v[168:171], v[240:243], v[12:15]
	v_mfma_f32_16x16x32_bf16 v[56:59], v[172:175], v[212:215], v[56:59]
	v_mfma_f32_16x16x32_bf16 v[52:55], v[184:187], v[212:215], v[52:55]
	v_mfma_f32_16x16x32_bf16 v[40:43], v[172:175], v[220:223], v[40:43]
	v_mfma_f32_16x16x32_bf16 v[36:39], v[184:187], v[220:223], v[36:39]
	v_mfma_f32_16x16x32_bf16 v[24:27], v[172:175], v[228:231], v[24:27]
	v_mfma_f32_16x16x32_bf16 v[20:23], v[184:187], v[228:231], v[20:23]
	v_mfma_f32_16x16x32_bf16 v[8:11], v[172:175], v[236:239], v[8:11]
	v_mfma_f32_16x16x32_bf16 v[2:5], v[184:187], v[236:239], v[4:7]
	v_mfma_f32_16x16x32_bf16 v[56:59], v[176:179], v[216:219], v[56:59]
	v_mfma_f32_16x16x32_bf16 v[52:55], v[208:211], v[216:219], v[52:55]
	v_mfma_f32_16x16x32_bf16 v[40:43], v[176:179], v[224:227], v[40:43]
	v_mfma_f32_16x16x32_bf16 v[36:39], v[208:211], v[224:227], v[36:39]
	v_mfma_f32_16x16x32_bf16 v[24:27], v[176:179], v[232:235], v[24:27]
	v_mfma_f32_16x16x32_bf16 v[20:23], v[208:211], v[232:235], v[20:23]
	v_mfma_f32_16x16x32_bf16 v[8:11], v[176:179], v[240:243], v[8:11]
	v_mfma_f32_16x16x32_bf16 v[2:5], v[208:211], v[240:243], v[2:5]
	s_barrier
	s_setprio 0
	s_add_i32 s26, 0, 0x18000
	v_add_u32_e32 v1, s26, v182
	s_add_i32 s27, 0, 0x1c000
	ds_read_b128 v[148:151], v1
	ds_read_b128 v[152:155], v1 offset:1024
	ds_read_b128 v[156:159], v1 offset:2048
	ds_read_b128 v[168:171], v1 offset:3072
	v_add_u32_e32 v1, s27, v182
	ds_read_b128 v[172:175], v1
	ds_read_b128 v[176:179], v1 offset:1024
	ds_read_b128 v[184:187], v1 offset:2048
	ds_read_b128 v[208:211], v1 offset:3072
	s_add_u32 s6, s6, 0xc0000
	s_addc_u32 s7, s7, 0
	s_mov_b32 m0, s18
	v_lshl_add_u64 v[6:7], s[6:7], 0, v[132:133]
	ds_read_b128 v[212:215], v183 offset:32768
	ds_read_b128 v[216:219], v183 offset:33792
	ds_read_b128 v[220:223], v183 offset:34816
	ds_read_b128 v[224:227], v183 offset:35840
	ds_read_b128 v[228:231], v183 offset:36864
	ds_read_b128 v[232:235], v183 offset:37888
	ds_read_b128 v[236:239], v183 offset:38912
	ds_read_b128 v[240:243], v183 offset:39936
	global_load_lds_dwordx4 v[6:7], off
	v_lshl_add_u64 v[6:7], s[6:7], 0, v[136:137]
	s_mov_b32 m0, s19
	s_nop 0
	global_load_lds_dwordx4 v[6:7], off
	s_waitcnt vmcnt(8)
	s_waitcnt lgkmcnt(0)
	s_setprio 1
	s_barrier
	v_mfma_f32_16x16x32_bf16 v[128:131], v[148:151], v[212:215], v[128:131]
	v_mfma_f32_16x16x32_bf16 v[124:127], v[156:159], v[212:215], v[124:127]
	v_mfma_f32_16x16x32_bf16 v[112:115], v[148:151], v[220:223], v[112:115]
	v_mfma_f32_16x16x32_bf16 v[108:111], v[156:159], v[220:223], v[108:111]
	v_mfma_f32_16x16x32_bf16 v[96:99], v[148:151], v[228:231], v[96:99]
	v_mfma_f32_16x16x32_bf16 v[92:95], v[156:159], v[228:231], v[92:95]
	v_mfma_f32_16x16x32_bf16 v[80:83], v[148:151], v[236:239], v[80:83]
	v_mfma_f32_16x16x32_bf16 v[76:79], v[156:159], v[236:239], v[76:79]
	v_mfma_f32_16x16x32_bf16 v[128:131], v[152:155], v[216:219], v[128:131]
	v_mfma_f32_16x16x32_bf16 v[124:127], v[168:171], v[216:219], v[124:127]
	v_mfma_f32_16x16x32_bf16 v[112:115], v[152:155], v[224:227], v[112:115]
	v_mfma_f32_16x16x32_bf16 v[108:111], v[168:171], v[224:227], v[108:111]
	v_mfma_f32_16x16x32_bf16 v[96:99], v[152:155], v[232:235], v[96:99]
	v_mfma_f32_16x16x32_bf16 v[92:95], v[168:171], v[232:235], v[92:95]
	v_mfma_f32_16x16x32_bf16 v[80:83], v[152:155], v[240:243], v[80:83]
	v_mfma_f32_16x16x32_bf16 v[76:79], v[168:171], v[240:243], v[76:79]
	v_mfma_f32_16x16x32_bf16 v[120:123], v[172:175], v[212:215], v[120:123]
	v_mfma_f32_16x16x32_bf16 v[116:119], v[184:187], v[212:215], v[116:119]
	v_mfma_f32_16x16x32_bf16 v[104:107], v[172:175], v[220:223], v[104:107]
	v_mfma_f32_16x16x32_bf16 v[100:103], v[184:187], v[220:223], v[100:103]
	v_mfma_f32_16x16x32_bf16 v[88:91], v[172:175], v[228:231], v[88:91]
	v_mfma_f32_16x16x32_bf16 v[84:87], v[184:187], v[228:231], v[84:87]
	v_mfma_f32_16x16x32_bf16 v[72:75], v[172:175], v[236:239], v[72:75]
	v_mfma_f32_16x16x32_bf16 v[68:71], v[184:187], v[236:239], v[68:71]
	v_mfma_f32_16x16x32_bf16 v[120:123], v[176:179], v[216:219], v[120:123]
	v_mfma_f32_16x16x32_bf16 v[116:119], v[208:211], v[216:219], v[116:119]
	v_mfma_f32_16x16x32_bf16 v[104:107], v[176:179], v[224:227], v[104:107]
	v_mfma_f32_16x16x32_bf16 v[100:103], v[208:211], v[224:227], v[100:103]
	v_mfma_f32_16x16x32_bf16 v[88:91], v[176:179], v[232:235], v[88:91]
	v_mfma_f32_16x16x32_bf16 v[84:87], v[208:211], v[232:235], v[84:87]
	v_mfma_f32_16x16x32_bf16 v[72:75], v[176:179], v[240:243], v[72:75]
	v_mfma_f32_16x16x32_bf16 v[68:71], v[208:211], v[240:243], v[68:71]
	s_barrier
; #define PG8_STAGE(bufoff, gbase, voff) do { _Pragma("unroll") for (int _i = 0; _i < 2; ++_i) \
;         __builtin_amdgcn_global_load_lds((const unsigned*)((const char*)(gbase) + (voff)[_i]), (LAS unsigned*)(lds + (bufoff) + ldsw + _i * 8192), 16, 0, 0); } while (0)
; #define PG8_LDA(dst, b, h) do { _Pragma("unroll") for (int m = 0; m < 4; ++m) _Pragma("unroll") for (int k = 0; k < 2; ++k) dst[m][k] = *(const LAS bf16x8*)(lds + PG8_SA(b, h) + aoff + m * 2048 + k * 1024); } while (0)
; #define PG8_MMA(ai, bj, At, Bt) do { __builtin_amdgcn_s_setprio(1); _Pragma("unroll") for (int m = 0; m < 4; ++m) _Pragma("unroll") for (int n = 0; n < 2; ++n) _Pragma("unroll") for (int k = 0; k < 2; ++k) \
;         acc[ai][bj][m][n] = __builtin_amdgcn_mfma_f32_16x16x32_bf16(Bt[n][k], At[m][k], acc[ai][bj][m][n], 0, 0, 0); __builtin_amdgcn_s_setprio(0); } while (0)
; #define PG8_WAIT_V(n) asm volatile("s_waitcnt vmcnt(" #n ")" ::: "memory")
; #define PG8_WAIT_L(n) asm volatile("s_waitcnt lgkmcnt(" #n ")" ::: "memory")
; #define PG8_BAR __builtin_amdgcn_s_barrier()
; #define PG8_SCHED __builtin_amdgcn_sched_barrier(0)
; template <class Epi, class Order = StaticOrder, bool HALFN = false>
; __device__ __forceinline__ void gemm_phase(LAS unsigned char* lds, const Gemm g, const Epi& E) {
;     ...
;         for (int t = 0; t < nt; t += 2) {
;             const bool last = (t == nt - 2);
;             if constexpr (Epi::SEAMS) { if (t == Epi::SEAM0 || t == Epi::SEAM1) E.seam(acc, cur, t == Epi::SEAM0 ? 0 : 1, wr, wc, fr, fq); }
;     ...
;             PG8_LDA(At, 1, 1); PG8_STAGE(PG8_SB(1, 0), b3, voffB); PG8_STAGE(PG8_SB(1, 1), b3 + hstepB, voffB); PG8_STAGE(PG8_SA(1, 0), a3, voffA);
;             PG8_WAIT_V(8); PG8_WAIT_L(0); PG8_BAR; PG8_MMA(1, 0, At, B0); if constexpr (!HALFN) PG8_MMA(1, 1, At, B1); PG8_BAR; PG8_SCHED;
;         }
	s_setprio 0
	s_add_i32 s6, s26, s15
	v_lshl_add_u64 v[6:7], v[160:161], 0, s[60:61]
	s_mov_b32 m0, s6
	ds_read_b128 v[212:215], v183 offset:49152
	ds_read_b128 v[216:219], v183 offset:50176
	ds_read_b128 v[220:223], v183 offset:51200
	ds_read_b128 v[224:227], v183 offset:52224
	ds_read_b128 v[228:231], v183 offset:53248
	ds_read_b128 v[232:235], v183 offset:54272
	ds_read_b128 v[236:239], v183 offset:55296
	ds_read_b128 v[240:243], v183 offset:56320
	global_load_lds_dwordx4 v[6:7], off
	s_add_i32 m0, s6, 0x2000
	s_add_u32 s4, s4, 0xc0080
	v_lshl_add_u64 v[6:7], v[244:245], 0, s[60:61]
	s_addc_u32 s5, s5, 0
	s_add_i32 s6, s27, s15
	global_load_lds_dwordx4 v[6:7], off
	v_lshl_add_u64 v[6:7], s[4:5], 0, v[134:135]
	s_mov_b32 m0, s6
	s_nop 0
	global_load_lds_dwordx4 v[6:7], off
	v_lshl_add_u64 v[6:7], s[4:5], 0, v[138:139]
	s_add_i32 m0, s6, 0x2000
	s_nop 0
	global_load_lds_dwordx4 v[6:7], off
	v_lshl_add_u64 v[6:7], v[246:247], 0, s[60:61]
	s_mov_b32 m0, s22
	s_nop 0
	global_load_lds_dwordx4 v[6:7], off
	v_lshl_add_u64 v[6:7], v[248:249], 0, s[60:61]
	s_mov_b32 m0, s23
	s_nop 0
	global_load_lds_dwordx4 v[6:7], off
	s_waitcnt vmcnt(8)
	s_waitcnt lgkmcnt(0)
	s_setprio 1
	s_barrier
	v_mfma_f32_16x16x32_bf16 v[64:67], v[148:151], v[212:215], v[64:67]
	v_mfma_f32_16x16x32_bf16 v[60:63], v[156:159], v[212:215], v[60:63]
	v_mfma_f32_16x16x32_bf16 v[48:51], v[148:151], v[220:223], v[48:51]
	v_mfma_f32_16x16x32_bf16 v[44:47], v[156:159], v[220:223], v[44:47]
	v_mfma_f32_16x16x32_bf16 v[32:35], v[148:151], v[228:231], v[32:35]
	v_mfma_f32_16x16x32_bf16 v[28:31], v[156:159], v[228:231], v[28:31]
	v_mfma_f32_16x16x32_bf16 v[16:19], v[148:151], v[236:239], v[16:19]
	v_mfma_f32_16x16x32_bf16 v[12:15], v[156:159], v[236:239], v[12:15]
	v_mfma_f32_16x16x32_bf16 v[64:67], v[152:155], v[216:219], v[64:67]
	v_mfma_f32_16x16x32_bf16 v[60:63], v[168:171], v[216:219], v[60:63]
	v_mfma_f32_16x16x32_bf16 v[48:51], v[152:155], v[224:227], v[48:51]
	v_mfma_f32_16x16x32_bf16 v[44:47], v[168:171], v[224:227], v[44:47]
	v_mfma_f32_16x16x32_bf16 v[32:35], v[152:155], v[232:235], v[32:35]
	v_mfma_f32_16x16x32_bf16 v[28:31], v[168:171], v[232:235], v[28:31]
	v_mfma_f32_16x16x32_bf16 v[16:19], v[152:155], v[240:243], v[16:19]
	v_mfma_f32_16x16x32_bf16 v[12:15], v[168:171], v[240:243], v[12:15]
	v_mfma_f32_16x16x32_bf16 v[56:59], v[172:175], v[212:215], v[56:59]
	v_mfma_f32_16x16x32_bf16 v[52:55], v[184:187], v[212:215], v[52:55]
	v_mfma_f32_16x16x32_bf16 v[40:43], v[172:175], v[220:223], v[40:43]
	v_mfma_f32_16x16x32_bf16 v[36:39], v[184:187], v[220:223], v[36:39]
	v_mfma_f32_16x16x32_bf16 v[24:27], v[172:175], v[228:231], v[24:27]
	v_mfma_f32_16x16x32_bf16 v[20:23], v[184:187], v[228:231], v[20:23]
	v_mfma_f32_16x16x32_bf16 v[6:9], v[172:175], v[236:239], v[8:11]
	v_mfma_f32_16x16x32_bf16 v[2:5], v[184:187], v[236:239], v[2:5]
	v_mfma_f32_16x16x32_bf16 v[56:59], v[176:179], v[216:219], v[56:59]
	v_mfma_f32_16x16x32_bf16 v[52:55], v[208:211], v[216:219], v[52:55]
	v_mfma_f32_16x16x32_bf16 v[40:43], v[176:179], v[224:227], v[40:43]
	v_mfma_f32_16x16x32_bf16 v[36:39], v[208:211], v[224:227], v[36:39]
	v_mfma_f32_16x16x32_bf16 v[24:27], v[176:179], v[232:235], v[24:27]
	v_mfma_f32_16x16x32_bf16 v[20:23], v[208:211], v[232:235], v[20:23]
	v_mfma_f32_16x16x32_bf16 v[8:11], v[176:179], v[240:243], v[6:9]
	v_mfma_f32_16x16x32_bf16 v[4:7], v[208:211], v[240:243], v[2:5]
	s_barrier
	s_setprio 0
	s_add_i32 s4, s74, 2
	s_add_u32 s54, s54, 0x100
	s_addc_u32 s55, s55, 0
	s_cmp_gt_u32 s74, 45
	s_cbranch_scc1 .LBB0_621
	s_mov_b32 s74, s4
	s_cmp_lt_i32 s74, 32
	s_cbranch_scc1 .LBB0_615
	s_branch .LBB0_614

; #define PG8_STAGE(bufoff, gbase, voff) do { _Pragma("unroll") for (int _i = 0; _i < 2; ++_i) \
;         __builtin_amdgcn_global_load_lds((const unsigned*)((const char*)(gbase) + (voff)[_i]), (LAS unsigned*)(lds + (bufoff) + ldsw + _i * 8192), 16, 0, 0); } while (0)
; #define PG8_LDA(dst, b, h) do { _Pragma("unroll") for (int m = 0; m < 4; ++m) _Pragma("unroll") for (int k = 0; k < 2; ++k) dst[m][k] = *(const LAS bf16x8*)(lds + PG8_SA(b, h) + aoff + m * 2048 + k * 1024); } while (0)
; #define PG8_LDB(dst, b, h) do { _Pragma("unroll") for (int n = 0; n < 2; ++n) _Pragma("unroll") for (int k = 0; k < 2; ++k) dst[n][k] = *(const LAS bf16x8*)(lds + PG8_SB(b, h) + boff + n * 2048 + k * 1024); } while (0)
; #define PG8_MMA(ai, bj, At, Bt) do { __builtin_amdgcn_s_setprio(1); _Pragma("unroll") for (int m = 0; m < 4; ++m) _Pragma("unroll") for (int n = 0; n < 2; ++n) _Pragma("unroll") for (int k = 0; k < 2; ++k) \
;         acc[ai][bj][m][n] = __builtin_amdgcn_mfma_f32_16x16x32_bf16(Bt[n][k], At[m][k], acc[ai][bj][m][n], 0, 0, 0); __builtin_amdgcn_s_setprio(0); } while (0)
; #define PG8_WAIT_V(n) asm volatile("s_waitcnt vmcnt(" #n ")" ::: "memory")
; #define PG8_WAIT_L(n) asm volatile("s_waitcnt lgkmcnt(" #n ")" ::: "memory")
; #define PG8_BAR __builtin_amdgcn_s_barrier()
; #define PG8_SCHED __builtin_amdgcn_sched_barrier(0)
; template <class Epi, class Order = StaticOrder, bool HALFN = false>
; __device__ __forceinline__ void gemm_phase(LAS unsigned char* lds, const Gemm g, const Epi& E) {
;     ...
;             const char* a1 = cA + (size_t)(t + 1) * kstep;
;             const char* a2 = last ? nA : cA + (size_t)(t + 2) * kstep; const char* b2 = last ? nB : cB + (size_t)(t + 2) * kstep;
;             const char* a3 = a2 + kstep; const char* b3 = b2 + kstep;
;             PG8_LDB(B0, 0, 0); if constexpr (!HALFN) PG8_LDB(B1, 0, 1); PG8_SCHED; PG8_LDA(At, 0, 0); PG8_STAGE(PG8_SA(1, 1), a1 + hstepA, voffA);
;             PG8_WAIT_V(8); PG8_WAIT_L(0); PG8_BAR; PG8_MMA(0, 0, At, B0); if constexpr (!HALFN) PG8_MMA(0, 1, At, B1); PG8_BAR; PG8_SCHED;
;             PG8_LDA(At, 0, 1); PG8_STAGE(PG8_SB(0, 0), b2, voffB); PG8_STAGE(PG8_SB(0, 1), b2 + hstepB, voffB); PG8_STAGE(PG8_SA(0, 0), a2, voffA);
;             PG8_WAIT_V(8); PG8_WAIT_L(0); PG8_BAR; PG8_MMA(1, 0, At, B0); if constexpr (!HALFN) PG8_MMA(1, 1, At, B1); PG8_BAR; PG8_SCHED;
.LBB0_709:
	s_add_u32 s4, s62, 0xfff80080
	s_addc_u32 s5, s63, -1
	s_add_i32 s30, 0, 0x10000
	s_cmp_eq_u32 s29, 28
	s_cselect_b32 s7, s23, s5
	s_cselect_b32 s6, s24, s4
	v_add_u32_e32 v145, s30, v143
	s_cselect_b32 s5, s25, s28
	s_cselect_b32 s4, s26, s27
	s_add_i32 s34, 0, 0x14000
	ds_read_b128 v[146:149], v145
	ds_read_b128 v[150:153], v145 offset:1024
	ds_read_b128 v[154:157], v145 offset:2048
	ds_read_b128 v[158:161], v145 offset:3072
	v_add_u32_e32 v145, s34, v143
	ds_read_b128 v[168:171], v145
	ds_read_b128 v[172:175], v145 offset:1024
	ds_read_b128 v[176:179], v145 offset:2048
	ds_read_b128 v[180:183], v145 offset:3072
	v_lshl_add_u64 v[236:237], s[62:63], 0, v[138:139]
	s_add_i32 m0, s16, 0xc000
	ds_read_b128 v[184:187], v144
	ds_read_b128 v[208:211], v144 offset:1024
	ds_read_b128 v[212:215], v144 offset:2048
	ds_read_b128 v[216:219], v144 offset:3072
	ds_read_b128 v[220:223], v144 offset:4096
	ds_read_b128 v[224:227], v144 offset:5120
	ds_read_b128 v[228:231], v144 offset:6144
	ds_read_b128 v[232:235], v144 offset:7168
	global_load_lds_dwordx4 v[236:237], off
	v_lshl_add_u64 v[236:237], s[62:63], 0, v[140:141]
	s_add_i32 m0, s16, 0xe000
	s_nop 0
	global_load_lds_dwordx4 v[236:237], off
	s_waitcnt vmcnt(8)
	s_waitcnt lgkmcnt(0)
	s_setprio 1
	s_barrier
	v_mfma_f32_16x16x32_bf16 v[2:5], v[146:149], v[184:187], v[2:5]
	v_mfma_f32_16x16x32_bf16 v[6:9], v[154:157], v[184:187], v[6:9]
	v_mfma_f32_16x16x32_bf16 v[10:13], v[146:149], v[212:215], v[10:13]
	v_mfma_f32_16x16x32_bf16 v[14:17], v[154:157], v[212:215], v[14:17]
	v_mfma_f32_16x16x32_bf16 v[18:21], v[146:149], v[220:223], v[18:21]
	v_mfma_f32_16x16x32_bf16 v[26:29], v[154:157], v[220:223], v[26:29]
	v_mfma_f32_16x16x32_bf16 v[30:33], v[146:149], v[228:231], v[30:33]
	v_mfma_f32_16x16x32_bf16 v[42:45], v[154:157], v[228:231], v[42:45]
	v_mfma_f32_16x16x32_bf16 v[2:5], v[150:153], v[208:211], v[2:5]
	v_mfma_f32_16x16x32_bf16 v[6:9], v[158:161], v[208:211], v[6:9]
	v_mfma_f32_16x16x32_bf16 v[10:13], v[150:153], v[216:219], v[10:13]
	v_mfma_f32_16x16x32_bf16 v[14:17], v[158:161], v[216:219], v[14:17]
	v_mfma_f32_16x16x32_bf16 v[18:21], v[150:153], v[224:227], v[18:21]
	v_mfma_f32_16x16x32_bf16 v[26:29], v[158:161], v[224:227], v[26:29]
	v_mfma_f32_16x16x32_bf16 v[30:33], v[150:153], v[232:235], v[30:33]
	v_mfma_f32_16x16x32_bf16 v[42:45], v[158:161], v[232:235], v[42:45]
	v_mfma_f32_16x16x32_bf16 v[22:25], v[168:171], v[184:187], v[22:25]
	v_mfma_f32_16x16x32_bf16 v[34:37], v[176:179], v[184:187], v[34:37]
	v_mfma_f32_16x16x32_bf16 v[38:41], v[168:171], v[212:215], v[38:41]
	v_mfma_f32_16x16x32_bf16 v[46:49], v[176:179], v[212:215], v[46:49]
	v_mfma_f32_16x16x32_bf16 v[50:53], v[168:171], v[220:223], v[50:53]
	v_mfma_f32_16x16x32_bf16 v[54:57], v[176:179], v[220:223], v[54:57]
	v_mfma_f32_16x16x32_bf16 v[58:61], v[168:171], v[228:231], v[58:61]
	v_mfma_f32_16x16x32_bf16 v[66:69], v[176:179], v[228:231], v[66:69]
	v_mfma_f32_16x16x32_bf16 v[22:25], v[172:175], v[208:211], v[22:25]
	v_mfma_f32_16x16x32_bf16 v[34:37], v[180:183], v[208:211], v[34:37]
	v_mfma_f32_16x16x32_bf16 v[38:41], v[172:175], v[216:219], v[38:41]
	v_mfma_f32_16x16x32_bf16 v[46:49], v[180:183], v[216:219], v[46:49]
	v_mfma_f32_16x16x32_bf16 v[50:53], v[172:175], v[224:227], v[50:53]
	v_mfma_f32_16x16x32_bf16 v[54:57], v[180:183], v[224:227], v[54:57]
	v_mfma_f32_16x16x32_bf16 v[58:61], v[172:175], v[232:235], v[58:61]
	v_mfma_f32_16x16x32_bf16 v[66:69], v[180:183], v[232:235], v[66:69]
	s_barrier
	s_setprio 0
	s_add_i32 s30, s30, s10
	v_lshl_add_u64 v[236:237], s[4:5], 0, v[132:133]
	s_mov_b32 m0, s30
	ds_read_b128 v[184:187], v144 offset:16384
	ds_read_b128 v[208:211], v144 offset:17408
	ds_read_b128 v[212:215], v144 offset:18432
	ds_read_b128 v[216:219], v144 offset:19456
	ds_read_b128 v[220:223], v144 offset:20480
	ds_read_b128 v[224:227], v144 offset:21504
	ds_read_b128 v[228:231], v144 offset:22528
	ds_read_b128 v[232:235], v144 offset:23552
	global_load_lds_dwordx4 v[236:237], off
	s_add_i32 m0, s30, 0x2000
	s_add_u32 s30, s4, 0x80000
	v_lshl_add_u64 v[238:239], s[4:5], 0, v[136:137]
	s_addc_u32 s31, s5, 0
	s_add_i32 s34, s34, s10
	global_load_lds_dwordx4 v[238:239], off
	v_lshl_add_u64 v[240:241], s[30:31], 0, v[132:133]
	s_mov_b32 m0, s34
	v_lshl_add_u64 v[242:243], s[6:7], 0, v[134:135]
	global_load_lds_dwordx4 v[240:241], off
	v_lshl_add_u64 v[240:241], s[30:31], 0, v[136:137]
	s_add_i32 m0, s34, 0x2000
	s_nop 0
	global_load_lds_dwordx4 v[240:241], off
	v_lshl_add_u64 v[240:241], s[6:7], 0, v[130:131]
	s_mov_b32 m0, s16
	s_nop 0
	global_load_lds_dwordx4 v[240:241], off
	s_mov_b32 m0, s17
	s_nop 0
	global_load_lds_dwordx4 v[242:243], off
	s_waitcnt vmcnt(8)
	s_waitcnt lgkmcnt(0)
	s_setprio 1
	s_barrier
; #define PG8_STAGE(bufoff, gbase, voff) do { _Pragma("unroll") for (int _i = 0; _i < 2; ++_i) \
;         __builtin_amdgcn_global_load_lds((const unsigned*)((const char*)(gbase) + (voff)[_i]), (LAS unsigned*)(lds + (bufoff) + ldsw + _i * 8192), 16, 0, 0); } while (0)
; #define PG8_LDA(dst, b, h) do { _Pragma("unroll") for (int m = 0; m < 4; ++m) _Pragma("unroll") for (int k = 0; k < 2; ++k) dst[m][k] = *(const LAS bf16x8*)(lds + PG8_SA(b, h) + aoff + m * 2048 + k * 1024); } while (0)
; #define PG8_LDB(dst, b, h) do { _Pragma("unroll") for (int n = 0; n < 2; ++n) _Pragma("unroll") for (int k = 0; k < 2; ++k) dst[n][k] = *(const LAS bf16x8*)(lds + PG8_SB(b, h) + boff + n * 2048 + k * 1024); } while (0)
; #define PG8_MMA(ai, bj, At, Bt) do { __builtin_amdgcn_s_setprio(1); _Pragma("unroll") for (int m = 0; m < 4; ++m) _Pragma("unroll") for (int n = 0; n < 2; ++n) _Pragma("unroll") for (int k = 0; k < 2; ++k) \
;         acc[ai][bj][m][n] = __builtin_amdgcn_mfma_f32_16x16x32_bf16(Bt[n][k], At[m][k], acc[ai][bj][m][n], 0, 0, 0); __builtin_amdgcn_s_setprio(0); } while (0)
; #define PG8_WAIT_V(n) asm volatile("s_waitcnt vmcnt(" #n ")" ::: "memory")
; #define PG8_WAIT_L(n) asm volatile("s_waitcnt lgkmcnt(" #n ")" ::: "memory")
; #define PG8_BAR __builtin_amdgcn_s_barrier()
; #define PG8_SCHED __builtin_amdgcn_sched_barrier(0)
; template <class Epi, class Order = StaticOrder, bool HALFN = false>
; __device__ __forceinline__ void gemm_phase(LAS unsigned char* lds, const Gemm g, const Epi& E) {
;     ...
;             PG8_WAIT_V(8); PG8_WAIT_L(0); PG8_BAR; PG8_MMA(1, 0, At, B0); if constexpr (!HALFN) PG8_MMA(1, 1, At, B1); PG8_BAR; PG8_SCHED;
;             PG8_LDB(B0, 1, 0); if constexpr (!HALFN) PG8_LDB(B1, 1, 1); PG8_SCHED; PG8_LDA(At, 1, 0); PG8_STAGE(PG8_SA(0, 1), a2 + hstepA, voffA);
;             PG8_WAIT_V(8); PG8_WAIT_L(0); PG8_BAR; PG8_MMA(0, 0, At, B0); if constexpr (!HALFN) PG8_MMA(0, 1, At, B1); PG8_BAR; PG8_SCHED;
;             PG8_LDA(At, 1, 1); PG8_STAGE(PG8_SB(1, 0), b3, voffB); PG8_STAGE(PG8_SB(1, 1), b3 + hstepB, voffB); PG8_STAGE(PG8_SA(1, 0), a3, voffA);
;             PG8_WAIT_V(8); PG8_WAIT_L(0); PG8_BAR; PG8_MMA(1, 0, At, B0); if constexpr (!HALFN) PG8_MMA(1, 1, At, B1); PG8_BAR; PG8_SCHED;
	v_mfma_f32_16x16x32_bf16 v[62:65], v[146:149], v[184:187], v[62:65]
	v_mfma_f32_16x16x32_bf16 v[70:73], v[154:157], v[184:187], v[70:73]
	v_mfma_f32_16x16x32_bf16 v[82:85], v[146:149], v[212:215], v[82:85]
	v_mfma_f32_16x16x32_bf16 v[86:89], v[154:157], v[212:215], v[86:89]
	v_mfma_f32_16x16x32_bf16 v[90:93], v[146:149], v[220:223], v[90:93]
	v_mfma_f32_16x16x32_bf16 v[94:97], v[154:157], v[220:223], v[94:97]
	v_mfma_f32_16x16x32_bf16 v[98:101], v[146:149], v[228:231], v[98:101]
	v_mfma_f32_16x16x32_bf16 v[106:109], v[154:157], v[228:231], v[106:109]
	v_mfma_f32_16x16x32_bf16 v[62:65], v[150:153], v[208:211], v[62:65]
	v_mfma_f32_16x16x32_bf16 v[70:73], v[158:161], v[208:211], v[70:73]
	v_mfma_f32_16x16x32_bf16 v[82:85], v[150:153], v[216:219], v[82:85]
	v_mfma_f32_16x16x32_bf16 v[86:89], v[158:161], v[216:219], v[86:89]
	v_mfma_f32_16x16x32_bf16 v[90:93], v[150:153], v[224:227], v[90:93]
	v_mfma_f32_16x16x32_bf16 v[94:97], v[158:161], v[224:227], v[94:97]
	v_mfma_f32_16x16x32_bf16 v[98:101], v[150:153], v[232:235], v[98:101]
	v_mfma_f32_16x16x32_bf16 v[106:109], v[158:161], v[232:235], v[106:109]
	v_mfma_f32_16x16x32_bf16 v[74:77], v[168:171], v[184:187], v[74:77]
	v_mfma_f32_16x16x32_bf16 v[78:81], v[176:179], v[184:187], v[78:81]
	v_mfma_f32_16x16x32_bf16 v[102:105], v[168:171], v[212:215], v[102:105]
	v_mfma_f32_16x16x32_bf16 v[110:113], v[176:179], v[212:215], v[110:113]
	v_mfma_f32_16x16x32_bf16 v[114:117], v[168:171], v[220:223], v[114:117]
	v_mfma_f32_16x16x32_bf16 v[118:121], v[176:179], v[220:223], v[118:121]
	v_mfma_f32_16x16x32_bf16 v[122:125], v[168:171], v[228:231], v[122:125]
	v_mfma_f32_16x16x32_bf16 v[126:129], v[176:179], v[228:231], v[126:129]
	v_mfma_f32_16x16x32_bf16 v[74:77], v[172:175], v[208:211], v[74:77]
	v_mfma_f32_16x16x32_bf16 v[78:81], v[180:183], v[208:211], v[78:81]
	v_mfma_f32_16x16x32_bf16 v[102:105], v[172:175], v[216:219], v[102:105]
	v_mfma_f32_16x16x32_bf16 v[110:113], v[180:183], v[216:219], v[110:113]
	v_mfma_f32_16x16x32_bf16 v[114:117], v[172:175], v[224:227], v[114:117]
	v_mfma_f32_16x16x32_bf16 v[118:121], v[180:183], v[224:227], v[118:121]
	v_mfma_f32_16x16x32_bf16 v[122:125], v[172:175], v[232:235], v[122:125]
	v_mfma_f32_16x16x32_bf16 v[126:129], v[180:183], v[232:235], v[126:129]
	s_barrier
	s_setprio 0
	s_add_i32 s30, 0, 0x18000
	v_add_u32_e32 v145, s30, v143
	s_add_i32 s31, 0, 0x1c000
	ds_read_b128 v[146:149], v145
	ds_read_b128 v[150:153], v145 offset:1024
	ds_read_b128 v[154:157], v145 offset:2048
	ds_read_b128 v[158:161], v145 offset:3072
	v_add_u32_e32 v145, s31, v143
	ds_read_b128 v[168:171], v145
	ds_read_b128 v[172:175], v145 offset:1024
	ds_read_b128 v[176:179], v145 offset:2048
	ds_read_b128 v[180:183], v145 offset:3072
	s_add_u32 s6, s6, 0x80000
	s_addc_u32 s7, s7, 0
	s_mov_b32 m0, s18
	v_lshl_add_u64 v[244:245], s[6:7], 0, v[130:131]
	ds_read_b128 v[184:187], v144 offset:32768
	ds_read_b128 v[208:211], v144 offset:33792
	ds_read_b128 v[212:215], v144 offset:34816
	ds_read_b128 v[216:219], v144 offset:35840
	ds_read_b128 v[220:223], v144 offset:36864
	ds_read_b128 v[224:227], v144 offset:37888
	ds_read_b128 v[228:231], v144 offset:38912
	ds_read_b128 v[232:235], v144 offset:39936
	global_load_lds_dwordx4 v[244:245], off
	v_lshl_add_u64 v[244:245], s[6:7], 0, v[134:135]
	s_mov_b32 m0, s19
	s_nop 0
	global_load_lds_dwordx4 v[244:245], off
	s_waitcnt vmcnt(8)
	s_waitcnt lgkmcnt(0)
	s_setprio 1
	s_barrier
	v_mfma_f32_16x16x32_bf16 v[2:5], v[146:149], v[184:187], v[2:5]
	v_mfma_f32_16x16x32_bf16 v[6:9], v[154:157], v[184:187], v[6:9]
	v_mfma_f32_16x16x32_bf16 v[10:13], v[146:149], v[212:215], v[10:13]
	v_mfma_f32_16x16x32_bf16 v[14:17], v[154:157], v[212:215], v[14:17]
	v_mfma_f32_16x16x32_bf16 v[18:21], v[146:149], v[220:223], v[18:21]
	v_mfma_f32_16x16x32_bf16 v[26:29], v[154:157], v[220:223], v[26:29]
	v_mfma_f32_16x16x32_bf16 v[30:33], v[146:149], v[228:231], v[30:33]
	v_mfma_f32_16x16x32_bf16 v[42:45], v[154:157], v[228:231], v[42:45]
	v_mfma_f32_16x16x32_bf16 v[2:5], v[150:153], v[208:211], v[2:5]
	v_mfma_f32_16x16x32_bf16 v[6:9], v[158:161], v[208:211], v[6:9]
	v_mfma_f32_16x16x32_bf16 v[10:13], v[150:153], v[216:219], v[10:13]
	v_mfma_f32_16x16x32_bf16 v[14:17], v[158:161], v[216:219], v[14:17]
	v_mfma_f32_16x16x32_bf16 v[18:21], v[150:153], v[224:227], v[18:21]
	v_mfma_f32_16x16x32_bf16 v[26:29], v[158:161], v[224:227], v[26:29]
	v_mfma_f32_16x16x32_bf16 v[30:33], v[150:153], v[232:235], v[30:33]
	v_mfma_f32_16x16x32_bf16 v[42:45], v[158:161], v[232:235], v[42:45]
	v_mfma_f32_16x16x32_bf16 v[22:25], v[168:171], v[184:187], v[22:25]
	v_mfma_f32_16x16x32_bf16 v[34:37], v[176:179], v[184:187], v[34:37]
	v_mfma_f32_16x16x32_bf16 v[38:41], v[168:171], v[212:215], v[38:41]
	v_mfma_f32_16x16x32_bf16 v[46:49], v[176:179], v[212:215], v[46:49]
	v_mfma_f32_16x16x32_bf16 v[50:53], v[168:171], v[220:223], v[50:53]
	v_mfma_f32_16x16x32_bf16 v[54:57], v[176:179], v[220:223], v[54:57]
	v_mfma_f32_16x16x32_bf16 v[58:61], v[168:171], v[228:231], v[58:61]
	v_mfma_f32_16x16x32_bf16 v[66:69], v[176:179], v[228:231], v[66:69]
	v_mfma_f32_16x16x32_bf16 v[22:25], v[172:175], v[208:211], v[22:25]
	v_mfma_f32_16x16x32_bf16 v[34:37], v[180:183], v[208:211], v[34:37]
	v_mfma_f32_16x16x32_bf16 v[38:41], v[172:175], v[216:219], v[38:41]
	v_mfma_f32_16x16x32_bf16 v[46:49], v[180:183], v[216:219], v[46:49]
	v_mfma_f32_16x16x32_bf16 v[50:53], v[172:175], v[224:227], v[50:53]
	v_mfma_f32_16x16x32_bf16 v[54:57], v[180:183], v[224:227], v[54:57]
	v_mfma_f32_16x16x32_bf16 v[58:61], v[172:175], v[232:235], v[58:61]
	v_mfma_f32_16x16x32_bf16 v[66:69], v[180:183], v[232:235], v[66:69]
	s_barrier
; #define PG8_STAGE(bufoff, gbase, voff) do { _Pragma("unroll") for (int _i = 0; _i < 2; ++_i) \
;         __builtin_amdgcn_global_load_lds((const unsigned*)((const char*)(gbase) + (voff)[_i]), (LAS unsigned*)(lds + (bufoff) + ldsw + _i * 8192), 16, 0, 0); } while (0)
; #define PG8_LDA(dst, b, h) do { _Pragma("unroll") for (int m = 0; m < 4; ++m) _Pragma("unroll") for (int k = 0; k < 2; ++k) dst[m][k] = *(const LAS bf16x8*)(lds + PG8_SA(b, h) + aoff + m * 2048 + k * 1024); } while (0)
; #define PG8_MMA(ai, bj, At, Bt) do { __builtin_amdgcn_s_setprio(1); _Pragma("unroll") for (int m = 0; m < 4; ++m) _Pragma("unroll") for (int n = 0; n < 2; ++n) _Pragma("unroll") for (int k = 0; k < 2; ++k) \
;         acc[ai][bj][m][n] = __builtin_amdgcn_mfma_f32_16x16x32_bf16(Bt[n][k], At[m][k], acc[ai][bj][m][n], 0, 0, 0); __builtin_amdgcn_s_setprio(0); } while (0)
; #define PG8_WAIT_V(n) asm volatile("s_waitcnt vmcnt(" #n ")" ::: "memory")
; #define PG8_WAIT_L(n) asm volatile("s_waitcnt lgkmcnt(" #n ")" ::: "memory")
; #define PG8_BAR __builtin_amdgcn_s_barrier()
; #define PG8_SCHED __builtin_amdgcn_sched_barrier(0)
; template <class Epi, class Order = StaticOrder, bool HALFN = false>
; __device__ __forceinline__ void gemm_phase(LAS unsigned char* lds, const Gemm g, const Epi& E) {
;     ...
;             PG8_LDA(At, 1, 1); PG8_STAGE(PG8_SB(1, 0), b3, voffB); PG8_STAGE(PG8_SB(1, 1), b3 + hstepB, voffB); PG8_STAGE(PG8_SA(1, 0), a3, voffA);
;             PG8_WAIT_V(8); PG8_WAIT_L(0); PG8_BAR; PG8_MMA(1, 0, At, B0); if constexpr (!HALFN) PG8_MMA(1, 1, At, B1); PG8_BAR; PG8_SCHED;
;         }
;         if (wr == 0) PG8_BAR;
	s_setprio 0
	s_add_i32 s6, s30, s10
	v_lshl_add_u64 v[236:237], v[236:237], 0, s[60:61]
	s_mov_b32 m0, s6
	ds_read_b128 v[184:187], v144 offset:49152
	ds_read_b128 v[208:211], v144 offset:50176
	ds_read_b128 v[212:215], v144 offset:51200
	ds_read_b128 v[216:219], v144 offset:52224
	ds_read_b128 v[220:223], v144 offset:53248
	ds_read_b128 v[224:227], v144 offset:54272
	ds_read_b128 v[228:231], v144 offset:55296
	ds_read_b128 v[232:235], v144 offset:56320
	global_load_lds_dwordx4 v[236:237], off
	s_add_i32 m0, s6, 0x2000
	s_add_u32 s4, s4, 0x80080
	v_lshl_add_u64 v[236:237], v[238:239], 0, s[60:61]
	s_addc_u32 s5, s5, 0
	s_add_i32 s6, s31, s10
	global_load_lds_dwordx4 v[236:237], off
	v_lshl_add_u64 v[236:237], s[4:5], 0, v[132:133]
	s_mov_b32 m0, s6
	s_nop 0
	global_load_lds_dwordx4 v[236:237], off
	v_lshl_add_u64 v[236:237], s[4:5], 0, v[136:137]
	s_add_i32 m0, s6, 0x2000
	s_nop 0
	global_load_lds_dwordx4 v[236:237], off
	v_lshl_add_u64 v[236:237], v[240:241], 0, s[60:61]
	s_mov_b32 m0, s20
	s_nop 0
	global_load_lds_dwordx4 v[236:237], off
	v_lshl_add_u64 v[236:237], v[242:243], 0, s[60:61]
	s_mov_b32 m0, s21
	s_nop 0
	global_load_lds_dwordx4 v[236:237], off
	s_waitcnt vmcnt(8)
	s_waitcnt lgkmcnt(0)
	s_setprio 1
	s_barrier
	v_mfma_f32_16x16x32_bf16 v[62:65], v[146:149], v[184:187], v[62:65]
	v_mfma_f32_16x16x32_bf16 v[70:73], v[154:157], v[184:187], v[70:73]
	v_mfma_f32_16x16x32_bf16 v[82:85], v[146:149], v[212:215], v[82:85]
	v_mfma_f32_16x16x32_bf16 v[86:89], v[154:157], v[212:215], v[86:89]
	v_mfma_f32_16x16x32_bf16 v[90:93], v[146:149], v[220:223], v[90:93]
	v_mfma_f32_16x16x32_bf16 v[94:97], v[154:157], v[220:223], v[94:97]
	v_mfma_f32_16x16x32_bf16 v[98:101], v[146:149], v[228:231], v[98:101]
	v_mfma_f32_16x16x32_bf16 v[106:109], v[154:157], v[228:231], v[106:109]
	v_mfma_f32_16x16x32_bf16 v[62:65], v[150:153], v[208:211], v[62:65]
	v_mfma_f32_16x16x32_bf16 v[70:73], v[158:161], v[208:211], v[70:73]
	v_mfma_f32_16x16x32_bf16 v[82:85], v[150:153], v[216:219], v[82:85]
	v_mfma_f32_16x16x32_bf16 v[86:89], v[158:161], v[216:219], v[86:89]
	v_mfma_f32_16x16x32_bf16 v[90:93], v[150:153], v[224:227], v[90:93]
	v_mfma_f32_16x16x32_bf16 v[94:97], v[158:161], v[224:227], v[94:97]
	v_mfma_f32_16x16x32_bf16 v[98:101], v[150:153], v[232:235], v[98:101]
	v_mfma_f32_16x16x32_bf16 v[106:109], v[158:161], v[232:235], v[106:109]
	v_mfma_f32_16x16x32_bf16 v[74:77], v[168:171], v[184:187], v[74:77]
	v_mfma_f32_16x16x32_bf16 v[78:81], v[176:179], v[184:187], v[78:81]
	v_mfma_f32_16x16x32_bf16 v[102:105], v[168:171], v[212:215], v[102:105]
	v_mfma_f32_16x16x32_bf16 v[110:113], v[176:179], v[212:215], v[110:113]
	v_mfma_f32_16x16x32_bf16 v[114:117], v[168:171], v[220:223], v[114:117]
	v_mfma_f32_16x16x32_bf16 v[118:121], v[176:179], v[220:223], v[118:121]
	v_mfma_f32_16x16x32_bf16 v[122:125], v[168:171], v[228:231], v[122:125]
	v_mfma_f32_16x16x32_bf16 v[126:129], v[176:179], v[228:231], v[126:129]
	v_mfma_f32_16x16x32_bf16 v[74:77], v[172:175], v[208:211], v[74:77]
	v_mfma_f32_16x16x32_bf16 v[78:81], v[180:183], v[208:211], v[78:81]
	v_mfma_f32_16x16x32_bf16 v[102:105], v[172:175], v[216:219], v[102:105]
	v_mfma_f32_16x16x32_bf16 v[110:113], v[180:183], v[216:219], v[110:113]
	v_mfma_f32_16x16x32_bf16 v[114:117], v[172:175], v[224:227], v[114:117]
	v_mfma_f32_16x16x32_bf16 v[118:121], v[180:183], v[224:227], v[118:121]
	v_mfma_f32_16x16x32_bf16 v[122:125], v[172:175], v[232:235], v[122:125]
	v_mfma_f32_16x16x32_bf16 v[126:129], v[180:183], v[232:235], v[126:129]
	s_barrier
	s_setprio 0
	s_add_i32 s29, s29, 2
	s_add_u32 s62, s62, 0x100
	s_addc_u32 s63, s63, 0
	s_add_u32 s27, s27, 0x100
	s_addc_u32 s28, s28, 0
	s_cmp_gt_u32 s29, 29
	s_cbranch_scc0 .LBB0_709
	s_and_b64 vcc, exec, s[44:45]
	s_cbranch_vccz .LBB0_712
	s_barrier

; #define PG8_STAGE(bufoff, gbase, voff) do { _Pragma("unroll") for (int _i = 0; _i < 2; ++_i) \
;         __builtin_amdgcn_global_load_lds((const unsigned*)((const char*)(gbase) + (voff)[_i]), (LAS unsigned*)(lds + (bufoff) + ldsw + _i * 8192), 16, 0, 0); } while (0)
; #define PG8_LDA(dst, b, h) do { _Pragma("unroll") for (int m = 0; m < 4; ++m) _Pragma("unroll") for (int k = 0; k < 2; ++k) dst[m][k] = *(const LAS bf16x8*)(lds + PG8_SA(b, h) + aoff + m * 2048 + k * 1024); } while (0)
; #define PG8_LDB(dst, b, h) do { _Pragma("unroll") for (int n = 0; n < 2; ++n) _Pragma("unroll") for (int k = 0; k < 2; ++k) dst[n][k] = *(const LAS bf16x8*)(lds + PG8_SB(b, h) + boff + n * 2048 + k * 1024); } while (0)
; #define PG8_MMA(ai, bj, At, Bt) do { __builtin_amdgcn_s_setprio(1); _Pragma("unroll") for (int m = 0; m < 4; ++m) _Pragma("unroll") for (int n = 0; n < 2; ++n) _Pragma("unroll") for (int k = 0; k < 2; ++k) \
;         acc[ai][bj][m][n] = __builtin_amdgcn_mfma_f32_16x16x32_bf16(Bt[n][k], At[m][k], acc[ai][bj][m][n], 0, 0, 0); __builtin_amdgcn_s_setprio(0); } while (0)
; #define PG8_WAIT_V(n) asm volatile("s_waitcnt vmcnt(" #n ")" ::: "memory")
; #define PG8_WAIT_L(n) asm volatile("s_waitcnt lgkmcnt(" #n ")" ::: "memory")
; #define PG8_BAR __builtin_amdgcn_s_barrier()
; #define PG8_SCHED __builtin_amdgcn_sched_barrier(0)
; template <class Epi, class Order = StaticOrder, bool HALFN = false>
; __device__ __forceinline__ void gemm_phase(LAS unsigned char* lds, const Gemm g, const Epi& E) {
;     ...
;             const char* a1 = cA + (size_t)(t + 1) * kstep;
;             const char* a2 = last ? nA : cA + (size_t)(t + 2) * kstep; const char* b2 = last ? nB : cB + (size_t)(t + 2) * kstep;
;             const char* a3 = a2 + kstep; const char* b3 = b2 + kstep;
;             PG8_LDB(B0, 0, 0); if constexpr (!HALFN) PG8_LDB(B1, 0, 1); PG8_SCHED; PG8_LDA(At, 0, 0); PG8_STAGE(PG8_SA(1, 1), a1 + hstepA, voffA);
;             PG8_WAIT_V(8); PG8_WAIT_L(0); PG8_BAR; PG8_MMA(0, 0, At, B0); if constexpr (!HALFN) PG8_MMA(0, 1, At, B1); PG8_BAR; PG8_SCHED;
;             PG8_LDA(At, 0, 1); PG8_STAGE(PG8_SB(0, 0), b2, voffB); PG8_STAGE(PG8_SB(0, 1), b2 + hstepB, voffB); PG8_STAGE(PG8_SA(0, 0), a2, voffA);
;             PG8_WAIT_V(8); PG8_WAIT_L(0); PG8_BAR; PG8_MMA(1, 0, At, B0); if constexpr (!HALFN) PG8_MMA(1, 1, At, B1); PG8_BAR; PG8_SCHED;
.LBB0_799:
	s_add_u32 s4, s62, 0xfff80080
	s_addc_u32 s5, s63, -1
	s_add_i32 s30, 0, 0x10000
	s_cmp_eq_u32 s29, 28
	s_cselect_b32 s7, s23, s5
	s_cselect_b32 s6, s24, s4
	s_cselect_b32 s5, s25, s28
	s_cselect_b32 s4, s26, s27
	s_add_i32 s34, 0, 0x14000
	v_add_u32_e32 v142, s30, v209
	v_add_u32_e32 v158, s34, v209
	ds_read_b128 v[122:125], v142
	ds_read_b128 v[130:133], v142 offset:1024
	ds_read_b128 v[138:141], v142 offset:2048
	ds_read_b128 v[142:145], v142 offset:3072
	ds_read_b128 v[146:149], v158
	ds_read_b128 v[150:153], v158 offset:1024
	ds_read_b128 v[154:157], v158 offset:2048
	ds_read_b128 v[158:161], v158 offset:3072
	v_lshl_add_u64 v[236:237], s[62:63], 0, v[176:177]
	s_add_i32 m0, s11, 0xc000
	ds_read_b128 v[180:183], v210
	ds_read_b128 v[184:187], v210 offset:1024
	ds_read_b128 v[212:215], v210 offset:2048
	ds_read_b128 v[216:219], v210 offset:3072
	ds_read_b128 v[220:223], v210 offset:4096
	ds_read_b128 v[224:227], v210 offset:5120
	ds_read_b128 v[228:231], v210 offset:6144
	ds_read_b128 v[232:235], v210 offset:7168
	global_load_lds_dwordx4 v[236:237], off
	v_lshl_add_u64 v[236:237], s[62:63], 0, v[178:179]
	s_add_i32 m0, s11, 0xe000
	s_nop 0
	global_load_lds_dwordx4 v[236:237], off
	s_waitcnt vmcnt(8)
	s_waitcnt lgkmcnt(0)
	s_setprio 1
	s_barrier
	v_mfma_f32_16x16x32_bf16 v[134:137], v[122:125], v[180:183], v[134:137]
	v_mfma_f32_16x16x32_bf16 v[126:129], v[138:141], v[180:183], v[126:129]
	v_mfma_f32_16x16x32_bf16 v[110:113], v[122:125], v[212:215], v[110:113]
	v_mfma_f32_16x16x32_bf16 v[106:109], v[138:141], v[212:215], v[106:109]
	v_mfma_f32_16x16x32_bf16 v[94:97], v[122:125], v[220:223], v[94:97]
	v_mfma_f32_16x16x32_bf16 v[90:93], v[138:141], v[220:223], v[90:93]
	v_mfma_f32_16x16x32_bf16 v[78:81], v[122:125], v[228:231], v[78:81]
	v_mfma_f32_16x16x32_bf16 v[74:77], v[138:141], v[228:231], v[74:77]
	v_mfma_f32_16x16x32_bf16 v[134:137], v[130:133], v[184:187], v[134:137]
	v_mfma_f32_16x16x32_bf16 v[126:129], v[142:145], v[184:187], v[126:129]
	v_mfma_f32_16x16x32_bf16 v[110:113], v[130:133], v[216:219], v[110:113]
	v_mfma_f32_16x16x32_bf16 v[106:109], v[142:145], v[216:219], v[106:109]
	v_mfma_f32_16x16x32_bf16 v[94:97], v[130:133], v[224:227], v[94:97]
	v_mfma_f32_16x16x32_bf16 v[90:93], v[142:145], v[224:227], v[90:93]
	v_mfma_f32_16x16x32_bf16 v[78:81], v[130:133], v[232:235], v[78:81]
	v_mfma_f32_16x16x32_bf16 v[74:77], v[142:145], v[232:235], v[74:77]
	v_mfma_f32_16x16x32_bf16 v[118:121], v[146:149], v[180:183], v[118:121]
	v_mfma_f32_16x16x32_bf16 v[114:117], v[154:157], v[180:183], v[114:117]
	v_mfma_f32_16x16x32_bf16 v[102:105], v[146:149], v[212:215], v[102:105]
	v_mfma_f32_16x16x32_bf16 v[98:101], v[154:157], v[212:215], v[98:101]
	v_mfma_f32_16x16x32_bf16 v[86:89], v[146:149], v[220:223], v[86:89]
	v_mfma_f32_16x16x32_bf16 v[82:85], v[154:157], v[220:223], v[82:85]
	v_mfma_f32_16x16x32_bf16 v[70:73], v[146:149], v[228:231], v[70:73]
	v_mfma_f32_16x16x32_bf16 v[66:69], v[154:157], v[228:231], v[66:69]
	v_mfma_f32_16x16x32_bf16 v[118:121], v[150:153], v[184:187], v[118:121]
	v_mfma_f32_16x16x32_bf16 v[114:117], v[158:161], v[184:187], v[114:117]
	v_mfma_f32_16x16x32_bf16 v[102:105], v[150:153], v[216:219], v[102:105]
	v_mfma_f32_16x16x32_bf16 v[98:101], v[158:161], v[216:219], v[98:101]
	v_mfma_f32_16x16x32_bf16 v[86:89], v[150:153], v[224:227], v[86:89]
	v_mfma_f32_16x16x32_bf16 v[82:85], v[158:161], v[224:227], v[82:85]
	v_mfma_f32_16x16x32_bf16 v[70:73], v[150:153], v[232:235], v[70:73]
	v_mfma_f32_16x16x32_bf16 v[66:69], v[158:161], v[232:235], v[66:69]
	s_barrier
	s_setprio 0
	s_add_i32 s30, s30, s10
	v_lshl_add_u64 v[236:237], s[4:5], 0, v[170:171]
	s_mov_b32 m0, s30
	ds_read_b128 v[180:183], v210 offset:16384
	ds_read_b128 v[184:187], v210 offset:17408
	ds_read_b128 v[212:215], v210 offset:18432
	ds_read_b128 v[216:219], v210 offset:19456
	ds_read_b128 v[220:223], v210 offset:20480
	ds_read_b128 v[224:227], v210 offset:21504
	ds_read_b128 v[228:231], v210 offset:22528
	ds_read_b128 v[232:235], v210 offset:23552
	global_load_lds_dwordx4 v[236:237], off
	s_add_i32 m0, s30, 0x2000
	s_add_u32 s30, s4, 0x80000
	v_lshl_add_u64 v[238:239], s[4:5], 0, v[174:175]
	s_addc_u32 s31, s5, 0
	s_add_i32 s34, s34, s10
	global_load_lds_dwordx4 v[238:239], off
	v_lshl_add_u64 v[240:241], s[30:31], 0, v[170:171]
	s_mov_b32 m0, s34
	v_lshl_add_u64 v[242:243], s[6:7], 0, v[172:173]
	global_load_lds_dwordx4 v[240:241], off
	v_lshl_add_u64 v[240:241], s[30:31], 0, v[174:175]
	s_add_i32 m0, s34, 0x2000
	s_nop 0
	global_load_lds_dwordx4 v[240:241], off
	v_lshl_add_u64 v[240:241], s[6:7], 0, v[168:169]
	s_mov_b32 m0, s11
	s_nop 0
	global_load_lds_dwordx4 v[240:241], off
	s_mov_b32 m0, s15
	s_nop 0
	global_load_lds_dwordx4 v[242:243], off
	s_waitcnt vmcnt(8)
	s_waitcnt lgkmcnt(0)
	s_setprio 1
	s_barrier
; #define PG8_STAGE(bufoff, gbase, voff) do { _Pragma("unroll") for (int _i = 0; _i < 2; ++_i) \
;         __builtin_amdgcn_global_load_lds((const unsigned*)((const char*)(gbase) + (voff)[_i]), (LAS unsigned*)(lds + (bufoff) + ldsw + _i * 8192), 16, 0, 0); } while (0)
; #define PG8_LDA(dst, b, h) do { _Pragma("unroll") for (int m = 0; m < 4; ++m) _Pragma("unroll") for (int k = 0; k < 2; ++k) dst[m][k] = *(const LAS bf16x8*)(lds + PG8_SA(b, h) + aoff + m * 2048 + k * 1024); } while (0)
; #define PG8_LDB(dst, b, h) do { _Pragma("unroll") for (int n = 0; n < 2; ++n) _Pragma("unroll") for (int k = 0; k < 2; ++k) dst[n][k] = *(const LAS bf16x8*)(lds + PG8_SB(b, h) + boff + n * 2048 + k * 1024); } while (0)
; #define PG8_MMA(ai, bj, At, Bt) do { __builtin_amdgcn_s_setprio(1); _Pragma("unroll") for (int m = 0; m < 4; ++m) _Pragma("unroll") for (int n = 0; n < 2; ++n) _Pragma("unroll") for (int k = 0; k < 2; ++k) \
;         acc[ai][bj][m][n] = __builtin_amdgcn_mfma_f32_16x16x32_bf16(Bt[n][k], At[m][k], acc[ai][bj][m][n], 0, 0, 0); __builtin_amdgcn_s_setprio(0); } while (0)
; #define PG8_WAIT_V(n) asm volatile("s_waitcnt vmcnt(" #n ")" ::: "memory")
; #define PG8_WAIT_L(n) asm volatile("s_waitcnt lgkmcnt(" #n ")" ::: "memory")
; #define PG8_BAR __builtin_amdgcn_s_barrier()
; #define PG8_SCHED __builtin_amdgcn_sched_barrier(0)
; template <class Epi, class Order = StaticOrder, bool HALFN = false>
; __device__ __forceinline__ void gemm_phase(LAS unsigned char* lds, const Gemm g, const Epi& E) {
;     ...
;             PG8_WAIT_V(8); PG8_WAIT_L(0); PG8_BAR; PG8_MMA(1, 0, At, B0); if constexpr (!HALFN) PG8_MMA(1, 1, At, B1); PG8_BAR; PG8_SCHED;
;             PG8_LDB(B0, 1, 0); if constexpr (!HALFN) PG8_LDB(B1, 1, 1); PG8_SCHED; PG8_LDA(At, 1, 0); PG8_STAGE(PG8_SA(0, 1), a2 + hstepA, voffA);
;             PG8_WAIT_V(8); PG8_WAIT_L(0); PG8_BAR; PG8_MMA(0, 0, At, B0); if constexpr (!HALFN) PG8_MMA(0, 1, At, B1); PG8_BAR; PG8_SCHED;
;             PG8_LDA(At, 1, 1); PG8_STAGE(PG8_SB(1, 0), b3, voffB); PG8_STAGE(PG8_SB(1, 1), b3 + hstepB, voffB); PG8_STAGE(PG8_SA(1, 0), a3, voffA);
;             PG8_WAIT_V(8); PG8_WAIT_L(0); PG8_BAR; PG8_MMA(1, 0, At, B0); if constexpr (!HALFN) PG8_MMA(1, 1, At, B1); PG8_BAR; PG8_SCHED;
	v_mfma_f32_16x16x32_bf16 v[62:65], v[122:125], v[180:183], v[62:65]
	v_mfma_f32_16x16x32_bf16 v[58:61], v[138:141], v[180:183], v[58:61]
	v_mfma_f32_16x16x32_bf16 v[46:49], v[122:125], v[212:215], v[46:49]
	v_mfma_f32_16x16x32_bf16 v[42:45], v[138:141], v[212:215], v[42:45]
	v_mfma_f32_16x16x32_bf16 v[30:33], v[122:125], v[220:223], v[30:33]
	v_mfma_f32_16x16x32_bf16 v[26:29], v[138:141], v[220:223], v[26:29]
	v_mfma_f32_16x16x32_bf16 v[14:17], v[122:125], v[228:231], v[14:17]
	v_mfma_f32_16x16x32_bf16 v[10:13], v[138:141], v[228:231], v[10:13]
	v_mfma_f32_16x16x32_bf16 v[62:65], v[130:133], v[184:187], v[62:65]
	v_mfma_f32_16x16x32_bf16 v[58:61], v[142:145], v[184:187], v[58:61]
	v_mfma_f32_16x16x32_bf16 v[46:49], v[130:133], v[216:219], v[46:49]
	v_mfma_f32_16x16x32_bf16 v[42:45], v[142:145], v[216:219], v[42:45]
	v_mfma_f32_16x16x32_bf16 v[30:33], v[130:133], v[224:227], v[30:33]
	v_mfma_f32_16x16x32_bf16 v[26:29], v[142:145], v[224:227], v[26:29]
	v_mfma_f32_16x16x32_bf16 v[14:17], v[130:133], v[232:235], v[14:17]
	v_mfma_f32_16x16x32_bf16 v[10:13], v[142:145], v[232:235], v[10:13]
	v_mfma_f32_16x16x32_bf16 v[54:57], v[146:149], v[180:183], v[54:57]
	v_mfma_f32_16x16x32_bf16 v[50:53], v[154:157], v[180:183], v[50:53]
	v_mfma_f32_16x16x32_bf16 v[38:41], v[146:149], v[212:215], v[38:41]
	v_mfma_f32_16x16x32_bf16 v[34:37], v[154:157], v[212:215], v[34:37]
	v_mfma_f32_16x16x32_bf16 v[22:25], v[146:149], v[220:223], v[22:25]
	v_mfma_f32_16x16x32_bf16 v[18:21], v[154:157], v[220:223], v[18:21]
	v_mfma_f32_16x16x32_bf16 v[6:9], v[146:149], v[228:231], v[6:9]
	v_mfma_f32_16x16x32_bf16 v[2:5], v[154:157], v[228:231], v[2:5]
	v_mfma_f32_16x16x32_bf16 v[54:57], v[150:153], v[184:187], v[54:57]
	v_mfma_f32_16x16x32_bf16 v[50:53], v[158:161], v[184:187], v[50:53]
	v_mfma_f32_16x16x32_bf16 v[38:41], v[150:153], v[216:219], v[38:41]
	v_mfma_f32_16x16x32_bf16 v[34:37], v[158:161], v[216:219], v[34:37]
	v_mfma_f32_16x16x32_bf16 v[22:25], v[150:153], v[224:227], v[22:25]
	v_mfma_f32_16x16x32_bf16 v[18:21], v[158:161], v[224:227], v[18:21]
	v_mfma_f32_16x16x32_bf16 v[6:9], v[150:153], v[232:235], v[6:9]
	v_mfma_f32_16x16x32_bf16 v[2:5], v[158:161], v[232:235], v[2:5]
	s_barrier
	s_setprio 0
	s_add_i32 s30, 0, 0x18000
	s_add_i32 s31, 0, 0x1c000
	v_add_u32_e32 v142, s30, v209
	v_add_u32_e32 v158, s31, v209
	ds_read_b128 v[122:125], v142
	ds_read_b128 v[130:133], v142 offset:1024
	ds_read_b128 v[138:141], v142 offset:2048
	ds_read_b128 v[142:145], v142 offset:3072
	ds_read_b128 v[146:149], v158
	ds_read_b128 v[150:153], v158 offset:1024
	ds_read_b128 v[154:157], v158 offset:2048
	ds_read_b128 v[158:161], v158 offset:3072
	s_add_u32 s6, s6, 0x80000
	s_addc_u32 s7, s7, 0
	s_mov_b32 m0, s16
	v_lshl_add_u64 v[244:245], s[6:7], 0, v[168:169]
	ds_read_b128 v[180:183], v210 offset:32768
	ds_read_b128 v[184:187], v210 offset:33792
	ds_read_b128 v[212:215], v210 offset:34816
	ds_read_b128 v[216:219], v210 offset:35840
	ds_read_b128 v[220:223], v210 offset:36864
	ds_read_b128 v[224:227], v210 offset:37888
	ds_read_b128 v[228:231], v210 offset:38912
	ds_read_b128 v[232:235], v210 offset:39936
	global_load_lds_dwordx4 v[244:245], off
	v_lshl_add_u64 v[244:245], s[6:7], 0, v[172:173]
	s_mov_b32 m0, s17
	s_nop 0
	global_load_lds_dwordx4 v[244:245], off
	s_waitcnt vmcnt(8)
	s_waitcnt lgkmcnt(0)
	s_setprio 1
	s_barrier
	v_mfma_f32_16x16x32_bf16 v[134:137], v[122:125], v[180:183], v[134:137]
	v_mfma_f32_16x16x32_bf16 v[126:129], v[138:141], v[180:183], v[126:129]
	v_mfma_f32_16x16x32_bf16 v[110:113], v[122:125], v[212:215], v[110:113]
	v_mfma_f32_16x16x32_bf16 v[106:109], v[138:141], v[212:215], v[106:109]
	v_mfma_f32_16x16x32_bf16 v[94:97], v[122:125], v[220:223], v[94:97]
	v_mfma_f32_16x16x32_bf16 v[90:93], v[138:141], v[220:223], v[90:93]
	v_mfma_f32_16x16x32_bf16 v[78:81], v[122:125], v[228:231], v[78:81]
	v_mfma_f32_16x16x32_bf16 v[74:77], v[138:141], v[228:231], v[74:77]
	v_mfma_f32_16x16x32_bf16 v[134:137], v[130:133], v[184:187], v[134:137]
	v_mfma_f32_16x16x32_bf16 v[126:129], v[142:145], v[184:187], v[126:129]
	v_mfma_f32_16x16x32_bf16 v[110:113], v[130:133], v[216:219], v[110:113]
	v_mfma_f32_16x16x32_bf16 v[106:109], v[142:145], v[216:219], v[106:109]
	v_mfma_f32_16x16x32_bf16 v[94:97], v[130:133], v[224:227], v[94:97]
	v_mfma_f32_16x16x32_bf16 v[90:93], v[142:145], v[224:227], v[90:93]
	v_mfma_f32_16x16x32_bf16 v[78:81], v[130:133], v[232:235], v[78:81]
	v_mfma_f32_16x16x32_bf16 v[74:77], v[142:145], v[232:235], v[74:77]
	v_mfma_f32_16x16x32_bf16 v[118:121], v[146:149], v[180:183], v[118:121]
	v_mfma_f32_16x16x32_bf16 v[114:117], v[154:157], v[180:183], v[114:117]
	v_mfma_f32_16x16x32_bf16 v[102:105], v[146:149], v[212:215], v[102:105]
	v_mfma_f32_16x16x32_bf16 v[98:101], v[154:157], v[212:215], v[98:101]
	v_mfma_f32_16x16x32_bf16 v[86:89], v[146:149], v[220:223], v[86:89]
	v_mfma_f32_16x16x32_bf16 v[82:85], v[154:157], v[220:223], v[82:85]
	v_mfma_f32_16x16x32_bf16 v[70:73], v[146:149], v[228:231], v[70:73]
	v_mfma_f32_16x16x32_bf16 v[66:69], v[154:157], v[228:231], v[66:69]
	v_mfma_f32_16x16x32_bf16 v[118:121], v[150:153], v[184:187], v[118:121]
	v_mfma_f32_16x16x32_bf16 v[114:117], v[158:161], v[184:187], v[114:117]
	v_mfma_f32_16x16x32_bf16 v[102:105], v[150:153], v[216:219], v[102:105]
	v_mfma_f32_16x16x32_bf16 v[98:101], v[158:161], v[216:219], v[98:101]
	v_mfma_f32_16x16x32_bf16 v[86:89], v[150:153], v[224:227], v[86:89]
	v_mfma_f32_16x16x32_bf16 v[82:85], v[158:161], v[224:227], v[82:85]
	v_mfma_f32_16x16x32_bf16 v[70:73], v[150:153], v[232:235], v[70:73]
	v_mfma_f32_16x16x32_bf16 v[66:69], v[158:161], v[232:235], v[66:69]
	s_barrier
; #define PG8_STAGE(bufoff, gbase, voff) do { _Pragma("unroll") for (int _i = 0; _i < 2; ++_i) \
;         __builtin_amdgcn_global_load_lds((const unsigned*)((const char*)(gbase) + (voff)[_i]), (LAS unsigned*)(lds + (bufoff) + ldsw + _i * 8192), 16, 0, 0); } while (0)
; #define PG8_LDA(dst, b, h) do { _Pragma("unroll") for (int m = 0; m < 4; ++m) _Pragma("unroll") for (int k = 0; k < 2; ++k) dst[m][k] = *(const LAS bf16x8*)(lds + PG8_SA(b, h) + aoff + m * 2048 + k * 1024); } while (0)
; #define PG8_MMA(ai, bj, At, Bt) do { __builtin_amdgcn_s_setprio(1); _Pragma("unroll") for (int m = 0; m < 4; ++m) _Pragma("unroll") for (int n = 0; n < 2; ++n) _Pragma("unroll") for (int k = 0; k < 2; ++k) \
;         acc[ai][bj][m][n] = __builtin_amdgcn_mfma_f32_16x16x32_bf16(Bt[n][k], At[m][k], acc[ai][bj][m][n], 0, 0, 0); __builtin_amdgcn_s_setprio(0); } while (0)
; #define PG8_WAIT_V(n) asm volatile("s_waitcnt vmcnt(" #n ")" ::: "memory")
; #define PG8_WAIT_L(n) asm volatile("s_waitcnt lgkmcnt(" #n ")" ::: "memory")
; #define PG8_BAR __builtin_amdgcn_s_barrier()
; #define PG8_SCHED __builtin_amdgcn_sched_barrier(0)
; template <class Epi, class Order = StaticOrder, bool HALFN = false>
; __device__ __forceinline__ void gemm_phase(LAS unsigned char* lds, const Gemm g, const Epi& E) {
;     ...
;             PG8_LDA(At, 1, 1); PG8_STAGE(PG8_SB(1, 0), b3, voffB); PG8_STAGE(PG8_SB(1, 1), b3 + hstepB, voffB); PG8_STAGE(PG8_SA(1, 0), a3, voffA);
;             PG8_WAIT_V(8); PG8_WAIT_L(0); PG8_BAR; PG8_MMA(1, 0, At, B0); if constexpr (!HALFN) PG8_MMA(1, 1, At, B1); PG8_BAR; PG8_SCHED;
;         }
;         if (wr == 0) PG8_BAR;
	s_setprio 0
	s_add_i32 s6, s30, s10
	v_lshl_add_u64 v[236:237], v[236:237], 0, s[60:61]
	s_mov_b32 m0, s6
	ds_read_b128 v[180:183], v210 offset:49152
	ds_read_b128 v[184:187], v210 offset:50176
	ds_read_b128 v[212:215], v210 offset:51200
	ds_read_b128 v[216:219], v210 offset:52224
	ds_read_b128 v[220:223], v210 offset:53248
	ds_read_b128 v[224:227], v210 offset:54272
	ds_read_b128 v[228:231], v210 offset:55296
	ds_read_b128 v[232:235], v210 offset:56320
	global_load_lds_dwordx4 v[236:237], off
	s_add_i32 m0, s6, 0x2000
	s_add_u32 s4, s4, 0x80080
	v_lshl_add_u64 v[236:237], v[238:239], 0, s[60:61]
	s_addc_u32 s5, s5, 0
	s_add_i32 s6, s31, s10
	global_load_lds_dwordx4 v[236:237], off
	v_lshl_add_u64 v[236:237], s[4:5], 0, v[170:171]
	s_mov_b32 m0, s6
	s_nop 0
	global_load_lds_dwordx4 v[236:237], off
	v_lshl_add_u64 v[236:237], s[4:5], 0, v[174:175]
	s_add_i32 m0, s6, 0x2000
	s_nop 0
	global_load_lds_dwordx4 v[236:237], off
	v_lshl_add_u64 v[236:237], v[240:241], 0, s[60:61]
	s_mov_b32 m0, s20
	s_nop 0
	global_load_lds_dwordx4 v[236:237], off
	v_lshl_add_u64 v[236:237], v[242:243], 0, s[60:61]
	s_mov_b32 m0, s21
	s_nop 0
	global_load_lds_dwordx4 v[236:237], off
	s_waitcnt vmcnt(8)
	s_waitcnt lgkmcnt(0)
	s_setprio 1
	s_barrier
	v_mfma_f32_16x16x32_bf16 v[62:65], v[122:125], v[180:183], v[62:65]
	v_mfma_f32_16x16x32_bf16 v[58:61], v[138:141], v[180:183], v[58:61]
	v_mfma_f32_16x16x32_bf16 v[46:49], v[122:125], v[212:215], v[46:49]
	v_mfma_f32_16x16x32_bf16 v[42:45], v[138:141], v[212:215], v[42:45]
	v_mfma_f32_16x16x32_bf16 v[30:33], v[122:125], v[220:223], v[30:33]
	v_mfma_f32_16x16x32_bf16 v[26:29], v[138:141], v[220:223], v[26:29]
	v_mfma_f32_16x16x32_bf16 v[14:17], v[122:125], v[228:231], v[14:17]
	v_mfma_f32_16x16x32_bf16 v[10:13], v[138:141], v[228:231], v[10:13]
	v_mfma_f32_16x16x32_bf16 v[62:65], v[130:133], v[184:187], v[62:65]
	v_mfma_f32_16x16x32_bf16 v[58:61], v[142:145], v[184:187], v[58:61]
	v_mfma_f32_16x16x32_bf16 v[46:49], v[130:133], v[216:219], v[46:49]
	v_mfma_f32_16x16x32_bf16 v[42:45], v[142:145], v[216:219], v[42:45]
	v_mfma_f32_16x16x32_bf16 v[30:33], v[130:133], v[224:227], v[30:33]
	v_mfma_f32_16x16x32_bf16 v[26:29], v[142:145], v[224:227], v[26:29]
	v_mfma_f32_16x16x32_bf16 v[14:17], v[130:133], v[232:235], v[14:17]
	v_mfma_f32_16x16x32_bf16 v[10:13], v[142:145], v[232:235], v[10:13]
	v_mfma_f32_16x16x32_bf16 v[54:57], v[146:149], v[180:183], v[54:57]
	v_mfma_f32_16x16x32_bf16 v[50:53], v[154:157], v[180:183], v[50:53]
	v_mfma_f32_16x16x32_bf16 v[38:41], v[146:149], v[212:215], v[38:41]
	v_mfma_f32_16x16x32_bf16 v[34:37], v[154:157], v[212:215], v[34:37]
	v_mfma_f32_16x16x32_bf16 v[22:25], v[146:149], v[220:223], v[22:25]
	v_mfma_f32_16x16x32_bf16 v[18:21], v[154:157], v[220:223], v[18:21]
	v_mfma_f32_16x16x32_bf16 v[6:9], v[146:149], v[228:231], v[6:9]
	v_mfma_f32_16x16x32_bf16 v[2:5], v[154:157], v[228:231], v[2:5]
	v_mfma_f32_16x16x32_bf16 v[54:57], v[150:153], v[184:187], v[54:57]
	v_mfma_f32_16x16x32_bf16 v[50:53], v[158:161], v[184:187], v[50:53]
	v_mfma_f32_16x16x32_bf16 v[38:41], v[150:153], v[216:219], v[38:41]
	v_mfma_f32_16x16x32_bf16 v[34:37], v[158:161], v[216:219], v[34:37]
	v_mfma_f32_16x16x32_bf16 v[22:25], v[150:153], v[224:227], v[22:25]
	v_mfma_f32_16x16x32_bf16 v[18:21], v[158:161], v[224:227], v[18:21]
	v_mfma_f32_16x16x32_bf16 v[6:9], v[150:153], v[232:235], v[6:9]
	v_mfma_f32_16x16x32_bf16 v[2:5], v[158:161], v[232:235], v[2:5]
	s_barrier
	s_setprio 0
	s_add_i32 s29, s29, 2
	s_add_u32 s62, s62, 0x100
	s_addc_u32 s63, s63, 0
	s_add_u32 s27, s27, 0x100
	s_addc_u32 s28, s28, 0
	s_cmp_gt_u32 s29, 29
	s_cbranch_scc0 .LBB0_799
	s_and_b64 vcc, exec, s[48:49]
	s_cbranch_vccz .LBB0_802
	s_barrier
